# snake MFMA order + row-statistic partial sums snapped to a 2^-6 grid before the f32 atomics (order-independent exact accumulation, deterministic outputs)
# speedup vs baseline: 1.0044x; 1.0044x over previous
.LBB0_232:
	v_lshl_add_u32 v64, s54, 8, v216
	v_lshl_or_b32 v140, s55, 8, v218
	v_ashrrev_i32_e32 v65, 31, v64
	v_readlane_b32 s60, v252, 0
	v_ashrrev_i32_e32 v141, 31, v140
	s_waitcnt lgkmcnt(0)
	v_lshlrev_b64 v[0:1], 13, v[64:65]
	v_readlane_b32 s61, v252, 1
	v_lshlrev_b64 v[16:17], 2, v[140:141]
	v_readlane_b32 s74, v252, 14
	v_lshl_add_u64 v[212:213], s[60:61], 0, v[0:1]
	v_lshl_add_u64 v[0:1], v[212:213], 0, v[16:17]
	v_readlane_b32 s75, v252, 15
	global_load_dwordx4 v[28:31], v[0:1], off
	global_load_dwordx4 v[40:43], v[0:1], off offset:64
	global_load_dwordx4 v[52:55], v[0:1], off offset:512
	v_lshl_add_u64 v[2:3], s[74:75], 0, v[16:17]
	global_load_dwordx4 v[12:15], v[2:3], off
	global_load_dwordx4 v[8:11], v[2:3], off offset:64
	global_load_dwordx4 v[4:7], v[2:3], off offset:512
	global_load_dwordx4 v[60:63], v[0:1], off offset:576
	v_or_b32_e32 v66, 16, v64
	v_or_b32_e32 v214, 32, v64
	v_ashrrev_i32_e32 v67, 31, v66
	v_ashrrev_i32_e32 v215, 31, v214
	v_lshlrev_b64 v[18:19], 13, v[66:67]
	v_lshlrev_b64 v[20:21], 13, v[214:215]
	v_lshl_add_u64 v[18:19], s[60:61], 0, v[18:19]
	v_lshl_add_u64 v[20:21], s[60:61], 0, v[20:21]
	global_load_dwordx4 v[0:3], v[2:3], off offset:576
	v_lshl_add_u64 v[18:19], v[18:19], 0, v[16:17]
	v_lshl_add_u64 v[16:17], v[20:21], 0, v[16:17]
	global_load_dwordx4 v[56:59], v[18:19], off
	global_load_dwordx4 v[48:51], v[18:19], off offset:64
	global_load_dwordx4 v[36:39], v[18:19], off offset:512
	global_load_dwordx4 v[24:27], v[18:19], off offset:576
	global_load_dwordx4 v[44:47], v[16:17], off
	global_load_dwordx4 v[32:35], v[16:17], off offset:64
	global_load_dwordx4 v[20:23], v[16:17], off offset:512
	s_nop 0
	global_load_dwordx4 v[16:19], v[16:17], off offset:576
	v_and_b32_e32 v225, 64, v223
	v_xor_b32_e32 v224, 16, v223
	v_add_u32_e32 v225, 64, v225
	v_xor_b32_e32 v226, 32, v223
	v_cmp_lt_i32_e32 vcc, v224, v225
	v_readlane_b32 s62, v252, 2
	v_readlane_b32 s63, v252, 3
	v_readlane_b32 s64, v252, 4
	v_readlane_b32 s65, v252, 5
	v_readlane_b32 s66, v252, 6
	v_readlane_b32 s67, v252, 7
	v_readlane_b32 s68, v252, 8
	v_readlane_b32 s69, v252, 9
	v_readlane_b32 s70, v252, 10
	v_readlane_b32 s71, v252, 11
	v_readlane_b32 s72, v252, 12
	v_readlane_b32 s73, v252, 13
	v_cndmask_b32_e32 v224, v223, v224, vcc
	v_cmp_lt_i32_e32 vcc, v226, v225
	v_readlane_b32 s60, v252, 16
	v_readlane_b32 s74, v252, 30
	v_cndmask_b32_e32 v228, v223, v226, vcc
	v_lshlrev_b64 v[226:227], 11, v[64:65]
	v_lshl_add_u64 v[226:227], v[226:227], 0, v[140:141]
	v_readlane_b32 s75, v252, 31
	v_lshlrev_b32_e32 v225, 2, v224
	v_lshlrev_b32_e32 v224, 2, v228
	v_lshl_add_u64 v[228:229], v[226:227], 2, s[74:75]
	v_lshlrev_b64 v[226:227], 1, v[226:227]
	v_lshl_add_u64 v[230:231], s[12:13], 0, v[226:227]
	v_or_b32_e32 v232, 32, v226
	v_mov_b32_e32 v233, v227
	v_lshl_add_u64 v[232:233], s[12:13], 0, v[232:233]
	v_readlane_b32 s61, v252, 17
	v_readlane_b32 s62, v252, 18
	v_readlane_b32 s63, v252, 19
	v_readlane_b32 s64, v252, 20
	v_readlane_b32 s65, v252, 21
	v_readlane_b32 s66, v252, 22
	v_readlane_b32 s67, v252, 23
	v_readlane_b32 s68, v252, 24
	v_readlane_b32 s69, v252, 25
	v_readlane_b32 s70, v252, 26
	v_readlane_b32 s71, v252, 27
	v_readlane_b32 s72, v252, 28
	v_readlane_b32 s73, v252, 29
	s_waitcnt vmcnt(0)
	v_pk_add_f32 v[30:31], v[200:201], v[30:31]
	v_pk_add_f32 v[28:29], v[202:203], v[28:29]
	v_pk_add_f32 v[42:43], v[204:205], v[42:43]
	v_pk_add_f32 v[40:41], v[206:207], v[40:41]
	v_pk_add_f32 v[54:55], v[210:211], v[54:55]
	v_pk_add_f32 v[52:53], v[208:209], v[52:53]
	v_mul_f32_e32 v234, v29, v29
	v_mul_f32_e32 v235, v31, v31
	v_pk_mul_f32 v[200:201], v[14:15], v[30:31]
	v_pk_mul_f32 v[202:203], v[12:13], v[28:29]
	v_mul_f32_e32 v236, v41, v41
	v_mul_f32_e32 v237, v43, v43
	global_store_dwordx4 v[228:229], v[28:31], off
	v_pk_mul_f32 v[204:205], v[10:11], v[42:43]
	v_pk_mul_f32 v[206:207], v[8:9], v[40:41]
	v_mul_f32_e32 v238, v53, v53
	v_mul_f32_e32 v239, v55, v55
	v_fmac_f32_e32 v234, v28, v28
	v_fmac_f32_e32 v235, v30, v30
	v_cvt_pk_bf16_f32 v28, v202, v203
	v_cvt_pk_bf16_f32 v29, v200, v201
	v_fmac_f32_e32 v236, v40, v40
	v_fmac_f32_e32 v237, v42, v42
	v_cvt_pk_bf16_f32 v30, v206, v207
	v_cvt_pk_bf16_f32 v31, v204, v205
	v_fmac_f32_e32 v238, v52, v52
	v_fmac_f32_e32 v239, v54, v54
	v_add_f32_e32 v200, v234, v235
	global_store_dwordx2 v[230:231], v[28:29], off
	global_store_dwordx4 v[228:229], v[40:43], off offset:64
	v_add_f32_e32 v28, v236, v237
	v_pk_mul_f32 v[208:209], v[6:7], v[54:55]
	v_pk_mul_f32 v[210:211], v[4:5], v[52:53]
	global_store_dwordx2 v[232:233], v[30:31], off
	global_store_dwordx4 v[228:229], v[52:55], off offset:512
	v_add_f32_e32 v29, v238, v239
	v_add_f32_e32 v28, v200, v28
	v_or_b32_e32 v30, 0x100, v226
	v_mov_b32_e32 v31, v227
	v_add_f32_e32 v40, v28, v29
	v_cvt_pk_bf16_f32 v28, v210, v211
	v_cvt_pk_bf16_f32 v29, v208, v209
	v_lshl_add_u64 v[30:31], s[12:13], 0, v[30:31]
	global_store_dwordx2 v[30:31], v[28:29], off
	v_pk_add_f32 v[30:31], v[198:199], v[62:63]
	v_pk_add_f32 v[28:29], v[196:197], v[60:61]
	v_mul_f32_e32 v42, v31, v31
	v_mul_f32_e32 v41, v29, v29
	v_fmac_f32_e32 v41, v28, v28
	v_fmac_f32_e32 v42, v30, v30
	v_add_f32_e32 v41, v41, v42
	v_add_f32_e32 v41, v40, v41
	ds_bpermute_b32 v42, v225, v41
	global_store_dwordx4 v[228:229], v[28:31], off offset:576
	v_or_b32_e32 v226, 0x120, v226
	s_nop 0
	v_pk_mul_f32 v[28:29], v[0:1], v[28:29]
	v_pk_mul_f32 v[30:31], v[2:3], v[30:31]
	v_cvt_pk_bf16_f32 v40, v28, v29
	s_waitcnt lgkmcnt(0)
	v_add_f32_e32 v28, v41, v42
	ds_bpermute_b32 v29, v224, v28
	v_cvt_pk_bf16_f32 v41, v30, v31
	v_lshl_add_u64 v[30:31], s[12:13], 0, v[226:227]
	global_store_dwordx2 v[30:31], v[40:41], off
	s_and_saveexec_b64 s[24:25], s[4:5]
	s_cbranch_execz .LBB0_234
	v_lshl_add_u64 v[30:31], v[64:65], 2, s[14:15]
	s_waitcnt lgkmcnt(0)
	v_add_f32_e32 v28, v28, v29
	v_add_f32_e32 v28, 0x48400000, v28
	v_add_f32_e32 v28, 0xc8400000, v28
	global_atomic_add_f32 v[30:31], v28, off
.LBB0_234:
	s_or_b64 exec, exec, s[24:25]
	v_or_b32_e32 v196, 48, v64
	v_ashrrev_i32_e32 v197, 31, v196
	v_readlane_b32 s60, v252, 0
	s_waitcnt lgkmcnt(0)
	v_lshlrev_b64 v[28:29], 13, v[196:197]
	v_readlane_b32 s61, v252, 1
	v_readlane_b32 s62, v252, 2
	v_readlane_b32 s63, v252, 3
	v_lshl_add_u64 v[28:29], s[60:61], 0, v[28:29]
	v_lshl_add_u64 v[28:29], v[140:141], 2, v[28:29]
	global_load_dwordx4 v[60:63], v[28:29], off
	global_load_dwordx4 v[52:55], v[28:29], off offset:64
	global_load_dwordx4 v[40:43], v[28:29], off offset:512
	s_nop 0
	global_load_dwordx4 v[28:31], v[28:29], off offset:576
	v_readlane_b32 s64, v252, 4
	v_readlane_b32 s65, v252, 5
	v_readlane_b32 s66, v252, 6
	v_readlane_b32 s67, v252, 7
	v_readlane_b32 s68, v252, 8
	v_readlane_b32 s69, v252, 9
	v_readlane_b32 s70, v252, 10
	v_readlane_b32 s71, v252, 11
	v_readlane_b32 s72, v252, 12
	v_readlane_b32 s73, v252, 13
	v_readlane_b32 s74, v252, 14
	v_readlane_b32 s75, v252, 15
	v_lshlrev_b64 v[198:199], 11, v[66:67]
	v_readlane_b32 s60, v252, 16
	v_lshl_add_u64 v[198:199], v[198:199], 0, v[140:141]
	v_pk_add_f32 v[58:59], v[194:195], v[58:59]
	v_pk_add_f32 v[56:57], v[192:193], v[56:57]
	v_readlane_b32 s74, v252, 30
	v_readlane_b32 s75, v252, 31
	v_mul_f32_e32 v65, v57, v57
	v_mul_f32_e32 v194, v59, v59
	v_lshl_add_u64 v[192:193], v[198:199], 2, s[74:75]
	global_store_dwordx4 v[192:193], v[56:59], off
	v_fmac_f32_e32 v65, v56, v56
	v_fmac_f32_e32 v194, v58, v58
	v_pk_mul_f32 v[58:59], v[14:15], v[58:59]
	v_pk_mul_f32 v[56:57], v[12:13], v[56:57]
	v_add_f32_e32 v65, v65, v194
	v_cvt_pk_bf16_f32 v56, v56, v57
	v_cvt_pk_bf16_f32 v57, v58, v59
	v_lshlrev_b64 v[58:59], 1, v[198:199]
	v_lshl_add_u64 v[194:195], s[12:13], 0, v[58:59]
	v_pk_add_f32 v[50:51], v[190:191], v[50:51]
	v_pk_add_f32 v[48:49], v[188:189], v[48:49]
	global_store_dwordx2 v[194:195], v[56:57], off
	v_mul_f32_e32 v56, v49, v49
	v_mul_f32_e32 v57, v51, v51
	global_store_dwordx4 v[192:193], v[48:51], off offset:64
	v_fmac_f32_e32 v56, v48, v48
	v_fmac_f32_e32 v57, v50, v50
	v_pk_mul_f32 v[50:51], v[10:11], v[50:51]
	v_pk_mul_f32 v[48:49], v[8:9], v[48:49]
	v_pk_add_f32 v[38:39], v[186:187], v[38:39]
	v_cvt_pk_bf16_f32 v48, v48, v49
	v_cvt_pk_bf16_f32 v49, v50, v51
	v_or_b32_e32 v50, 32, v58
	v_mov_b32_e32 v51, v59
	v_lshl_add_u64 v[50:51], s[12:13], 0, v[50:51]
	v_pk_add_f32 v[36:37], v[184:185], v[36:37]
	global_store_dwordx2 v[50:51], v[48:49], off
	v_mul_f32_e32 v48, v37, v37
	v_mul_f32_e32 v49, v39, v39
	global_store_dwordx4 v[192:193], v[36:39], off offset:512
	v_fmac_f32_e32 v48, v36, v36
	v_fmac_f32_e32 v49, v38, v38
	v_pk_mul_f32 v[38:39], v[6:7], v[38:39]
	v_pk_mul_f32 v[36:37], v[4:5], v[36:37]
	v_pk_add_f32 v[26:27], v[182:183], v[26:27]
	v_cvt_pk_bf16_f32 v36, v36, v37
	v_cvt_pk_bf16_f32 v37, v38, v39
	v_or_b32_e32 v38, 0x100, v58
	v_mov_b32_e32 v39, v59
	v_lshl_add_u64 v[38:39], s[12:13], 0, v[38:39]
	v_pk_add_f32 v[24:25], v[180:181], v[24:25]
	v_add_f32_e32 v56, v56, v57
	global_store_dwordx2 v[38:39], v[36:37], off
	v_mul_f32_e32 v36, v25, v25
	v_mul_f32_e32 v37, v27, v27
	v_add_f32_e32 v56, v65, v56
	v_add_f32_e32 v48, v48, v49
	v_fmac_f32_e32 v36, v24, v24
	v_fmac_f32_e32 v37, v26, v26
	v_add_f32_e32 v48, v56, v48
	v_add_f32_e32 v36, v36, v37
	v_add_f32_e32 v37, v48, v36
	ds_bpermute_b32 v38, v225, v37
	global_store_dwordx4 v[192:193], v[24:27], off offset:576
	v_or_b32_e32 v58, 0x120, v58
	v_readlane_b32 s61, v252, 17
	v_pk_mul_f32 v[24:25], v[0:1], v[24:25]
	v_pk_mul_f32 v[26:27], v[2:3], v[26:27]
	v_cvt_pk_bf16_f32 v36, v24, v25
	s_waitcnt lgkmcnt(0)
	v_add_f32_e32 v24, v37, v38
	ds_bpermute_b32 v25, v224, v24
	v_cvt_pk_bf16_f32 v37, v26, v27
	v_lshl_add_u64 v[26:27], s[12:13], 0, v[58:59]
	v_readlane_b32 s62, v252, 18
	v_readlane_b32 s63, v252, 19
	v_readlane_b32 s64, v252, 20
	v_readlane_b32 s65, v252, 21
	v_readlane_b32 s66, v252, 22
	v_readlane_b32 s67, v252, 23
	v_readlane_b32 s68, v252, 24
	v_readlane_b32 s69, v252, 25
	v_readlane_b32 s70, v252, 26
	v_readlane_b32 s71, v252, 27
	v_readlane_b32 s72, v252, 28
	v_readlane_b32 s73, v252, 29
	global_store_dwordx2 v[26:27], v[36:37], off
	s_and_saveexec_b64 s[24:25], s[4:5]
	s_cbranch_execz .LBB0_236
	v_lshl_add_u64 v[26:27], v[66:67], 2, s[14:15]
	s_waitcnt lgkmcnt(0)
	v_add_f32_e32 v24, v24, v25
	v_add_f32_e32 v24, 0x48400000, v24
	v_add_f32_e32 v24, 0xc8400000, v24
	global_atomic_add_f32 v[26:27], v24, off
.LBB0_236:
	s_or_b64 exec, exec, s[24:25]
	v_add_u32_e32 v180, 0x80, v64
	v_ashrrev_i32_e32 v181, 31, v180
	v_readlane_b32 s60, v252, 0
	s_waitcnt lgkmcnt(0)
	v_lshlrev_b64 v[24:25], 13, v[180:181]
	v_readlane_b32 s61, v252, 1
	v_readlane_b32 s62, v252, 2
	v_readlane_b32 s63, v252, 3
	v_lshl_add_u64 v[24:25], s[60:61], 0, v[24:25]
	v_lshl_add_u64 v[24:25], v[140:141], 2, v[24:25]
	global_load_dwordx4 v[64:67], v[24:25], off
	global_load_dwordx4 v[48:51], v[24:25], off offset:64
	global_load_dwordx4 v[36:39], v[24:25], off offset:512
	s_nop 0
	global_load_dwordx4 v[24:27], v[24:25], off offset:576
	v_readlane_b32 s64, v252, 4
	v_readlane_b32 s65, v252, 5
	v_readlane_b32 s66, v252, 6
	v_readlane_b32 s67, v252, 7
	v_readlane_b32 s68, v252, 8
	v_readlane_b32 s69, v252, 9
	v_readlane_b32 s70, v252, 10
	v_readlane_b32 s71, v252, 11
	v_readlane_b32 s72, v252, 12
	v_readlane_b32 s73, v252, 13
	v_readlane_b32 s74, v252, 14
	v_readlane_b32 s75, v252, 15
	v_lshlrev_b64 v[56:57], 11, v[214:215]
	v_readlane_b32 s60, v252, 16
	v_lshl_add_u64 v[56:57], v[56:57], 0, v[140:141]
	v_pk_add_f32 v[46:47], v[178:179], v[46:47]
	v_pk_add_f32 v[44:45], v[176:177], v[44:45]
	v_readlane_b32 s74, v252, 30
	v_readlane_b32 s75, v252, 31
	v_mul_f32_e32 v176, v45, v45
	v_mul_f32_e32 v177, v47, v47
	v_lshl_add_u64 v[58:59], v[56:57], 2, s[74:75]
	global_store_dwordx4 v[58:59], v[44:47], off
	v_fmac_f32_e32 v176, v44, v44
	v_fmac_f32_e32 v177, v46, v46
	v_pk_mul_f32 v[46:47], v[14:15], v[46:47]
	v_pk_mul_f32 v[44:45], v[12:13], v[44:45]
	v_pk_add_f32 v[34:35], v[174:175], v[34:35]
	v_cvt_pk_bf16_f32 v44, v44, v45
	v_cvt_pk_bf16_f32 v45, v46, v47
	v_lshlrev_b64 v[46:47], 1, v[56:57]
	v_lshl_add_u64 v[56:57], s[12:13], 0, v[46:47]
	v_pk_add_f32 v[32:33], v[172:173], v[32:33]
	global_store_dwordx2 v[56:57], v[44:45], off
	v_mul_f32_e32 v44, v33, v33
	v_mul_f32_e32 v45, v35, v35
	global_store_dwordx4 v[58:59], v[32:35], off offset:64
	v_fmac_f32_e32 v44, v32, v32
	v_fmac_f32_e32 v45, v34, v34
	v_pk_mul_f32 v[34:35], v[10:11], v[34:35]
	v_pk_mul_f32 v[32:33], v[8:9], v[32:33]
	v_pk_add_f32 v[22:23], v[170:171], v[22:23]
	v_cvt_pk_bf16_f32 v32, v32, v33
	v_cvt_pk_bf16_f32 v33, v34, v35
	v_or_b32_e32 v34, 32, v46
	v_mov_b32_e32 v35, v47
	v_lshl_add_u64 v[34:35], s[12:13], 0, v[34:35]
	v_pk_add_f32 v[20:21], v[168:169], v[20:21]
	global_store_dwordx2 v[34:35], v[32:33], off
	v_mul_f32_e32 v32, v21, v21
	v_mul_f32_e32 v33, v23, v23
	global_store_dwordx4 v[58:59], v[20:23], off offset:512
	v_fmac_f32_e32 v32, v20, v20
	v_fmac_f32_e32 v33, v22, v22
	v_pk_mul_f32 v[22:23], v[6:7], v[22:23]
	v_pk_mul_f32 v[20:21], v[4:5], v[20:21]
	v_pk_add_f32 v[18:19], v[166:167], v[18:19]
	v_cvt_pk_bf16_f32 v20, v20, v21
	v_cvt_pk_bf16_f32 v21, v22, v23
	v_or_b32_e32 v22, 0x100, v46
	v_mov_b32_e32 v23, v47
	v_lshl_add_u64 v[22:23], s[12:13], 0, v[22:23]
	v_pk_add_f32 v[16:17], v[164:165], v[16:17]
	v_add_f32_e32 v176, v176, v177
	v_add_f32_e32 v44, v44, v45
	global_store_dwordx2 v[22:23], v[20:21], off
	v_mul_f32_e32 v20, v17, v17
	v_mul_f32_e32 v21, v19, v19
	v_add_f32_e32 v44, v176, v44
	v_add_f32_e32 v32, v32, v33
	v_fmac_f32_e32 v20, v16, v16
	v_fmac_f32_e32 v21, v18, v18
	v_add_f32_e32 v32, v44, v32
	v_add_f32_e32 v20, v20, v21
	v_add_f32_e32 v21, v32, v20
	ds_bpermute_b32 v22, v225, v21
	global_store_dwordx4 v[58:59], v[16:19], off offset:576
	v_or_b32_e32 v46, 0x120, v46
	v_readlane_b32 s61, v252, 17
	v_pk_mul_f32 v[16:17], v[0:1], v[16:17]
	v_pk_mul_f32 v[18:19], v[2:3], v[18:19]
	v_cvt_pk_bf16_f32 v20, v16, v17
	s_waitcnt lgkmcnt(0)
	v_add_f32_e32 v16, v21, v22
	ds_bpermute_b32 v17, v224, v16
	v_cvt_pk_bf16_f32 v21, v18, v19
	v_lshl_add_u64 v[18:19], s[12:13], 0, v[46:47]
	v_readlane_b32 s62, v252, 18
	v_readlane_b32 s63, v252, 19
	v_readlane_b32 s64, v252, 20
	v_readlane_b32 s65, v252, 21
	v_readlane_b32 s66, v252, 22
	v_readlane_b32 s67, v252, 23
	v_readlane_b32 s68, v252, 24
	v_readlane_b32 s69, v252, 25
	v_readlane_b32 s70, v252, 26
	v_readlane_b32 s71, v252, 27
	v_readlane_b32 s72, v252, 28
	v_readlane_b32 s73, v252, 29
	global_store_dwordx2 v[18:19], v[20:21], off
	s_and_saveexec_b64 s[24:25], s[4:5]
	s_cbranch_execz .LBB0_238
	v_lshl_add_u64 v[18:19], v[214:215], 2, s[14:15]
	s_waitcnt lgkmcnt(0)
	v_add_f32_e32 v16, v16, v17
	v_add_f32_e32 v16, 0x48400000, v16
	v_add_f32_e32 v16, 0xc8400000, v16
	global_atomic_add_f32 v[18:19], v16, off
.LBB0_238:
	s_or_b64 exec, exec, s[24:25]
	s_waitcnt lgkmcnt(0)
	v_lshl_add_u64 v[16:17], v[140:141], 2, v[212:213]
	v_lshl_add_u64 v[18:19], v[16:17], 0, s[20:21]
	v_add_co_u32_e32 v16, vcc, 0x120000, v16
	v_lshlrev_b64 v[20:21], 11, v[196:197]
	s_nop 0
	v_addc_co_u32_e32 v17, vcc, 0, v17, vcc
	global_load_dwordx4 v[44:47], v[18:19], off offset:64
	global_load_dwordx4 v[32:35], v[18:19], off offset:512
	global_load_dwordx4 v[56:59], v[16:17], off
	s_nop 0
	global_load_dwordx4 v[16:19], v[18:19], off offset:576
	v_lshl_add_u64 v[164:165], v[20:21], 0, v[140:141]
	s_waitcnt vmcnt(27)
	v_pk_add_f32 v[22:23], v[160:161], v[62:63]
	v_pk_add_f32 v[20:21], v[158:159], v[60:61]
	v_readlane_b32 s60, v252, 16
	v_readlane_b32 s74, v252, 30
	v_readlane_b32 s75, v252, 31
	v_mul_f32_e32 v62, v21, v21
	v_mul_f32_e32 v63, v23, v23
	v_lshl_add_u64 v[60:61], v[164:165], 2, s[74:75]
	v_fmac_f32_e32 v62, v20, v20
	v_fmac_f32_e32 v63, v22, v22
	global_store_dwordx4 v[60:61], v[20:23], off
	v_add_f32_e32 v158, v62, v63
	v_lshlrev_b64 v[62:63], 1, v[164:165]
	v_pk_mul_f32 v[22:23], v[14:15], v[22:23]
	v_pk_mul_f32 v[20:21], v[12:13], v[20:21]
	v_readlane_b32 s61, v252, 17
	v_cvt_pk_bf16_f32 v20, v20, v21
	v_cvt_pk_bf16_f32 v21, v22, v23
	v_lshl_add_u64 v[22:23], s[12:13], 0, v[62:63]
	global_store_dwordx2 v[22:23], v[20:21], off
	s_waitcnt vmcnt(28)
	v_pk_add_f32 v[22:23], v[156:157], v[54:55]
	v_pk_add_f32 v[20:21], v[154:155], v[52:53]
	v_mul_f32_e32 v53, v23, v23
	v_mul_f32_e32 v52, v21, v21
	global_store_dwordx4 v[60:61], v[20:23], off offset:64
	v_fmac_f32_e32 v52, v20, v20
	v_fmac_f32_e32 v53, v22, v22
	v_pk_mul_f32 v[22:23], v[10:11], v[22:23]
	v_pk_mul_f32 v[20:21], v[8:9], v[20:21]
	v_add_f32_e32 v52, v52, v53
	v_cvt_pk_bf16_f32 v20, v20, v21
	v_cvt_pk_bf16_f32 v21, v22, v23
	v_or_b32_e32 v22, 32, v62
	v_mov_b32_e32 v23, v63
	v_lshl_add_u64 v[22:23], s[12:13], 0, v[22:23]
	global_store_dwordx2 v[22:23], v[20:21], off
	s_waitcnt vmcnt(29)
	v_pk_add_f32 v[22:23], v[152:153], v[42:43]
	v_pk_add_f32 v[20:21], v[150:151], v[40:41]
	v_mul_f32_e32 v41, v23, v23
	v_mul_f32_e32 v40, v21, v21
	global_store_dwordx4 v[60:61], v[20:23], off offset:512
	v_fmac_f32_e32 v40, v20, v20
	v_fmac_f32_e32 v41, v22, v22
	v_pk_mul_f32 v[22:23], v[6:7], v[22:23]
	v_pk_mul_f32 v[20:21], v[4:5], v[20:21]
	v_add_f32_e32 v52, v158, v52
	v_cvt_pk_bf16_f32 v20, v20, v21
	v_cvt_pk_bf16_f32 v21, v22, v23
	v_or_b32_e32 v22, 0x100, v62
	v_mov_b32_e32 v23, v63
	v_lshl_add_u64 v[22:23], s[12:13], 0, v[22:23]
	global_store_dwordx2 v[22:23], v[20:21], off
	s_waitcnt vmcnt(30)
	v_pk_add_f32 v[22:23], v[148:149], v[30:31]
	v_pk_add_f32 v[20:21], v[146:147], v[28:29]
	v_mul_f32_e32 v29, v23, v23
	v_mul_f32_e32 v28, v21, v21
	v_add_f32_e32 v40, v40, v41
	v_fmac_f32_e32 v28, v20, v20
	v_fmac_f32_e32 v29, v22, v22
	v_add_f32_e32 v40, v52, v40
	v_add_f32_e32 v28, v28, v29
	v_add_f32_e32 v29, v40, v28
	ds_bpermute_b32 v30, v225, v29
	global_store_dwordx4 v[60:61], v[20:23], off offset:576
	v_or_b32_e32 v62, 0x120, v62
	v_readlane_b32 s62, v252, 18
	v_pk_mul_f32 v[20:21], v[0:1], v[20:21]
	v_pk_mul_f32 v[22:23], v[2:3], v[22:23]
	v_cvt_pk_bf16_f32 v28, v20, v21
	s_waitcnt lgkmcnt(0)
	v_add_f32_e32 v20, v29, v30
	ds_bpermute_b32 v21, v224, v20
	v_cvt_pk_bf16_f32 v29, v22, v23
	v_lshl_add_u64 v[22:23], s[12:13], 0, v[62:63]
	v_readlane_b32 s63, v252, 19
	v_readlane_b32 s64, v252, 20
	v_readlane_b32 s65, v252, 21
	v_readlane_b32 s66, v252, 22
	v_readlane_b32 s67, v252, 23
	v_readlane_b32 s68, v252, 24
	v_readlane_b32 s69, v252, 25
	v_readlane_b32 s70, v252, 26
	v_readlane_b32 s71, v252, 27
	v_readlane_b32 s72, v252, 28
	v_readlane_b32 s73, v252, 29
	global_store_dwordx2 v[22:23], v[28:29], off
	s_and_saveexec_b64 s[24:25], s[4:5]
	s_cbranch_execz .LBB0_240
	v_lshl_add_u64 v[22:23], v[196:197], 2, s[14:15]
	s_waitcnt lgkmcnt(0)
	v_add_f32_e32 v20, v20, v21
	v_add_f32_e32 v20, 0x48400000, v20
	v_add_f32_e32 v20, 0xc8400000, v20
	global_atomic_add_f32 v[22:23], v20, off
.LBB0_240:
	s_or_b64 exec, exec, s[24:25]
	v_or_b32_e32 v146, 32, v180
	v_ashrrev_i32_e32 v147, 31, v146
	v_readlane_b32 s60, v252, 0
	s_waitcnt lgkmcnt(0)
	v_lshlrev_b64 v[20:21], 13, v[146:147]
	v_readlane_b32 s61, v252, 1
	v_readlane_b32 s62, v252, 2
	v_readlane_b32 s63, v252, 3
	v_lshl_add_u64 v[20:21], s[60:61], 0, v[20:21]
	v_lshl_add_u64 v[20:21], v[140:141], 2, v[20:21]
	global_load_dwordx4 v[52:55], v[20:21], off
	global_load_dwordx4 v[40:43], v[20:21], off offset:64
	global_load_dwordx4 v[28:31], v[20:21], off offset:512
	s_nop 0
	global_load_dwordx4 v[20:23], v[20:21], off offset:576
	v_readlane_b32 s64, v252, 4
	v_readlane_b32 s65, v252, 5
	v_readlane_b32 s66, v252, 6
	v_readlane_b32 s67, v252, 7
	v_readlane_b32 s68, v252, 8
	v_readlane_b32 s69, v252, 9
	v_readlane_b32 s70, v252, 10
	v_readlane_b32 s71, v252, 11
	v_readlane_b32 s72, v252, 12
	v_readlane_b32 s73, v252, 13
	v_readlane_b32 s74, v252, 14
	v_readlane_b32 s75, v252, 15
	v_lshlrev_b64 v[60:61], 11, v[180:181]
	v_readlane_b32 s60, v252, 16
	v_lshl_add_u64 v[148:149], v[60:61], 0, v[140:141]
	s_waitcnt vmcnt(27)
	v_pk_add_f32 v[62:63], v[144:145], v[66:67]
	v_pk_add_f32 v[60:61], v[142:143], v[64:65]
	v_readlane_b32 s74, v252, 30
	v_readlane_b32 s75, v252, 31
	v_mul_f32_e32 v66, v61, v61
	v_mul_f32_e32 v67, v63, v63
	v_lshl_add_u64 v[64:65], v[148:149], 2, s[74:75]
	global_store_dwordx4 v[64:65], v[60:63], off
	v_fmac_f32_e32 v66, v60, v60
	v_fmac_f32_e32 v67, v62, v62
	v_pk_mul_f32 v[62:63], v[14:15], v[62:63]
	v_pk_mul_f32 v[60:61], v[12:13], v[60:61]
	v_add_f32_e32 v142, v66, v67
	v_cvt_pk_bf16_f32 v60, v60, v61
	v_cvt_pk_bf16_f32 v61, v62, v63
	v_lshlrev_b64 v[62:63], 1, v[148:149]
	v_lshl_add_u64 v[66:67], s[12:13], 0, v[62:63]
	s_waitcnt vmcnt(27)
	v_pk_add_f32 v[50:51], v[126:127], v[50:51]
	v_pk_add_f32 v[48:49], v[124:125], v[48:49]
	global_store_dwordx2 v[66:67], v[60:61], off
	v_mul_f32_e32 v60, v49, v49
	v_mul_f32_e32 v61, v51, v51
	global_store_dwordx4 v[64:65], v[48:51], off offset:64
	v_fmac_f32_e32 v60, v48, v48
	v_fmac_f32_e32 v61, v50, v50
	v_pk_mul_f32 v[50:51], v[10:11], v[50:51]
	v_pk_mul_f32 v[48:49], v[8:9], v[48:49]
	s_waitcnt vmcnt(28)
	v_pk_add_f32 v[38:39], v[122:123], v[38:39]
	v_cvt_pk_bf16_f32 v48, v48, v49
	v_cvt_pk_bf16_f32 v49, v50, v51
	v_or_b32_e32 v50, 32, v62
	v_mov_b32_e32 v51, v63
	v_lshl_add_u64 v[50:51], s[12:13], 0, v[50:51]
	v_pk_add_f32 v[36:37], v[120:121], v[36:37]
	global_store_dwordx2 v[50:51], v[48:49], off
	v_mul_f32_e32 v48, v37, v37
	v_mul_f32_e32 v49, v39, v39
	global_store_dwordx4 v[64:65], v[36:39], off offset:512
	v_fmac_f32_e32 v48, v36, v36
	v_fmac_f32_e32 v49, v38, v38
	v_pk_mul_f32 v[38:39], v[6:7], v[38:39]
	v_pk_mul_f32 v[36:37], v[4:5], v[36:37]
	s_waitcnt vmcnt(29)
	v_pk_add_f32 v[26:27], v[118:119], v[26:27]
	v_cvt_pk_bf16_f32 v36, v36, v37
	v_cvt_pk_bf16_f32 v37, v38, v39
	v_or_b32_e32 v38, 0x100, v62
	v_mov_b32_e32 v39, v63
	v_lshl_add_u64 v[38:39], s[12:13], 0, v[38:39]
	v_pk_add_f32 v[24:25], v[116:117], v[24:25]
	v_add_f32_e32 v60, v60, v61
	global_store_dwordx2 v[38:39], v[36:37], off
	v_mul_f32_e32 v36, v25, v25
	v_mul_f32_e32 v37, v27, v27
	v_add_f32_e32 v60, v142, v60
	v_add_f32_e32 v48, v48, v49
	v_fmac_f32_e32 v36, v24, v24
	v_fmac_f32_e32 v37, v26, v26
	v_add_f32_e32 v48, v60, v48
	v_add_f32_e32 v36, v36, v37
	v_add_f32_e32 v37, v48, v36
	ds_bpermute_b32 v38, v225, v37
	global_store_dwordx4 v[64:65], v[24:27], off offset:576
	v_or_b32_e32 v62, 0x120, v62
	v_readlane_b32 s61, v252, 17
	v_pk_mul_f32 v[24:25], v[0:1], v[24:25]
	v_pk_mul_f32 v[26:27], v[2:3], v[26:27]
	v_cvt_pk_bf16_f32 v36, v24, v25
	s_waitcnt lgkmcnt(0)
	v_add_f32_e32 v24, v37, v38
	ds_bpermute_b32 v25, v224, v24
	v_cvt_pk_bf16_f32 v37, v26, v27
	v_lshl_add_u64 v[26:27], s[12:13], 0, v[62:63]
	v_readlane_b32 s62, v252, 18
	v_readlane_b32 s63, v252, 19
	v_readlane_b32 s64, v252, 20
	v_readlane_b32 s65, v252, 21
	v_readlane_b32 s66, v252, 22
	v_readlane_b32 s67, v252, 23
	v_readlane_b32 s68, v252, 24
	v_readlane_b32 s69, v252, 25
	v_readlane_b32 s70, v252, 26
	v_readlane_b32 s71, v252, 27
	v_readlane_b32 s72, v252, 28
	v_readlane_b32 s73, v252, 29
	global_store_dwordx2 v[26:27], v[36:37], off
	s_and_saveexec_b64 s[24:25], s[4:5]
	s_cbranch_execz .LBB0_242
	v_lshl_add_u64 v[26:27], v[180:181], 2, s[14:15]
	s_waitcnt lgkmcnt(0)
	v_add_f32_e32 v24, v24, v25
	v_add_f32_e32 v24, 0x48400000, v24
	v_add_f32_e32 v24, 0xc8400000, v24
	global_atomic_add_f32 v[26:27], v24, off
.LBB0_242:
	s_or_b64 exec, exec, s[24:25]
	v_or_b32_e32 v64, 48, v180
	v_ashrrev_i32_e32 v65, 31, v64
	v_readlane_b32 s60, v252, 0
	s_waitcnt lgkmcnt(0)
	v_lshlrev_b64 v[24:25], 13, v[64:65]
	v_readlane_b32 s61, v252, 1
	v_or_b32_e32 v66, 16, v180
	v_readlane_b32 s62, v252, 2
	v_lshl_add_u64 v[24:25], s[60:61], 0, v[24:25]
	v_lshl_add_u64 v[24:25], v[140:141], 2, v[24:25]
	global_load_dwordx4 v[60:63], v[24:25], off
	global_load_dwordx4 v[48:51], v[24:25], off offset:64
	global_load_dwordx4 v[36:39], v[24:25], off offset:512
	s_nop 0
	global_load_dwordx4 v[24:27], v[24:25], off offset:576
	v_readlane_b32 s63, v252, 3
	v_readlane_b32 s64, v252, 4
	v_readlane_b32 s65, v252, 5
	v_readlane_b32 s66, v252, 6
	v_readlane_b32 s67, v252, 7
	v_readlane_b32 s68, v252, 8
	v_readlane_b32 s69, v252, 9
	v_readlane_b32 s70, v252, 10
	v_readlane_b32 s71, v252, 11
	v_readlane_b32 s72, v252, 12
	v_readlane_b32 s73, v252, 13
	v_readlane_b32 s74, v252, 14
	v_readlane_b32 s75, v252, 15
	v_ashrrev_i32_e32 v67, 31, v66
	v_lshlrev_b64 v[116:117], 11, v[66:67]
	v_readlane_b32 s60, v252, 16
	v_lshl_add_u64 v[116:117], v[116:117], 0, v[140:141]
	s_waitcnt vmcnt(25)
	v_pk_add_f32 v[58:59], v[114:115], v[58:59]
	v_pk_add_f32 v[56:57], v[112:113], v[56:57]
	v_readlane_b32 s74, v252, 30
	v_readlane_b32 s75, v252, 31
	v_mul_f32_e32 v114, v57, v57
	v_mul_f32_e32 v115, v59, v59
	v_lshl_add_u64 v[112:113], v[116:117], 2, s[74:75]
	global_store_dwordx4 v[112:113], v[56:59], off
	v_fmac_f32_e32 v114, v56, v56
	v_fmac_f32_e32 v115, v58, v58
	v_pk_mul_f32 v[58:59], v[14:15], v[58:59]
	v_pk_mul_f32 v[56:57], v[12:13], v[56:57]
	v_add_f32_e32 v118, v114, v115
	v_cvt_pk_bf16_f32 v56, v56, v57
	v_cvt_pk_bf16_f32 v57, v58, v59
	v_lshlrev_b64 v[58:59], 1, v[116:117]
	v_lshl_add_u64 v[114:115], s[12:13], 0, v[58:59]
	v_pk_add_f32 v[46:47], v[110:111], v[46:47]
	v_pk_add_f32 v[44:45], v[108:109], v[44:45]
	global_store_dwordx2 v[114:115], v[56:57], off
	v_mul_f32_e32 v56, v45, v45
	v_mul_f32_e32 v57, v47, v47
	global_store_dwordx4 v[112:113], v[44:47], off offset:64
	v_fmac_f32_e32 v56, v44, v44
	v_fmac_f32_e32 v57, v46, v46
	v_pk_mul_f32 v[46:47], v[10:11], v[46:47]
	v_pk_mul_f32 v[44:45], v[8:9], v[44:45]
	v_pk_add_f32 v[34:35], v[106:107], v[34:35]
	v_cvt_pk_bf16_f32 v44, v44, v45
	v_cvt_pk_bf16_f32 v45, v46, v47
	v_or_b32_e32 v46, 32, v58
	v_mov_b32_e32 v47, v59
	v_lshl_add_u64 v[46:47], s[12:13], 0, v[46:47]
	v_pk_add_f32 v[32:33], v[104:105], v[32:33]
	global_store_dwordx2 v[46:47], v[44:45], off
	v_mul_f32_e32 v44, v33, v33
	v_mul_f32_e32 v45, v35, v35
	global_store_dwordx4 v[112:113], v[32:35], off offset:512
	v_fmac_f32_e32 v44, v32, v32
	v_fmac_f32_e32 v45, v34, v34
	v_pk_mul_f32 v[34:35], v[6:7], v[34:35]
	v_pk_mul_f32 v[32:33], v[4:5], v[32:33]
	s_waitcnt vmcnt(29)
	v_pk_add_f32 v[18:19], v[102:103], v[18:19]
	v_cvt_pk_bf16_f32 v32, v32, v33
	v_cvt_pk_bf16_f32 v33, v34, v35
	v_or_b32_e32 v34, 0x100, v58
	v_mov_b32_e32 v35, v59
	v_lshl_add_u64 v[34:35], s[12:13], 0, v[34:35]
	v_pk_add_f32 v[16:17], v[100:101], v[16:17]
	v_add_f32_e32 v56, v56, v57
	global_store_dwordx2 v[34:35], v[32:33], off
	v_mul_f32_e32 v32, v17, v17
	v_mul_f32_e32 v33, v19, v19
	v_add_f32_e32 v56, v118, v56
	v_add_f32_e32 v44, v44, v45
	v_fmac_f32_e32 v32, v16, v16
	v_fmac_f32_e32 v33, v18, v18
	v_add_f32_e32 v44, v56, v44
	v_add_f32_e32 v32, v32, v33
	v_add_f32_e32 v33, v44, v32
	ds_bpermute_b32 v34, v225, v33
	global_store_dwordx4 v[112:113], v[16:19], off offset:576
	v_or_b32_e32 v58, 0x120, v58
	v_readlane_b32 s61, v252, 17
	v_pk_mul_f32 v[16:17], v[0:1], v[16:17]
	v_pk_mul_f32 v[18:19], v[2:3], v[18:19]
	v_cvt_pk_bf16_f32 v32, v16, v17
	s_waitcnt lgkmcnt(0)
	v_add_f32_e32 v16, v33, v34
	ds_bpermute_b32 v17, v224, v16
	v_cvt_pk_bf16_f32 v33, v18, v19
	v_lshl_add_u64 v[18:19], s[12:13], 0, v[58:59]
	v_readlane_b32 s62, v252, 18
	v_readlane_b32 s63, v252, 19
	v_readlane_b32 s64, v252, 20
	v_readlane_b32 s65, v252, 21
	v_readlane_b32 s66, v252, 22
	v_readlane_b32 s67, v252, 23
	v_readlane_b32 s68, v252, 24
	v_readlane_b32 s69, v252, 25
	v_readlane_b32 s70, v252, 26
	v_readlane_b32 s71, v252, 27
	v_readlane_b32 s72, v252, 28
	v_readlane_b32 s73, v252, 29
	global_store_dwordx2 v[18:19], v[32:33], off
	s_and_saveexec_b64 s[24:25], s[4:5]
	s_cbranch_execz .LBB0_244
	v_lshl_add_u64 v[18:19], v[66:67], 2, s[14:15]
	s_waitcnt lgkmcnt(0)
	v_add_f32_e32 v16, v16, v17
	v_add_f32_e32 v16, 0x48400000, v16
	v_add_f32_e32 v16, 0xc8400000, v16
	global_atomic_add_f32 v[18:19], v16, off
.LBB0_244:
	s_or_b64 exec, exec, s[24:25]
	s_waitcnt lgkmcnt(0)
	v_lshlrev_b64 v[16:17], 11, v[146:147]
	v_readlane_b32 s60, v252, 16
	v_lshl_add_u64 v[32:33], v[16:17], 0, v[140:141]
	s_waitcnt vmcnt(23)
	v_pk_add_f32 v[18:19], v[98:99], v[54:55]
	v_pk_add_f32 v[16:17], v[96:97], v[52:53]
	v_readlane_b32 s74, v252, 30
	v_readlane_b32 s75, v252, 31
	v_mul_f32_e32 v44, v17, v17
	v_mul_f32_e32 v45, v19, v19
	v_lshl_add_u64 v[34:35], v[32:33], 2, s[74:75]
	global_store_dwordx4 v[34:35], v[16:19], off
	v_fmac_f32_e32 v44, v16, v16
	v_fmac_f32_e32 v45, v18, v18
	v_pk_mul_f32 v[18:19], v[14:15], v[18:19]
	v_pk_mul_f32 v[16:17], v[12:13], v[16:17]
	v_lshlrev_b64 v[32:33], 1, v[32:33]
	v_cvt_pk_bf16_f32 v16, v16, v17
	v_cvt_pk_bf16_f32 v17, v18, v19
	v_lshl_add_u64 v[18:19], s[12:13], 0, v[32:33]
	global_store_dwordx2 v[18:19], v[16:17], off
	s_waitcnt vmcnt(24)
	v_pk_add_f32 v[18:19], v[94:95], v[42:43]
	v_pk_add_f32 v[16:17], v[92:93], v[40:41]
	v_mul_f32_e32 v41, v19, v19
	v_mul_f32_e32 v40, v17, v17
	global_store_dwordx4 v[34:35], v[16:19], off offset:64
	v_fmac_f32_e32 v40, v16, v16
	v_fmac_f32_e32 v41, v18, v18
	v_pk_mul_f32 v[18:19], v[10:11], v[18:19]
	v_pk_mul_f32 v[16:17], v[8:9], v[16:17]
	v_add_f32_e32 v44, v44, v45
	v_cvt_pk_bf16_f32 v16, v16, v17
	v_cvt_pk_bf16_f32 v17, v18, v19
	v_or_b32_e32 v18, 32, v32
	v_mov_b32_e32 v19, v33
	v_lshl_add_u64 v[18:19], s[12:13], 0, v[18:19]
	global_store_dwordx2 v[18:19], v[16:17], off
	s_waitcnt vmcnt(25)
	v_pk_add_f32 v[18:19], v[90:91], v[30:31]
	v_pk_add_f32 v[16:17], v[88:89], v[28:29]
	v_mul_f32_e32 v29, v19, v19
	v_mul_f32_e32 v28, v17, v17
	global_store_dwordx4 v[34:35], v[16:19], off offset:512
	v_fmac_f32_e32 v28, v16, v16
	v_fmac_f32_e32 v29, v18, v18
	v_pk_mul_f32 v[18:19], v[6:7], v[18:19]
	v_pk_mul_f32 v[16:17], v[4:5], v[16:17]
	v_add_f32_e32 v40, v40, v41
	v_cvt_pk_bf16_f32 v16, v16, v17
	v_cvt_pk_bf16_f32 v17, v18, v19
	v_or_b32_e32 v18, 0x100, v32
	v_mov_b32_e32 v19, v33
	v_lshl_add_u64 v[18:19], s[12:13], 0, v[18:19]
	global_store_dwordx2 v[18:19], v[16:17], off
	s_waitcnt vmcnt(26)
	v_pk_add_f32 v[18:19], v[86:87], v[22:23]
	v_pk_add_f32 v[16:17], v[84:85], v[20:21]
	v_mul_f32_e32 v21, v19, v19
	v_mul_f32_e32 v20, v17, v17
	v_add_f32_e32 v40, v44, v40
	v_add_f32_e32 v28, v28, v29
	v_fmac_f32_e32 v20, v16, v16
	v_fmac_f32_e32 v21, v18, v18
	v_add_f32_e32 v28, v40, v28
	v_add_f32_e32 v20, v20, v21
	v_add_f32_e32 v21, v28, v20
	ds_bpermute_b32 v22, v225, v21
	global_store_dwordx4 v[34:35], v[16:19], off offset:576
	v_or_b32_e32 v32, 0x120, v32
	v_readlane_b32 s61, v252, 17
	v_pk_mul_f32 v[16:17], v[0:1], v[16:17]
	v_pk_mul_f32 v[18:19], v[2:3], v[18:19]
	v_cvt_pk_bf16_f32 v20, v16, v17
	s_waitcnt lgkmcnt(0)
	v_add_f32_e32 v16, v21, v22
	ds_bpermute_b32 v17, v224, v16
	v_cvt_pk_bf16_f32 v21, v18, v19
	v_lshl_add_u64 v[18:19], s[12:13], 0, v[32:33]
	v_readlane_b32 s62, v252, 18
	v_readlane_b32 s63, v252, 19
	v_readlane_b32 s64, v252, 20
	v_readlane_b32 s65, v252, 21
	v_readlane_b32 s66, v252, 22
	v_readlane_b32 s67, v252, 23
	v_readlane_b32 s68, v252, 24
	v_readlane_b32 s69, v252, 25
	v_readlane_b32 s70, v252, 26
	v_readlane_b32 s71, v252, 27
	v_readlane_b32 s72, v252, 28
	v_readlane_b32 s73, v252, 29
	global_store_dwordx2 v[18:19], v[20:21], off
	s_and_saveexec_b64 s[24:25], s[4:5]
	s_cbranch_execz .LBB0_246
	v_lshl_add_u64 v[18:19], v[146:147], 2, s[14:15]
	s_waitcnt lgkmcnt(0)
	v_add_f32_e32 v16, v16, v17
	v_add_f32_e32 v16, 0x48400000, v16
	v_add_f32_e32 v16, 0xc8400000, v16
	global_atomic_add_f32 v[18:19], v16, off
.LBB0_246:
	s_or_b64 exec, exec, s[24:25]
	s_waitcnt lgkmcnt(0)
	v_lshlrev_b64 v[16:17], 11, v[64:65]
	v_readlane_b32 s60, v252, 16
	v_lshl_add_u64 v[20:21], v[16:17], 0, v[140:141]
	s_waitcnt vmcnt(19)
	v_pk_add_f32 v[16:17], v[80:81], v[60:61]
	v_readlane_b32 s74, v252, 30
	v_readlane_b32 s75, v252, 31
	v_pk_add_f32 v[18:19], v[82:83], v[62:63]
	v_mul_f32_e32 v28, v17, v17
	v_lshl_add_u64 v[22:23], v[20:21], 2, s[74:75]
	global_store_dwordx4 v[22:23], v[16:19], off
	v_fmac_f32_e32 v28, v16, v16
	v_pk_mul_f32 v[14:15], v[14:15], v[18:19]
	v_pk_mul_f32 v[12:13], v[12:13], v[16:17]
	v_lshlrev_b64 v[16:17], 1, v[20:21]
	v_cvt_pk_bf16_f32 v12, v12, v13
	v_cvt_pk_bf16_f32 v13, v14, v15
	v_lshl_add_u64 v[14:15], s[12:13], 0, v[16:17]
	global_store_dwordx2 v[14:15], v[12:13], off
	s_waitcnt vmcnt(20)
	v_pk_add_f32 v[14:15], v[78:79], v[50:51]
	v_pk_add_f32 v[12:13], v[76:77], v[48:49]
	v_pk_mul_f32 v[10:11], v[10:11], v[14:15]
	v_pk_mul_f32 v[8:9], v[8:9], v[12:13]
	global_store_dwordx4 v[22:23], v[12:15], off offset:64
	v_cvt_pk_bf16_f32 v8, v8, v9
	v_cvt_pk_bf16_f32 v9, v10, v11
	v_or_b32_e32 v10, 32, v16
	v_mov_b32_e32 v11, v17
	v_lshl_add_u64 v[10:11], s[12:13], 0, v[10:11]
	global_store_dwordx2 v[10:11], v[8:9], off
	s_waitcnt vmcnt(21)
	v_pk_add_f32 v[10:11], v[74:75], v[38:39]
	v_pk_add_f32 v[8:9], v[72:73], v[36:37]
	v_pk_mul_f32 v[6:7], v[6:7], v[10:11]
	v_pk_mul_f32 v[4:5], v[4:5], v[8:9]
	v_mul_f32_e32 v29, v19, v19
	v_cvt_pk_bf16_f32 v4, v4, v5
	v_cvt_pk_bf16_f32 v5, v6, v7
	v_or_b32_e32 v6, 0x100, v16
	v_mov_b32_e32 v7, v17
	v_fmac_f32_e32 v29, v18, v18
	v_mul_f32_e32 v18, v13, v13
	v_mul_f32_e32 v19, v15, v15
	v_lshl_add_u64 v[6:7], s[12:13], 0, v[6:7]
	v_fmac_f32_e32 v18, v12, v12
	v_fmac_f32_e32 v19, v14, v14
	global_store_dwordx4 v[22:23], v[8:11], off offset:512
	v_mul_f32_e32 v12, v9, v9
	v_mul_f32_e32 v13, v11, v11
	global_store_dwordx2 v[6:7], v[4:5], off
	s_waitcnt vmcnt(22)
	v_pk_add_f32 v[6:7], v[70:71], v[26:27]
	v_pk_add_f32 v[4:5], v[68:69], v[24:25]
	v_add_f32_e32 v28, v28, v29
	v_add_f32_e32 v18, v18, v19
	v_fmac_f32_e32 v12, v8, v8
	v_fmac_f32_e32 v13, v10, v10
	v_mul_f32_e32 v8, v5, v5
	v_mul_f32_e32 v9, v7, v7
	v_add_f32_e32 v18, v28, v18
	v_add_f32_e32 v12, v12, v13
	v_fmac_f32_e32 v8, v4, v4
	v_fmac_f32_e32 v9, v6, v6
	v_add_f32_e32 v12, v18, v12
	v_add_f32_e32 v8, v8, v9
	v_add_f32_e32 v8, v12, v8
	ds_bpermute_b32 v9, v225, v8
	v_pk_mul_f32 v[0:1], v[0:1], v[4:5]
	global_store_dwordx4 v[22:23], v[4:7], off offset:576
	v_pk_mul_f32 v[2:3], v[2:3], v[6:7]
	v_or_b32_e32 v16, 0x120, v16
	v_cvt_pk_bf16_f32 v4, v0, v1
	s_waitcnt lgkmcnt(0)
	v_add_f32_e32 v0, v8, v9
	ds_bpermute_b32 v1, v224, v0
	v_cvt_pk_bf16_f32 v5, v2, v3
	v_lshl_add_u64 v[2:3], s[12:13], 0, v[16:17]
	v_readlane_b32 s61, v252, 17
	v_readlane_b32 s62, v252, 18
	v_readlane_b32 s63, v252, 19
	v_readlane_b32 s64, v252, 20
	v_readlane_b32 s65, v252, 21
	v_readlane_b32 s66, v252, 22
	v_readlane_b32 s67, v252, 23
	v_readlane_b32 s68, v252, 24
	v_readlane_b32 s69, v252, 25
	v_readlane_b32 s70, v252, 26
	v_readlane_b32 s71, v252, 27
	v_readlane_b32 s72, v252, 28
	v_readlane_b32 s73, v252, 29
	global_store_dwordx2 v[2:3], v[4:5], off
	s_and_saveexec_b64 s[24:25], s[4:5]
	s_cbranch_execz .LBB0_248
	v_lshl_add_u64 v[2:3], v[64:65], 2, s[14:15]
	s_waitcnt lgkmcnt(0)
	v_add_f32_e32 v0, v0, v1
	v_add_f32_e32 v0, 0x48400000, v0
	v_add_f32_e32 v0, 0xc8400000, v0
	global_atomic_add_f32 v[2:3], v0, off

.LBB0_852:
	v_lshl_add_u32 v200, s54, 8, v206
	v_readlane_b32 s60, v252, 16
	v_lshl_or_b32 v188, s55, 8, v208
	v_ashrrev_i32_e32 v201, 31, v200
	v_readlane_b32 s74, v252, 30
	v_readlane_b32 s75, v252, 31
	v_ashrrev_i32_e32 v189, 31, v188
	v_lshlrev_b64 v[112:113], 13, v[200:201]
	v_readlane_b32 s72, v252, 28
	v_readlane_b32 s73, v252, 29
	s_mov_b64 s[82:83], s[74:75]
	v_lshlrev_b64 v[144:145], 2, v[188:189]
	v_readlane_b32 s61, v252, 17
	v_readlane_b32 s62, v252, 18
	v_readlane_b32 s63, v252, 19
	v_readlane_b32 s64, v252, 20
	v_readlane_b32 s65, v252, 21
	v_readlane_b32 s66, v252, 22
	v_readlane_b32 s67, v252, 23
	v_readlane_b32 s68, v252, 24
	v_readlane_b32 s69, v252, 25
	v_readlane_b32 s70, v252, 26
	v_readlane_b32 s71, v252, 27
	v_lshl_add_u64 v[190:191], s[82:83], 0, v[112:113]
	s_mov_b64 s[80:81], s[72:73]
	v_lshl_add_u64 v[230:231], v[190:191], 0, v[144:145]
	v_readlane_b32 s60, v252, 32
	global_load_dwordx4 v[196:199], v[230:231], off
	global_load_dwordx4 v[216:219], v[230:231], off offset:64
	global_load_dwordx4 v[222:225], v[230:231], off offset:512
	v_readlane_b32 s74, v252, 46
	v_readlane_b32 s75, v252, 47
	v_or_b32_e32 v202, 16, v200
	v_or_b32_e32 v192, 32, v200
	v_lshl_add_u64 v[112:113], s[74:75], 0, v[144:145]
	global_load_dwordx4 v[128:131], v[112:113], off
	global_load_dwordx4 v[120:123], v[112:113], off offset:64
	global_load_dwordx4 v[116:119], v[112:113], off offset:512
	global_load_dwordx4 v[226:229], v[230:231], off offset:576
	v_ashrrev_i32_e32 v203, 31, v202
	v_ashrrev_i32_e32 v193, 31, v192
	v_lshlrev_b64 v[146:147], 13, v[202:203]
	v_lshlrev_b64 v[148:149], 13, v[192:193]
	v_lshl_add_u64 v[146:147], s[82:83], 0, v[146:147]
	global_load_dwordx4 v[112:115], v[112:113], off offset:576
	v_lshl_add_u64 v[148:149], s[82:83], 0, v[148:149]
	v_lshl_add_u64 v[204:205], v[146:147], 0, v[144:145]
	v_lshl_add_u64 v[194:195], v[148:149], 0, v[144:145]
	global_load_dwordx4 v[172:175], v[204:205], off
	global_load_dwordx4 v[168:171], v[204:205], off offset:64
	global_load_dwordx4 v[164:167], v[204:205], off offset:512
	global_load_dwordx4 v[160:163], v[204:205], off offset:576
	global_load_dwordx4 v[156:159], v[194:195], off
	global_load_dwordx4 v[152:155], v[194:195], off offset:64
	global_load_dwordx4 v[148:151], v[194:195], off offset:512
	global_load_dwordx4 v[144:147], v[194:195], off offset:576
	v_and_b32_e32 v214, 64, v212
	v_xor_b32_e32 v213, 16, v212
	v_add_u32_e32 v214, 64, v214
	v_xor_b32_e32 v215, 32, v212
	v_cmp_lt_i32_e32 vcc, v213, v214
	v_lshlrev_b64 v[232:233], 11, v[200:201]
	v_lshl_add_u64 v[232:233], v[232:233], 0, v[188:189]
	v_cndmask_b32_e32 v213, v212, v213, vcc
	v_cmp_lt_i32_e32 vcc, v215, v214
	v_lshlrev_b32_e32 v214, 2, v213
	v_lshlrev_b64 v[232:233], 1, v[232:233]
	v_cndmask_b32_e32 v215, v212, v215, vcc
	v_lshlrev_b32_e32 v213, 2, v215
	v_lshl_add_u64 v[234:235], s[14:15], 0, v[232:233]
	v_or_b32_e32 v236, 32, v232
	v_mov_b32_e32 v237, v233
	v_lshl_add_u64 v[236:237], s[14:15], 0, v[236:237]
	v_readlane_b32 s61, v252, 33
	v_readlane_b32 s62, v252, 34
	v_readlane_b32 s63, v252, 35
	v_readlane_b32 s64, v252, 36
	v_readlane_b32 s65, v252, 37
	v_readlane_b32 s66, v252, 38
	v_readlane_b32 s67, v252, 39
	v_readlane_b32 s68, v252, 40
	v_readlane_b32 s69, v252, 41
	v_readlane_b32 s70, v252, 42
	v_readlane_b32 s71, v252, 43
	v_readlane_b32 s72, v252, 44
	v_readlane_b32 s73, v252, 45
	s_waitcnt vmcnt(0)
	v_pk_add_f32 v[138:139], v[138:139], v[198:199]
	v_pk_add_f32 v[136:137], v[136:137], v[196:197]
	v_pk_add_f32 v[142:143], v[142:143], v[218:219]
	v_pk_add_f32 v[140:141], v[140:141], v[216:217]
	v_pk_add_f32 v[134:135], v[134:135], v[224:225]
	v_pk_add_f32 v[132:133], v[132:133], v[222:223]
	v_mul_f32_e32 v215, v137, v137
	v_mul_f32_e32 v221, v139, v139
	v_pk_mul_f32 v[196:197], v[130:131], v[138:139]
	v_pk_mul_f32 v[198:199], v[128:129], v[136:137]
	v_mul_f32_e32 v238, v141, v141
	v_mul_f32_e32 v239, v143, v143
	global_store_dwordx4 v[230:231], v[136:139], off
	v_pk_mul_f32 v[216:217], v[122:123], v[142:143]
	v_pk_mul_f32 v[218:219], v[120:121], v[140:141]
	v_mul_f32_e32 v240, v133, v133
	v_mul_f32_e32 v241, v135, v135
	v_fmac_f32_e32 v215, v136, v136
	v_fmac_f32_e32 v221, v138, v138
	v_cvt_pk_bf16_f32 v136, v198, v199
	v_cvt_pk_bf16_f32 v137, v196, v197
	v_fmac_f32_e32 v238, v140, v140
	v_fmac_f32_e32 v239, v142, v142
	v_cvt_pk_bf16_f32 v138, v218, v219
	v_cvt_pk_bf16_f32 v139, v216, v217
	v_fmac_f32_e32 v240, v132, v132
	v_fmac_f32_e32 v241, v134, v134
	v_add_f32_e32 v197, v215, v221
	global_store_dwordx2 v[234:235], v[136:137], off
	global_store_dwordx4 v[230:231], v[140:143], off offset:64
	v_add_f32_e32 v136, v238, v239
	v_pk_mul_f32 v[224:225], v[116:117], v[132:133]
	global_store_dwordx2 v[236:237], v[138:139], off
	global_store_dwordx4 v[230:231], v[132:135], off offset:512
	v_pk_mul_f32 v[222:223], v[118:119], v[134:135]
	v_cvt_pk_bf16_f32 v196, v224, v225
	v_add_f32_e32 v132, v240, v241
	v_add_f32_e32 v133, v197, v136
	v_add_f32_e32 v134, v133, v132
	v_or_b32_e32 v132, 0x100, v232
	v_mov_b32_e32 v133, v233
	v_cvt_pk_bf16_f32 v197, v222, v223
	v_lshl_add_u64 v[132:133], s[14:15], 0, v[132:133]
	v_pk_add_f32 v[126:127], v[126:127], v[228:229]
	v_pk_add_f32 v[124:125], v[124:125], v[226:227]
	global_store_dwordx2 v[132:133], v[196:197], off
	v_mul_f32_e32 v132, v125, v125
	v_mul_f32_e32 v133, v127, v127
	v_fmac_f32_e32 v132, v124, v124
	v_fmac_f32_e32 v133, v126, v126
	v_add_f32_e32 v132, v132, v133
	v_add_f32_e32 v133, v134, v132
	ds_bpermute_b32 v134, v214, v133
	global_store_dwordx4 v[230:231], v[124:127], off offset:576
	v_or_b32_e32 v232, 0x120, v232
	s_nop 0
	v_pk_mul_f32 v[124:125], v[112:113], v[124:125]
	v_pk_mul_f32 v[126:127], v[114:115], v[126:127]
	v_cvt_pk_bf16_f32 v132, v124, v125
	s_waitcnt lgkmcnt(0)
	v_add_f32_e32 v124, v133, v134
	ds_bpermute_b32 v125, v213, v124
	v_cvt_pk_bf16_f32 v133, v126, v127
	v_lshl_add_u64 v[126:127], s[14:15], 0, v[232:233]
	global_store_dwordx2 v[126:127], v[132:133], off
	s_and_saveexec_b64 s[28:29], s[2:3]
	s_cbranch_execz .LBB0_854
	v_lshl_add_u64 v[126:127], v[200:201], 2, s[16:17]
	s_waitcnt lgkmcnt(0)
	v_add_f32_e32 v124, v124, v125
	v_add_f32_e32 v124, 0x48400000, v124
	v_add_f32_e32 v124, 0xc8400000, v124
	global_atomic_add_f32 v[126:127], v124, off
.LBB0_854:
	s_or_b64 exec, exec, s[28:29]
	v_or_b32_e32 v196, 48, v200
	v_ashrrev_i32_e32 v197, 31, v196
	v_readlane_b32 s60, v252, 16
	s_waitcnt lgkmcnt(0)
	v_lshlrev_b64 v[124:125], 13, v[196:197]
	v_readlane_b32 s74, v252, 30
	v_readlane_b32 s75, v252, 31
	v_pk_add_f32 v[110:111], v[110:111], v[174:175]
	v_pk_add_f32 v[108:109], v[108:109], v[172:173]
	v_lshl_add_u64 v[124:125], s[74:75], 0, v[124:125]
	v_lshl_add_u64 v[198:199], v[188:189], 2, v[124:125]
	global_load_dwordx4 v[140:143], v[198:199], off
	global_load_dwordx4 v[136:139], v[198:199], off offset:64
	global_load_dwordx4 v[132:135], v[198:199], off offset:512
	global_load_dwordx4 v[124:127], v[198:199], off offset:576
	v_lshlrev_b64 v[216:217], 11, v[202:203]
	v_mul_f32_e32 v172, v109, v109
	v_mul_f32_e32 v173, v111, v111
	v_lshl_add_u64 v[216:217], v[216:217], 0, v[188:189]
	global_store_dwordx4 v[204:205], v[108:111], off
	v_fmac_f32_e32 v172, v108, v108
	v_fmac_f32_e32 v173, v110, v110
	v_pk_mul_f32 v[110:111], v[130:131], v[110:111]
	v_pk_mul_f32 v[108:109], v[128:129], v[108:109]
	v_add_f32_e32 v174, v172, v173
	v_cvt_pk_bf16_f32 v108, v108, v109
	v_cvt_pk_bf16_f32 v109, v110, v111
	v_lshlrev_b64 v[110:111], 1, v[216:217]
	v_lshl_add_u64 v[172:173], s[14:15], 0, v[110:111]
	v_pk_add_f32 v[106:107], v[106:107], v[170:171]
	v_pk_add_f32 v[104:105], v[104:105], v[168:169]
	global_store_dwordx2 v[172:173], v[108:109], off
	v_mul_f32_e32 v108, v105, v105
	v_mul_f32_e32 v109, v107, v107
	global_store_dwordx4 v[204:205], v[104:107], off offset:64
	v_fmac_f32_e32 v108, v104, v104
	v_fmac_f32_e32 v109, v106, v106
	v_pk_mul_f32 v[106:107], v[122:123], v[106:107]
	v_pk_mul_f32 v[104:105], v[120:121], v[104:105]
	v_pk_add_f32 v[102:103], v[102:103], v[166:167]
	v_cvt_pk_bf16_f32 v104, v104, v105
	v_cvt_pk_bf16_f32 v105, v106, v107
	v_or_b32_e32 v106, 32, v110
	v_mov_b32_e32 v107, v111
	v_lshl_add_u64 v[106:107], s[14:15], 0, v[106:107]
	v_pk_add_f32 v[100:101], v[100:101], v[164:165]
	global_store_dwordx2 v[106:107], v[104:105], off
	v_mul_f32_e32 v104, v101, v101
	v_mul_f32_e32 v105, v103, v103
	global_store_dwordx4 v[204:205], v[100:103], off offset:512
	v_fmac_f32_e32 v104, v100, v100
	v_fmac_f32_e32 v105, v102, v102
	v_pk_mul_f32 v[102:103], v[118:119], v[102:103]
	v_pk_mul_f32 v[100:101], v[116:117], v[100:101]
	v_pk_add_f32 v[98:99], v[98:99], v[162:163]
	v_cvt_pk_bf16_f32 v100, v100, v101
	v_cvt_pk_bf16_f32 v101, v102, v103
	v_or_b32_e32 v102, 0x100, v110
	v_mov_b32_e32 v103, v111
	v_lshl_add_u64 v[102:103], s[14:15], 0, v[102:103]
	v_pk_add_f32 v[96:97], v[96:97], v[160:161]
	v_add_f32_e32 v108, v108, v109
	global_store_dwordx2 v[102:103], v[100:101], off
	v_mul_f32_e32 v100, v97, v97
	v_mul_f32_e32 v101, v99, v99
	v_add_f32_e32 v108, v174, v108
	v_add_f32_e32 v104, v104, v105
	v_fmac_f32_e32 v100, v96, v96
	v_fmac_f32_e32 v101, v98, v98
	v_add_f32_e32 v104, v108, v104
	v_add_f32_e32 v100, v100, v101
	v_add_f32_e32 v101, v104, v100
	ds_bpermute_b32 v102, v214, v101
	global_store_dwordx4 v[204:205], v[96:99], off offset:576
	v_or_b32_e32 v110, 0x120, v110
	v_readlane_b32 s61, v252, 17
	v_pk_mul_f32 v[96:97], v[112:113], v[96:97]
	v_pk_mul_f32 v[98:99], v[114:115], v[98:99]
	v_cvt_pk_bf16_f32 v100, v96, v97
	s_waitcnt lgkmcnt(0)
	v_add_f32_e32 v96, v101, v102
	ds_bpermute_b32 v97, v213, v96
	v_cvt_pk_bf16_f32 v101, v98, v99
	v_lshl_add_u64 v[98:99], s[14:15], 0, v[110:111]
	v_readlane_b32 s62, v252, 18
	v_readlane_b32 s63, v252, 19
	v_readlane_b32 s64, v252, 20
	v_readlane_b32 s65, v252, 21
	v_readlane_b32 s66, v252, 22
	v_readlane_b32 s67, v252, 23
	v_readlane_b32 s68, v252, 24
	v_readlane_b32 s69, v252, 25
	v_readlane_b32 s70, v252, 26
	v_readlane_b32 s71, v252, 27
	v_readlane_b32 s72, v252, 28
	v_readlane_b32 s73, v252, 29
	global_store_dwordx2 v[98:99], v[100:101], off
	s_and_saveexec_b64 s[28:29], s[2:3]
	s_cbranch_execz .LBB0_856
	v_lshl_add_u64 v[98:99], v[202:203], 2, s[16:17]
	s_waitcnt lgkmcnt(0)
	v_add_f32_e32 v96, v96, v97
	v_add_f32_e32 v96, 0x48400000, v96
	v_add_f32_e32 v96, 0xc8400000, v96
	global_atomic_add_f32 v[98:99], v96, off
.LBB0_856:
	s_or_b64 exec, exec, s[28:29]
	v_add_u32_e32 v160, 0x80, v200
	v_ashrrev_i32_e32 v161, 31, v160
	v_readlane_b32 s60, v252, 16
	s_waitcnt lgkmcnt(0)
	v_lshlrev_b64 v[96:97], 13, v[160:161]
	v_readlane_b32 s74, v252, 30
	v_readlane_b32 s75, v252, 31
	v_pk_add_f32 v[94:95], v[94:95], v[158:159]
	v_pk_add_f32 v[92:93], v[92:93], v[156:157]
	v_lshl_add_u64 v[96:97], s[74:75], 0, v[96:97]
	v_lshl_add_u64 v[162:163], v[188:189], 2, v[96:97]
	global_load_dwordx4 v[108:111], v[162:163], off
	global_load_dwordx4 v[104:107], v[162:163], off offset:64
	global_load_dwordx4 v[100:103], v[162:163], off offset:512
	global_load_dwordx4 v[96:99], v[162:163], off offset:576
	v_lshlrev_b64 v[164:165], 11, v[192:193]
	v_mul_f32_e32 v156, v93, v93
	v_mul_f32_e32 v157, v95, v95
	v_lshl_add_u64 v[164:165], v[164:165], 0, v[188:189]
	global_store_dwordx4 v[194:195], v[92:95], off
	v_fmac_f32_e32 v156, v92, v92
	v_fmac_f32_e32 v157, v94, v94
	v_pk_mul_f32 v[94:95], v[130:131], v[94:95]
	v_pk_mul_f32 v[92:93], v[128:129], v[92:93]
	v_add_f32_e32 v158, v156, v157
	v_cvt_pk_bf16_f32 v92, v92, v93
	v_cvt_pk_bf16_f32 v93, v94, v95
	v_lshlrev_b64 v[94:95], 1, v[164:165]
	v_lshl_add_u64 v[156:157], s[14:15], 0, v[94:95]
	v_pk_add_f32 v[90:91], v[90:91], v[154:155]
	v_pk_add_f32 v[88:89], v[88:89], v[152:153]
	global_store_dwordx2 v[156:157], v[92:93], off
	v_mul_f32_e32 v92, v89, v89
	v_mul_f32_e32 v93, v91, v91
	global_store_dwordx4 v[194:195], v[88:91], off offset:64
	v_fmac_f32_e32 v92, v88, v88
	v_fmac_f32_e32 v93, v90, v90
	v_pk_mul_f32 v[90:91], v[122:123], v[90:91]
	v_pk_mul_f32 v[88:89], v[120:121], v[88:89]
	v_pk_add_f32 v[86:87], v[86:87], v[150:151]
	v_cvt_pk_bf16_f32 v88, v88, v89
	v_cvt_pk_bf16_f32 v89, v90, v91
	v_or_b32_e32 v90, 32, v94
	v_mov_b32_e32 v91, v95
	v_lshl_add_u64 v[90:91], s[14:15], 0, v[90:91]
	v_pk_add_f32 v[84:85], v[84:85], v[148:149]
	global_store_dwordx2 v[90:91], v[88:89], off
	v_mul_f32_e32 v88, v85, v85
	v_mul_f32_e32 v89, v87, v87
	global_store_dwordx4 v[194:195], v[84:87], off offset:512
	v_fmac_f32_e32 v88, v84, v84
	v_fmac_f32_e32 v89, v86, v86
	v_pk_mul_f32 v[86:87], v[118:119], v[86:87]
	v_pk_mul_f32 v[84:85], v[116:117], v[84:85]
	v_pk_add_f32 v[82:83], v[82:83], v[146:147]
	v_cvt_pk_bf16_f32 v84, v84, v85
	v_cvt_pk_bf16_f32 v85, v86, v87
	v_or_b32_e32 v86, 0x100, v94
	v_mov_b32_e32 v87, v95
	v_lshl_add_u64 v[86:87], s[14:15], 0, v[86:87]
	v_pk_add_f32 v[80:81], v[80:81], v[144:145]
	v_add_f32_e32 v92, v92, v93
	global_store_dwordx2 v[86:87], v[84:85], off
	v_mul_f32_e32 v84, v81, v81
	v_mul_f32_e32 v85, v83, v83
	v_add_f32_e32 v92, v158, v92
	v_add_f32_e32 v88, v88, v89
	v_fmac_f32_e32 v84, v80, v80
	v_fmac_f32_e32 v85, v82, v82
	v_add_f32_e32 v88, v92, v88
	v_add_f32_e32 v84, v84, v85
	v_add_f32_e32 v85, v88, v84
	ds_bpermute_b32 v86, v214, v85
	global_store_dwordx4 v[194:195], v[80:83], off offset:576
	v_or_b32_e32 v94, 0x120, v94
	v_readlane_b32 s61, v252, 17
	v_pk_mul_f32 v[80:81], v[112:113], v[80:81]
	v_pk_mul_f32 v[82:83], v[114:115], v[82:83]
	v_cvt_pk_bf16_f32 v84, v80, v81
	s_waitcnt lgkmcnt(0)
	v_add_f32_e32 v80, v85, v86
	ds_bpermute_b32 v81, v213, v80
	v_cvt_pk_bf16_f32 v85, v82, v83
	v_lshl_add_u64 v[82:83], s[14:15], 0, v[94:95]
	v_readlane_b32 s62, v252, 18
	v_readlane_b32 s63, v252, 19
	v_readlane_b32 s64, v252, 20
	v_readlane_b32 s65, v252, 21
	v_readlane_b32 s66, v252, 22
	v_readlane_b32 s67, v252, 23
	v_readlane_b32 s68, v252, 24
	v_readlane_b32 s69, v252, 25
	v_readlane_b32 s70, v252, 26
	v_readlane_b32 s71, v252, 27
	v_readlane_b32 s72, v252, 28
	v_readlane_b32 s73, v252, 29
	global_store_dwordx2 v[82:83], v[84:85], off
	s_and_saveexec_b64 s[28:29], s[2:3]
	s_cbranch_execz .LBB0_858
	v_lshl_add_u64 v[82:83], v[192:193], 2, s[16:17]
	s_waitcnt lgkmcnt(0)
	v_add_f32_e32 v80, v80, v81
	v_add_f32_e32 v80, 0x48400000, v80
	v_add_f32_e32 v80, 0xc8400000, v80
	global_atomic_add_f32 v[82:83], v80, off
.LBB0_858:
	s_or_b64 exec, exec, s[28:29]
	s_waitcnt lgkmcnt(0)
	v_lshl_add_u64 v[80:81], v[188:189], 2, v[190:191]
	v_lshl_add_u64 v[144:145], v[80:81], 0, s[24:25]
	v_add_co_u32_e32 v80, vcc, 0x120000, v80
	s_waitcnt vmcnt(23)
	v_pk_add_f32 v[78:79], v[78:79], v[142:143]
	v_addc_co_u32_e32 v81, vcc, 0, v81, vcc
	global_load_dwordx4 v[88:91], v[144:145], off offset:64
	global_load_dwordx4 v[84:87], v[144:145], off offset:512
	global_load_dwordx4 v[92:95], v[80:81], off
	s_nop 0
	global_load_dwordx4 v[80:83], v[144:145], off offset:576
	v_pk_add_f32 v[76:77], v[76:77], v[140:141]
	v_lshlrev_b64 v[146:147], 11, v[196:197]
	v_mul_f32_e32 v140, v77, v77
	v_mul_f32_e32 v141, v79, v79
	v_lshl_add_u64 v[146:147], v[146:147], 0, v[188:189]
	global_store_dwordx4 v[198:199], v[76:79], off
	v_fmac_f32_e32 v140, v76, v76
	v_fmac_f32_e32 v141, v78, v78
	v_pk_mul_f32 v[78:79], v[130:131], v[78:79]
	v_pk_mul_f32 v[76:77], v[128:129], v[76:77]
	v_add_f32_e32 v142, v140, v141
	v_cvt_pk_bf16_f32 v76, v76, v77
	v_cvt_pk_bf16_f32 v77, v78, v79
	v_lshlrev_b64 v[78:79], 1, v[146:147]
	v_lshl_add_u64 v[140:141], s[14:15], 0, v[78:79]
	s_waitcnt vmcnt(27)
	v_pk_add_f32 v[74:75], v[74:75], v[138:139]
	v_pk_add_f32 v[72:73], v[72:73], v[136:137]
	global_store_dwordx2 v[140:141], v[76:77], off
	v_mul_f32_e32 v76, v73, v73
	v_mul_f32_e32 v77, v75, v75
	global_store_dwordx4 v[198:199], v[72:75], off offset:64
	v_fmac_f32_e32 v76, v72, v72
	v_fmac_f32_e32 v77, v74, v74
	v_pk_mul_f32 v[74:75], v[122:123], v[74:75]
	v_pk_mul_f32 v[72:73], v[120:121], v[72:73]
	s_waitcnt vmcnt(28)
	v_pk_add_f32 v[70:71], v[70:71], v[134:135]
	v_cvt_pk_bf16_f32 v72, v72, v73
	v_cvt_pk_bf16_f32 v73, v74, v75
	v_or_b32_e32 v74, 32, v78
	v_mov_b32_e32 v75, v79
	v_lshl_add_u64 v[74:75], s[14:15], 0, v[74:75]
	v_pk_add_f32 v[68:69], v[68:69], v[132:133]
	global_store_dwordx2 v[74:75], v[72:73], off
	v_mul_f32_e32 v72, v69, v69
	v_mul_f32_e32 v73, v71, v71
	global_store_dwordx4 v[198:199], v[68:71], off offset:512
	v_fmac_f32_e32 v72, v68, v68
	v_fmac_f32_e32 v73, v70, v70
	v_pk_mul_f32 v[70:71], v[118:119], v[70:71]
	v_pk_mul_f32 v[68:69], v[116:117], v[68:69]
	s_waitcnt vmcnt(29)
	v_pk_add_f32 v[66:67], v[66:67], v[126:127]
	v_cvt_pk_bf16_f32 v68, v68, v69
	v_cvt_pk_bf16_f32 v69, v70, v71
	v_or_b32_e32 v70, 0x100, v78
	v_mov_b32_e32 v71, v79
	v_lshl_add_u64 v[70:71], s[14:15], 0, v[70:71]
	v_pk_add_f32 v[64:65], v[64:65], v[124:125]
	v_add_f32_e32 v76, v76, v77
	global_store_dwordx2 v[70:71], v[68:69], off
	v_mul_f32_e32 v68, v65, v65
	v_mul_f32_e32 v69, v67, v67
	v_add_f32_e32 v76, v142, v76
	v_add_f32_e32 v72, v72, v73
	v_fmac_f32_e32 v68, v64, v64
	v_fmac_f32_e32 v69, v66, v66
	v_add_f32_e32 v72, v76, v72
	v_add_f32_e32 v68, v68, v69
	v_add_f32_e32 v69, v72, v68
	ds_bpermute_b32 v70, v214, v69
	global_store_dwordx4 v[198:199], v[64:67], off offset:576
	v_or_b32_e32 v78, 0x120, v78
	s_nop 0
	v_pk_mul_f32 v[64:65], v[112:113], v[64:65]
	v_pk_mul_f32 v[66:67], v[114:115], v[66:67]
	v_cvt_pk_bf16_f32 v68, v64, v65
	s_waitcnt lgkmcnt(0)
	v_add_f32_e32 v64, v69, v70
	ds_bpermute_b32 v65, v213, v64
	v_cvt_pk_bf16_f32 v69, v66, v67
	v_lshl_add_u64 v[66:67], s[14:15], 0, v[78:79]
	global_store_dwordx2 v[66:67], v[68:69], off
	s_and_saveexec_b64 s[28:29], s[2:3]
	s_cbranch_execz .LBB0_860
	v_lshl_add_u64 v[66:67], v[196:197], 2, s[16:17]
	s_waitcnt lgkmcnt(0)
	v_add_f32_e32 v64, v64, v65
	v_add_f32_e32 v64, 0x48400000, v64
	v_add_f32_e32 v64, 0xc8400000, v64
	global_atomic_add_f32 v[66:67], v64, off
.LBB0_860:
	s_or_b64 exec, exec, s[28:29]
	v_or_b32_e32 v124, 32, v160
	v_ashrrev_i32_e32 v125, 31, v124
	v_readlane_b32 s60, v252, 16
	s_waitcnt lgkmcnt(0)
	v_lshlrev_b64 v[64:65], 13, v[124:125]
	v_readlane_b32 s74, v252, 30
	v_readlane_b32 s75, v252, 31
	s_waitcnt vmcnt(23)
	v_pk_add_f32 v[62:63], v[62:63], v[110:111]
	v_pk_add_f32 v[60:61], v[60:61], v[108:109]
	v_lshl_add_u64 v[64:65], s[74:75], 0, v[64:65]
	v_lshl_add_u64 v[126:127], v[188:189], 2, v[64:65]
	global_load_dwordx4 v[76:79], v[126:127], off
	global_load_dwordx4 v[72:75], v[126:127], off offset:64
	global_load_dwordx4 v[68:71], v[126:127], off offset:512
	global_load_dwordx4 v[64:67], v[126:127], off offset:576
	v_lshlrev_b64 v[132:133], 11, v[160:161]
	v_mul_f32_e32 v108, v61, v61
	v_mul_f32_e32 v109, v63, v63
	v_lshl_add_u64 v[132:133], v[132:133], 0, v[188:189]
	global_store_dwordx4 v[162:163], v[60:63], off
	v_fmac_f32_e32 v108, v60, v60
	v_fmac_f32_e32 v109, v62, v62
	v_pk_mul_f32 v[62:63], v[130:131], v[62:63]
	v_pk_mul_f32 v[60:61], v[128:129], v[60:61]
	v_add_f32_e32 v110, v108, v109
	v_cvt_pk_bf16_f32 v60, v60, v61
	v_cvt_pk_bf16_f32 v61, v62, v63
	v_lshlrev_b64 v[62:63], 1, v[132:133]
	v_lshl_add_u64 v[108:109], s[14:15], 0, v[62:63]
	s_waitcnt vmcnt(27)
	v_pk_add_f32 v[58:59], v[58:59], v[106:107]
	v_pk_add_f32 v[56:57], v[56:57], v[104:105]
	global_store_dwordx2 v[108:109], v[60:61], off
	v_mul_f32_e32 v60, v57, v57
	v_mul_f32_e32 v61, v59, v59
	global_store_dwordx4 v[162:163], v[56:59], off offset:64
	v_fmac_f32_e32 v60, v56, v56
	v_fmac_f32_e32 v61, v58, v58
	v_pk_mul_f32 v[58:59], v[122:123], v[58:59]
	v_pk_mul_f32 v[56:57], v[120:121], v[56:57]
	s_waitcnt vmcnt(28)
	v_pk_add_f32 v[54:55], v[54:55], v[102:103]
	v_cvt_pk_bf16_f32 v56, v56, v57
	v_cvt_pk_bf16_f32 v57, v58, v59
	v_or_b32_e32 v58, 32, v62
	v_mov_b32_e32 v59, v63
	v_lshl_add_u64 v[58:59], s[14:15], 0, v[58:59]
	v_pk_add_f32 v[52:53], v[52:53], v[100:101]
	global_store_dwordx2 v[58:59], v[56:57], off
	v_mul_f32_e32 v56, v53, v53
	v_mul_f32_e32 v57, v55, v55
	global_store_dwordx4 v[162:163], v[52:55], off offset:512
	v_fmac_f32_e32 v56, v52, v52
	v_fmac_f32_e32 v57, v54, v54
	v_pk_mul_f32 v[54:55], v[118:119], v[54:55]
	v_pk_mul_f32 v[52:53], v[116:117], v[52:53]
	s_waitcnt vmcnt(29)
	v_pk_add_f32 v[50:51], v[50:51], v[98:99]
	v_cvt_pk_bf16_f32 v52, v52, v53
	v_cvt_pk_bf16_f32 v53, v54, v55
	v_or_b32_e32 v54, 0x100, v62
	v_mov_b32_e32 v55, v63
	v_lshl_add_u64 v[54:55], s[14:15], 0, v[54:55]
	v_pk_add_f32 v[48:49], v[48:49], v[96:97]
	v_add_f32_e32 v60, v60, v61
	global_store_dwordx2 v[54:55], v[52:53], off
	v_mul_f32_e32 v52, v49, v49
	v_mul_f32_e32 v53, v51, v51
	v_add_f32_e32 v60, v110, v60
	v_add_f32_e32 v56, v56, v57
	v_fmac_f32_e32 v52, v48, v48
	v_fmac_f32_e32 v53, v50, v50
	v_add_f32_e32 v56, v60, v56
	v_add_f32_e32 v52, v52, v53
	v_add_f32_e32 v53, v56, v52
	ds_bpermute_b32 v54, v214, v53
	global_store_dwordx4 v[162:163], v[48:51], off offset:576
	v_or_b32_e32 v62, 0x120, v62
	v_readlane_b32 s61, v252, 17
	v_pk_mul_f32 v[48:49], v[112:113], v[48:49]
	v_pk_mul_f32 v[50:51], v[114:115], v[50:51]
	v_cvt_pk_bf16_f32 v52, v48, v49
	s_waitcnt lgkmcnt(0)
	v_add_f32_e32 v48, v53, v54
	ds_bpermute_b32 v49, v213, v48
	v_cvt_pk_bf16_f32 v53, v50, v51
	v_lshl_add_u64 v[50:51], s[14:15], 0, v[62:63]
	v_readlane_b32 s62, v252, 18
	v_readlane_b32 s63, v252, 19
	v_readlane_b32 s64, v252, 20
	v_readlane_b32 s65, v252, 21
	v_readlane_b32 s66, v252, 22
	v_readlane_b32 s67, v252, 23
	v_readlane_b32 s68, v252, 24
	v_readlane_b32 s69, v252, 25
	v_readlane_b32 s70, v252, 26
	v_readlane_b32 s71, v252, 27
	v_readlane_b32 s72, v252, 28
	v_readlane_b32 s73, v252, 29
	global_store_dwordx2 v[50:51], v[52:53], off
	s_and_saveexec_b64 s[28:29], s[2:3]
	s_cbranch_execz .LBB0_862
	v_lshl_add_u64 v[50:51], v[160:161], 2, s[16:17]
	s_waitcnt lgkmcnt(0)
	v_add_f32_e32 v48, v48, v49
	v_add_f32_e32 v48, 0x48400000, v48
	v_add_f32_e32 v48, 0xc8400000, v48
	global_atomic_add_f32 v[50:51], v48, off
.LBB0_862:
	s_or_b64 exec, exec, s[28:29]
	v_or_b32_e32 v96, 48, v160
	v_ashrrev_i32_e32 v97, 31, v96
	v_readlane_b32 s60, v252, 16
	s_waitcnt lgkmcnt(0)
	v_lshlrev_b64 v[48:49], 13, v[96:97]
	v_readlane_b32 s74, v252, 30
	v_readlane_b32 s75, v252, 31
	v_or_b32_e32 v100, 16, v160
	v_ashrrev_i32_e32 v101, 31, v100
	v_lshl_add_u64 v[48:49], s[74:75], 0, v[48:49]
	v_lshl_add_u64 v[98:99], v[188:189], 2, v[48:49]
	global_load_dwordx4 v[60:63], v[98:99], off
	global_load_dwordx4 v[56:59], v[98:99], off offset:64
	global_load_dwordx4 v[52:55], v[98:99], off offset:512
	global_load_dwordx4 v[48:51], v[98:99], off offset:576
	s_waitcnt vmcnt(25)
	v_pk_add_f32 v[46:47], v[46:47], v[94:95]
	v_pk_add_f32 v[44:45], v[44:45], v[92:93]
	v_lshlrev_b64 v[102:103], 11, v[100:101]
	v_mul_f32_e32 v92, v45, v45
	v_mul_f32_e32 v93, v47, v47
	v_lshl_add_u64 v[102:103], v[102:103], 0, v[188:189]
	global_store_dwordx4 v[144:145], v[44:47], off
	v_fmac_f32_e32 v92, v44, v44
	v_fmac_f32_e32 v93, v46, v46
	v_pk_mul_f32 v[46:47], v[130:131], v[46:47]
	v_pk_mul_f32 v[44:45], v[128:129], v[44:45]
	v_add_f32_e32 v94, v92, v93
	v_cvt_pk_bf16_f32 v44, v44, v45
	v_cvt_pk_bf16_f32 v45, v46, v47
	v_lshlrev_b64 v[46:47], 1, v[102:103]
	v_lshl_add_u64 v[92:93], s[14:15], 0, v[46:47]
	v_pk_add_f32 v[42:43], v[42:43], v[90:91]
	v_pk_add_f32 v[40:41], v[40:41], v[88:89]
	global_store_dwordx2 v[92:93], v[44:45], off
	v_mul_f32_e32 v44, v41, v41
	v_mul_f32_e32 v45, v43, v43
	global_store_dwordx4 v[144:145], v[40:43], off offset:64
	v_fmac_f32_e32 v44, v40, v40
	v_fmac_f32_e32 v45, v42, v42
	v_pk_mul_f32 v[42:43], v[122:123], v[42:43]
	v_pk_mul_f32 v[40:41], v[120:121], v[40:41]
	v_pk_add_f32 v[38:39], v[38:39], v[86:87]
	v_cvt_pk_bf16_f32 v40, v40, v41
	v_cvt_pk_bf16_f32 v41, v42, v43
	v_or_b32_e32 v42, 32, v46
	v_mov_b32_e32 v43, v47
	v_lshl_add_u64 v[42:43], s[14:15], 0, v[42:43]
	v_pk_add_f32 v[36:37], v[36:37], v[84:85]
	global_store_dwordx2 v[42:43], v[40:41], off
	v_mul_f32_e32 v40, v37, v37
	v_mul_f32_e32 v41, v39, v39
	global_store_dwordx4 v[144:145], v[36:39], off offset:512
	v_fmac_f32_e32 v40, v36, v36
	v_fmac_f32_e32 v41, v38, v38
	v_pk_mul_f32 v[38:39], v[118:119], v[38:39]
	v_pk_mul_f32 v[36:37], v[116:117], v[36:37]
	s_waitcnt vmcnt(29)
	v_pk_add_f32 v[34:35], v[34:35], v[82:83]
	v_cvt_pk_bf16_f32 v36, v36, v37
	v_cvt_pk_bf16_f32 v37, v38, v39
	v_or_b32_e32 v38, 0x100, v46
	v_mov_b32_e32 v39, v47
	v_lshl_add_u64 v[38:39], s[14:15], 0, v[38:39]
	v_pk_add_f32 v[32:33], v[32:33], v[80:81]
	v_add_f32_e32 v44, v44, v45
	global_store_dwordx2 v[38:39], v[36:37], off
	v_mul_f32_e32 v36, v33, v33
	v_mul_f32_e32 v37, v35, v35
	v_add_f32_e32 v44, v94, v44
	v_add_f32_e32 v40, v40, v41
	v_fmac_f32_e32 v36, v32, v32
	v_fmac_f32_e32 v37, v34, v34
	v_add_f32_e32 v40, v44, v40
	v_add_f32_e32 v36, v36, v37
	v_add_f32_e32 v37, v40, v36
	ds_bpermute_b32 v38, v214, v37
	global_store_dwordx4 v[144:145], v[32:35], off offset:576
	v_or_b32_e32 v46, 0x120, v46
	v_readlane_b32 s61, v252, 17
	v_pk_mul_f32 v[32:33], v[112:113], v[32:33]
	v_pk_mul_f32 v[34:35], v[114:115], v[34:35]
	v_cvt_pk_bf16_f32 v36, v32, v33
	s_waitcnt lgkmcnt(0)
	v_add_f32_e32 v32, v37, v38
	ds_bpermute_b32 v33, v213, v32
	v_cvt_pk_bf16_f32 v37, v34, v35
	v_lshl_add_u64 v[34:35], s[14:15], 0, v[46:47]
	v_readlane_b32 s62, v252, 18
	v_readlane_b32 s63, v252, 19
	v_readlane_b32 s64, v252, 20
	v_readlane_b32 s65, v252, 21
	v_readlane_b32 s66, v252, 22
	v_readlane_b32 s67, v252, 23
	v_readlane_b32 s68, v252, 24
	v_readlane_b32 s69, v252, 25
	v_readlane_b32 s70, v252, 26
	v_readlane_b32 s71, v252, 27
	v_readlane_b32 s72, v252, 28
	v_readlane_b32 s73, v252, 29
	global_store_dwordx2 v[34:35], v[36:37], off
	s_and_saveexec_b64 s[28:29], s[2:3]
	s_cbranch_execz .LBB0_864
	v_lshl_add_u64 v[34:35], v[100:101], 2, s[16:17]
	s_waitcnt lgkmcnt(0)
	v_add_f32_e32 v32, v32, v33
	v_add_f32_e32 v32, 0x48400000, v32
	v_add_f32_e32 v32, 0xc8400000, v32
	global_atomic_add_f32 v[34:35], v32, off
.LBB0_864:
	s_or_b64 exec, exec, s[28:29]
	s_waitcnt vmcnt(23)
	v_pk_add_f32 v[30:31], v[30:31], v[78:79]
	v_pk_add_f32 v[28:29], v[28:29], v[76:77]
	s_waitcnt lgkmcnt(0)
	v_lshlrev_b64 v[32:33], 11, v[124:125]
	v_mul_f32_e32 v34, v29, v29
	v_mul_f32_e32 v35, v31, v31
	v_lshl_add_u64 v[32:33], v[32:33], 0, v[188:189]
	global_store_dwordx4 v[126:127], v[28:31], off
	v_fmac_f32_e32 v34, v28, v28
	v_fmac_f32_e32 v35, v30, v30
	v_pk_mul_f32 v[30:31], v[130:131], v[30:31]
	v_pk_mul_f32 v[28:29], v[128:129], v[28:29]
	s_waitcnt vmcnt(23)
	v_pk_add_f32 v[26:27], v[26:27], v[74:75]
	v_cvt_pk_bf16_f32 v28, v28, v29
	v_cvt_pk_bf16_f32 v29, v30, v31
	v_lshlrev_b64 v[30:31], 1, v[32:33]
	v_lshl_add_u64 v[32:33], s[14:15], 0, v[30:31]
	v_pk_add_f32 v[24:25], v[24:25], v[72:73]
	global_store_dwordx2 v[32:33], v[28:29], off
	v_mul_f32_e32 v28, v25, v25
	v_mul_f32_e32 v29, v27, v27
	global_store_dwordx4 v[126:127], v[24:27], off offset:64
	v_fmac_f32_e32 v28, v24, v24
	v_fmac_f32_e32 v29, v26, v26
	v_pk_mul_f32 v[26:27], v[122:123], v[26:27]
	v_pk_mul_f32 v[24:25], v[120:121], v[24:25]
	s_waitcnt vmcnt(24)
	v_pk_add_f32 v[22:23], v[22:23], v[70:71]
	v_cvt_pk_bf16_f32 v24, v24, v25
	v_cvt_pk_bf16_f32 v25, v26, v27
	v_or_b32_e32 v26, 32, v30
	v_mov_b32_e32 v27, v31
	v_lshl_add_u64 v[26:27], s[14:15], 0, v[26:27]
	v_pk_add_f32 v[20:21], v[20:21], v[68:69]
	global_store_dwordx2 v[26:27], v[24:25], off
	v_mul_f32_e32 v24, v21, v21
	v_mul_f32_e32 v25, v23, v23
	global_store_dwordx4 v[126:127], v[20:23], off offset:512
	v_fmac_f32_e32 v24, v20, v20
	v_fmac_f32_e32 v25, v22, v22
	v_pk_mul_f32 v[22:23], v[118:119], v[22:23]
	v_pk_mul_f32 v[20:21], v[116:117], v[20:21]
	s_waitcnt vmcnt(25)
	v_pk_add_f32 v[18:19], v[18:19], v[66:67]
	v_cvt_pk_bf16_f32 v20, v20, v21
	v_cvt_pk_bf16_f32 v21, v22, v23
	v_or_b32_e32 v22, 0x100, v30
	v_mov_b32_e32 v23, v31
	v_lshl_add_u64 v[22:23], s[14:15], 0, v[22:23]
	v_pk_add_f32 v[16:17], v[16:17], v[64:65]
	v_add_f32_e32 v34, v34, v35
	v_add_f32_e32 v28, v28, v29
	global_store_dwordx2 v[22:23], v[20:21], off
	v_mul_f32_e32 v20, v17, v17
	v_mul_f32_e32 v21, v19, v19
	v_add_f32_e32 v28, v34, v28
	v_add_f32_e32 v24, v24, v25
	v_fmac_f32_e32 v20, v16, v16
	v_fmac_f32_e32 v21, v18, v18
	v_add_f32_e32 v24, v28, v24
	v_add_f32_e32 v20, v20, v21
	v_add_f32_e32 v21, v24, v20
	ds_bpermute_b32 v22, v214, v21
	global_store_dwordx4 v[126:127], v[16:19], off offset:576
	v_or_b32_e32 v30, 0x120, v30
	s_nop 0
	v_pk_mul_f32 v[16:17], v[112:113], v[16:17]
	v_pk_mul_f32 v[18:19], v[114:115], v[18:19]
	v_cvt_pk_bf16_f32 v20, v16, v17
	s_waitcnt lgkmcnt(0)
	v_add_f32_e32 v16, v21, v22
	ds_bpermute_b32 v17, v213, v16
	v_cvt_pk_bf16_f32 v21, v18, v19
	v_lshl_add_u64 v[18:19], s[14:15], 0, v[30:31]
	global_store_dwordx2 v[18:19], v[20:21], off
	s_and_saveexec_b64 s[28:29], s[2:3]
	s_cbranch_execz .LBB0_866
	v_lshl_add_u64 v[18:19], v[124:125], 2, s[16:17]
	s_waitcnt lgkmcnt(0)
	v_add_f32_e32 v16, v16, v17
	v_add_f32_e32 v16, 0x48400000, v16
	v_add_f32_e32 v16, 0xc8400000, v16
	global_atomic_add_f32 v[18:19], v16, off
.LBB0_866:
	s_or_b64 exec, exec, s[28:29]
	s_waitcnt vmcnt(19)
	v_pk_add_f32 v[14:15], v[14:15], v[62:63]
	v_pk_add_f32 v[12:13], v[12:13], v[60:61]
	s_waitcnt lgkmcnt(0)
	v_lshlrev_b64 v[16:17], 11, v[96:97]
	v_mul_f32_e32 v18, v13, v13
	v_mul_f32_e32 v19, v15, v15
	v_lshl_add_u64 v[16:17], v[16:17], 0, v[188:189]
	global_store_dwordx4 v[98:99], v[12:15], off
	v_fmac_f32_e32 v18, v12, v12
	v_fmac_f32_e32 v19, v14, v14
	v_pk_mul_f32 v[14:15], v[130:131], v[14:15]
	v_pk_mul_f32 v[12:13], v[128:129], v[12:13]
	s_waitcnt vmcnt(19)
	v_pk_add_f32 v[10:11], v[10:11], v[58:59]
	v_cvt_pk_bf16_f32 v12, v12, v13
	v_cvt_pk_bf16_f32 v13, v14, v15
	v_lshlrev_b64 v[14:15], 1, v[16:17]
	v_lshl_add_u64 v[16:17], s[14:15], 0, v[14:15]
	v_pk_add_f32 v[8:9], v[8:9], v[56:57]
	global_store_dwordx2 v[16:17], v[12:13], off
	v_mul_f32_e32 v12, v9, v9
	v_mul_f32_e32 v13, v11, v11
	global_store_dwordx4 v[98:99], v[8:11], off offset:64
	v_fmac_f32_e32 v12, v8, v8
	v_fmac_f32_e32 v13, v10, v10
	v_pk_mul_f32 v[10:11], v[122:123], v[10:11]
	v_pk_mul_f32 v[8:9], v[120:121], v[8:9]
	s_waitcnt vmcnt(20)
	v_pk_add_f32 v[6:7], v[6:7], v[54:55]
	v_cvt_pk_bf16_f32 v8, v8, v9
	v_cvt_pk_bf16_f32 v9, v10, v11
	v_or_b32_e32 v10, 32, v14
	v_mov_b32_e32 v11, v15
	v_lshl_add_u64 v[10:11], s[14:15], 0, v[10:11]
	v_pk_add_f32 v[4:5], v[4:5], v[52:53]
	global_store_dwordx2 v[10:11], v[8:9], off
	v_mul_f32_e32 v8, v5, v5
	v_mul_f32_e32 v9, v7, v7
	global_store_dwordx4 v[98:99], v[4:7], off offset:512
	v_fmac_f32_e32 v8, v4, v4
	v_fmac_f32_e32 v9, v6, v6
	v_pk_mul_f32 v[6:7], v[118:119], v[6:7]
	v_pk_mul_f32 v[4:5], v[116:117], v[4:5]
	s_waitcnt vmcnt(21)
	v_pk_add_f32 v[2:3], v[2:3], v[50:51]
	v_cvt_pk_bf16_f32 v4, v4, v5
	v_cvt_pk_bf16_f32 v5, v6, v7
	v_or_b32_e32 v6, 0x100, v14
	v_mov_b32_e32 v7, v15
	v_lshl_add_u64 v[6:7], s[14:15], 0, v[6:7]
	v_pk_add_f32 v[0:1], v[0:1], v[48:49]
	v_add_f32_e32 v18, v18, v19
	v_add_f32_e32 v12, v12, v13
	global_store_dwordx2 v[6:7], v[4:5], off
	v_mul_f32_e32 v4, v1, v1
	v_mul_f32_e32 v5, v3, v3
	v_add_f32_e32 v12, v18, v12
	v_add_f32_e32 v8, v8, v9
	v_fmac_f32_e32 v4, v0, v0
	v_fmac_f32_e32 v5, v2, v2
	v_add_f32_e32 v8, v12, v8
	v_add_f32_e32 v4, v4, v5
	v_add_f32_e32 v5, v8, v4
	ds_bpermute_b32 v6, v214, v5
	global_store_dwordx4 v[98:99], v[0:3], off offset:576
	v_or_b32_e32 v14, 0x120, v14
	s_nop 0
	v_pk_mul_f32 v[0:1], v[112:113], v[0:1]
	v_pk_mul_f32 v[2:3], v[114:115], v[2:3]
	v_cvt_pk_bf16_f32 v4, v0, v1
	s_waitcnt lgkmcnt(0)
	v_add_f32_e32 v0, v5, v6
	ds_bpermute_b32 v1, v213, v0
	v_cvt_pk_bf16_f32 v5, v2, v3
	v_lshl_add_u64 v[2:3], s[14:15], 0, v[14:15]
	global_store_dwordx2 v[2:3], v[4:5], off
	s_and_saveexec_b64 s[28:29], s[2:3]
	s_cbranch_execz .LBB0_868
	v_lshl_add_u64 v[2:3], v[96:97], 2, s[16:17]
	s_waitcnt lgkmcnt(0)
	v_add_f32_e32 v0, v0, v1
	v_add_f32_e32 v0, 0x48400000, v0
	v_add_f32_e32 v0, 0xc8400000, v0
	global_atomic_add_f32 v[2:3], v0, off

.LBB0_1060:
	v_readlane_b32 s60, v252, 16
	v_lshl_add_u32 v64, s54, 8, v218
	v_readlane_b32 s61, v252, 17
	v_readlane_b32 s62, v252, 18
	v_readlane_b32 s63, v252, 19
	v_readlane_b32 s72, v252, 28
	v_readlane_b32 s73, v252, 29
	v_lshl_or_b32 v144, s55, 8, v221
	v_ashrrev_i32_e32 v65, 31, v64
	v_readlane_b32 s74, v252, 30
	v_readlane_b32 s75, v252, 31
	s_mov_b64 s[60:61], s[72:73]
	v_ashrrev_i32_e32 v145, 31, v144
	s_waitcnt lgkmcnt(0)
	v_lshlrev_b64 v[0:1], 13, v[64:65]
	s_mov_b64 s[62:63], s[74:75]
	v_lshlrev_b64 v[16:17], 2, v[144:145]
	v_lshl_add_u64 v[210:211], s[62:63], 0, v[0:1]
	v_readlane_b32 s66, v252, 22
	v_readlane_b32 s67, v252, 23
	v_lshl_add_u64 v[228:229], v[210:211], 0, v[16:17]
	s_mov_b64 s[54:55], s[66:67]
	global_load_dwordx4 v[28:31], v[228:229], off
	global_load_dwordx4 v[40:43], v[228:229], off offset:64
	global_load_dwordx4 v[52:55], v[228:229], off offset:512
	v_lshl_add_u64 v[0:1], s[54:55], 0, v[16:17]
	global_load_dwordx4 v[12:15], v[0:1], off
	global_load_dwordx4 v[8:11], v[0:1], off offset:64
	global_load_dwordx4 v[4:7], v[0:1], off offset:512
	global_load_dwordx4 v[60:63], v[228:229], off offset:576
	v_or_b32_e32 v66, 16, v64
	v_or_b32_e32 v212, 32, v64
	v_ashrrev_i32_e32 v67, 31, v66
	v_ashrrev_i32_e32 v213, 31, v212
	v_lshlrev_b64 v[18:19], 13, v[66:67]
	v_lshlrev_b64 v[20:21], 13, v[212:213]
	v_lshl_add_u64 v[18:19], s[62:63], 0, v[18:19]
	global_load_dwordx4 v[0:3], v[0:1], off offset:576
	v_lshl_add_u64 v[20:21], s[62:63], 0, v[20:21]
	v_lshl_add_u64 v[216:217], v[18:19], 0, v[16:17]
	v_lshl_add_u64 v[214:215], v[20:21], 0, v[16:17]
	global_load_dwordx4 v[56:59], v[216:217], off
	global_load_dwordx4 v[48:51], v[216:217], off offset:64
	global_load_dwordx4 v[36:39], v[216:217], off offset:512
	global_load_dwordx4 v[24:27], v[216:217], off offset:576
	global_load_dwordx4 v[44:47], v[214:215], off
	global_load_dwordx4 v[32:35], v[214:215], off offset:64
	global_load_dwordx4 v[20:23], v[214:215], off offset:512
	global_load_dwordx4 v[16:19], v[214:215], off offset:576
	v_and_b32_e32 v227, 64, v225
	v_xor_b32_e32 v226, 16, v225
	v_add_u32_e32 v227, 64, v227
	v_xor_b32_e32 v230, 32, v225
	v_cmp_lt_i32_e32 vcc, v226, v227
	v_readlane_b32 s64, v252, 20
	v_readlane_b32 s65, v252, 21
	v_cndmask_b32_e32 v226, v225, v226, vcc
	v_cmp_lt_i32_e32 vcc, v230, v227
	v_lshlrev_b32_e32 v227, 2, v226
	v_readlane_b32 s68, v252, 24
	v_cndmask_b32_e32 v232, v225, v230, vcc
	v_lshlrev_b64 v[230:231], 11, v[64:65]
	v_lshl_add_u64 v[230:231], v[230:231], 0, v[144:145]
	v_lshlrev_b64 v[230:231], 1, v[230:231]
	v_lshlrev_b32_e32 v226, 2, v232
	v_lshl_add_u64 v[232:233], s[12:13], 0, v[230:231]
	v_or_b32_e32 v234, 32, v230
	v_mov_b32_e32 v235, v231
	v_lshl_add_u64 v[234:235], s[12:13], 0, v[234:235]
	v_readlane_b32 s69, v252, 25
	v_readlane_b32 s70, v252, 26
	v_readlane_b32 s71, v252, 27
	s_waitcnt vmcnt(0)
	v_pk_add_f32 v[30:31], v[198:199], v[30:31]
	v_pk_add_f32 v[28:29], v[200:201], v[28:29]
	v_pk_add_f32 v[42:43], v[202:203], v[42:43]
	v_pk_add_f32 v[40:41], v[204:205], v[40:41]
	v_pk_add_f32 v[54:55], v[208:209], v[54:55]
	v_pk_add_f32 v[52:53], v[206:207], v[52:53]
	v_mul_f32_e32 v236, v29, v29
	v_mul_f32_e32 v237, v31, v31
	v_pk_mul_f32 v[198:199], v[14:15], v[30:31]
	v_pk_mul_f32 v[200:201], v[12:13], v[28:29]
	v_mul_f32_e32 v238, v41, v41
	v_mul_f32_e32 v239, v43, v43
	global_store_dwordx4 v[228:229], v[28:31], off
	v_mul_f32_e32 v240, v53, v53
	v_mul_f32_e32 v241, v55, v55
	v_fmac_f32_e32 v236, v28, v28
	v_fmac_f32_e32 v237, v30, v30
	v_cvt_pk_bf16_f32 v28, v200, v201
	v_cvt_pk_bf16_f32 v29, v198, v199
	v_fmac_f32_e32 v238, v40, v40
	v_fmac_f32_e32 v239, v42, v42
	v_fmac_f32_e32 v240, v52, v52
	v_fmac_f32_e32 v241, v54, v54
	v_add_f32_e32 v199, v236, v237
	global_store_dwordx2 v[232:233], v[28:29], off
	global_store_dwordx4 v[228:229], v[40:43], off offset:64
	v_add_f32_e32 v28, v238, v239
	v_add_f32_e32 v29, v240, v241
	v_add_f32_e32 v28, v199, v28
	v_pk_mul_f32 v[202:203], v[10:11], v[42:43]
	v_pk_mul_f32 v[204:205], v[8:9], v[40:41]
	v_pk_mul_f32 v[206:207], v[6:7], v[54:55]
	v_pk_mul_f32 v[208:209], v[4:5], v[52:53]
	v_add_f32_e32 v40, v28, v29
	v_or_b32_e32 v28, 0x100, v230
	v_mov_b32_e32 v29, v231
	v_cvt_pk_bf16_f32 v30, v204, v205
	v_cvt_pk_bf16_f32 v31, v202, v203
	v_cvt_pk_bf16_f32 v198, v208, v209
	v_cvt_pk_bf16_f32 v199, v206, v207
	v_lshl_add_u64 v[28:29], s[12:13], 0, v[28:29]
	global_store_dwordx2 v[234:235], v[30:31], off
	global_store_dwordx4 v[228:229], v[52:55], off offset:512
	global_store_dwordx2 v[28:29], v[198:199], off
	v_pk_add_f32 v[30:31], v[196:197], v[62:63]
	v_pk_add_f32 v[28:29], v[194:195], v[60:61]
	v_mul_f32_e32 v42, v31, v31
	v_mul_f32_e32 v41, v29, v29
	v_fmac_f32_e32 v41, v28, v28
	v_fmac_f32_e32 v42, v30, v30
	v_add_f32_e32 v41, v41, v42
	v_add_f32_e32 v41, v40, v41
	ds_bpermute_b32 v42, v227, v41
	global_store_dwordx4 v[228:229], v[28:31], off offset:576
	v_or_b32_e32 v230, 0x120, v230
	s_nop 0
	v_pk_mul_f32 v[28:29], v[0:1], v[28:29]
	v_pk_mul_f32 v[30:31], v[2:3], v[30:31]
	v_cvt_pk_bf16_f32 v40, v28, v29
	s_waitcnt lgkmcnt(0)
	v_add_f32_e32 v28, v41, v42
	ds_bpermute_b32 v29, v226, v28
	v_cvt_pk_bf16_f32 v41, v30, v31
	v_lshl_add_u64 v[30:31], s[12:13], 0, v[230:231]
	global_store_dwordx2 v[30:31], v[40:41], off
	s_and_saveexec_b64 s[24:25], s[2:3]
	s_cbranch_execz .LBB0_1062
	v_lshl_add_u64 v[30:31], v[64:65], 2, s[14:15]
	s_waitcnt lgkmcnt(0)
	v_add_f32_e32 v28, v28, v29
	v_add_f32_e32 v28, 0x48400000, v28
	v_add_f32_e32 v28, 0xc8400000, v28
	global_atomic_add_f32 v[30:31], v28, off
.LBB0_1062:
	s_or_b64 exec, exec, s[24:25]
	v_or_b32_e32 v194, 48, v64
	v_ashrrev_i32_e32 v195, 31, v194
	v_readlane_b32 s60, v252, 16
	s_waitcnt lgkmcnt(0)
	v_lshlrev_b64 v[28:29], 13, v[194:195]
	v_readlane_b32 s74, v252, 30
	v_readlane_b32 s75, v252, 31
	v_pk_add_f32 v[58:59], v[192:193], v[58:59]
	v_pk_add_f32 v[56:57], v[190:191], v[56:57]
	v_lshl_add_u64 v[28:29], s[74:75], 0, v[28:29]
	v_lshl_add_u64 v[196:197], v[144:145], 2, v[28:29]
	global_load_dwordx4 v[60:63], v[196:197], off
	global_load_dwordx4 v[52:55], v[196:197], off offset:64
	global_load_dwordx4 v[40:43], v[196:197], off offset:512
	global_load_dwordx4 v[28:31], v[196:197], off offset:576
	v_lshlrev_b64 v[198:199], 11, v[66:67]
	v_mul_f32_e32 v65, v57, v57
	v_mul_f32_e32 v190, v59, v59
	v_lshl_add_u64 v[198:199], v[198:199], 0, v[144:145]
	global_store_dwordx4 v[216:217], v[56:59], off
	v_fmac_f32_e32 v65, v56, v56
	v_fmac_f32_e32 v190, v58, v58
	v_pk_mul_f32 v[58:59], v[14:15], v[58:59]
	v_pk_mul_f32 v[56:57], v[12:13], v[56:57]
	v_add_f32_e32 v65, v65, v190
	v_cvt_pk_bf16_f32 v56, v56, v57
	v_cvt_pk_bf16_f32 v57, v58, v59
	v_lshlrev_b64 v[58:59], 1, v[198:199]
	v_lshl_add_u64 v[190:191], s[12:13], 0, v[58:59]
	v_pk_add_f32 v[50:51], v[188:189], v[50:51]
	v_pk_add_f32 v[48:49], v[186:187], v[48:49]
	global_store_dwordx2 v[190:191], v[56:57], off
	v_mul_f32_e32 v56, v49, v49
	v_mul_f32_e32 v57, v51, v51
	global_store_dwordx4 v[216:217], v[48:51], off offset:64
	v_fmac_f32_e32 v56, v48, v48
	v_fmac_f32_e32 v57, v50, v50
	v_pk_mul_f32 v[50:51], v[10:11], v[50:51]
	v_pk_mul_f32 v[48:49], v[8:9], v[48:49]
	v_pk_add_f32 v[38:39], v[184:185], v[38:39]
	v_cvt_pk_bf16_f32 v48, v48, v49
	v_cvt_pk_bf16_f32 v49, v50, v51
	v_or_b32_e32 v50, 32, v58
	v_mov_b32_e32 v51, v59
	v_lshl_add_u64 v[50:51], s[12:13], 0, v[50:51]
	v_pk_add_f32 v[36:37], v[182:183], v[36:37]
	global_store_dwordx2 v[50:51], v[48:49], off
	v_mul_f32_e32 v48, v37, v37
	v_mul_f32_e32 v49, v39, v39
	global_store_dwordx4 v[216:217], v[36:39], off offset:512
	v_fmac_f32_e32 v48, v36, v36
	v_fmac_f32_e32 v49, v38, v38
	v_pk_mul_f32 v[38:39], v[6:7], v[38:39]
	v_pk_mul_f32 v[36:37], v[4:5], v[36:37]
	v_pk_add_f32 v[26:27], v[180:181], v[26:27]
	v_cvt_pk_bf16_f32 v36, v36, v37
	v_cvt_pk_bf16_f32 v37, v38, v39
	v_or_b32_e32 v38, 0x100, v58
	v_mov_b32_e32 v39, v59
	v_lshl_add_u64 v[38:39], s[12:13], 0, v[38:39]
	v_pk_add_f32 v[24:25], v[178:179], v[24:25]
	v_add_f32_e32 v56, v56, v57
	global_store_dwordx2 v[38:39], v[36:37], off
	v_mul_f32_e32 v36, v25, v25
	v_mul_f32_e32 v37, v27, v27
	v_add_f32_e32 v56, v65, v56
	v_add_f32_e32 v48, v48, v49
	v_fmac_f32_e32 v36, v24, v24
	v_fmac_f32_e32 v37, v26, v26
	v_add_f32_e32 v48, v56, v48
	v_add_f32_e32 v36, v36, v37
	v_add_f32_e32 v37, v48, v36
	ds_bpermute_b32 v38, v227, v37
	global_store_dwordx4 v[216:217], v[24:27], off offset:576
	v_or_b32_e32 v58, 0x120, v58
	v_readlane_b32 s61, v252, 17
	v_pk_mul_f32 v[24:25], v[0:1], v[24:25]
	v_pk_mul_f32 v[26:27], v[2:3], v[26:27]
	v_cvt_pk_bf16_f32 v36, v24, v25
	s_waitcnt lgkmcnt(0)
	v_add_f32_e32 v24, v37, v38
	ds_bpermute_b32 v25, v226, v24
	v_cvt_pk_bf16_f32 v37, v26, v27
	v_lshl_add_u64 v[26:27], s[12:13], 0, v[58:59]
	v_readlane_b32 s62, v252, 18
	v_readlane_b32 s63, v252, 19
	v_readlane_b32 s64, v252, 20
	v_readlane_b32 s65, v252, 21
	v_readlane_b32 s66, v252, 22
	v_readlane_b32 s67, v252, 23
	v_readlane_b32 s68, v252, 24
	v_readlane_b32 s69, v252, 25
	v_readlane_b32 s70, v252, 26
	v_readlane_b32 s71, v252, 27
	v_readlane_b32 s72, v252, 28
	v_readlane_b32 s73, v252, 29
	global_store_dwordx2 v[26:27], v[36:37], off
	s_and_saveexec_b64 s[24:25], s[2:3]
	s_cbranch_execz .LBB0_1064
	v_lshl_add_u64 v[26:27], v[66:67], 2, s[14:15]
	s_waitcnt lgkmcnt(0)
	v_add_f32_e32 v24, v24, v25
	v_add_f32_e32 v24, 0x48400000, v24
	v_add_f32_e32 v24, 0xc8400000, v24
	global_atomic_add_f32 v[26:27], v24, off
.LBB0_1064:
	s_or_b64 exec, exec, s[24:25]
	v_add_u32_e32 v178, 0x80, v64
	v_ashrrev_i32_e32 v179, 31, v178
	v_readlane_b32 s60, v252, 16
	s_waitcnt lgkmcnt(0)
	v_lshlrev_b64 v[24:25], 13, v[178:179]
	v_readlane_b32 s74, v252, 30
	v_readlane_b32 s75, v252, 31
	v_pk_add_f32 v[46:47], v[176:177], v[46:47]
	v_pk_add_f32 v[44:45], v[174:175], v[44:45]
	v_lshl_add_u64 v[24:25], s[74:75], 0, v[24:25]
	v_lshl_add_u64 v[180:181], v[144:145], 2, v[24:25]
	global_load_dwordx4 v[64:67], v[180:181], off
	global_load_dwordx4 v[48:51], v[180:181], off offset:64
	global_load_dwordx4 v[36:39], v[180:181], off offset:512
	global_load_dwordx4 v[24:27], v[180:181], off offset:576
	v_lshlrev_b64 v[56:57], 11, v[212:213]
	v_mul_f32_e32 v58, v45, v45
	v_mul_f32_e32 v59, v47, v47
	v_lshl_add_u64 v[56:57], v[56:57], 0, v[144:145]
	global_store_dwordx4 v[214:215], v[44:47], off
	v_fmac_f32_e32 v58, v44, v44
	v_fmac_f32_e32 v59, v46, v46
	v_pk_mul_f32 v[46:47], v[14:15], v[46:47]
	v_pk_mul_f32 v[44:45], v[12:13], v[44:45]
	v_pk_add_f32 v[34:35], v[172:173], v[34:35]
	v_cvt_pk_bf16_f32 v44, v44, v45
	v_cvt_pk_bf16_f32 v45, v46, v47
	v_lshlrev_b64 v[46:47], 1, v[56:57]
	v_lshl_add_u64 v[56:57], s[12:13], 0, v[46:47]
	v_pk_add_f32 v[32:33], v[170:171], v[32:33]
	global_store_dwordx2 v[56:57], v[44:45], off
	v_mul_f32_e32 v44, v33, v33
	v_mul_f32_e32 v45, v35, v35
	global_store_dwordx4 v[214:215], v[32:35], off offset:64
	v_fmac_f32_e32 v44, v32, v32
	v_fmac_f32_e32 v45, v34, v34
	v_pk_mul_f32 v[34:35], v[10:11], v[34:35]
	v_pk_mul_f32 v[32:33], v[8:9], v[32:33]
	v_pk_add_f32 v[22:23], v[168:169], v[22:23]
	v_cvt_pk_bf16_f32 v32, v32, v33
	v_cvt_pk_bf16_f32 v33, v34, v35
	v_or_b32_e32 v34, 32, v46
	v_mov_b32_e32 v35, v47
	v_lshl_add_u64 v[34:35], s[12:13], 0, v[34:35]
	v_pk_add_f32 v[20:21], v[166:167], v[20:21]
	global_store_dwordx2 v[34:35], v[32:33], off
	v_mul_f32_e32 v32, v21, v21
	v_mul_f32_e32 v33, v23, v23
	global_store_dwordx4 v[214:215], v[20:23], off offset:512
	v_fmac_f32_e32 v32, v20, v20
	v_fmac_f32_e32 v33, v22, v22
	v_pk_mul_f32 v[22:23], v[6:7], v[22:23]
	v_pk_mul_f32 v[20:21], v[4:5], v[20:21]
	v_pk_add_f32 v[18:19], v[164:165], v[18:19]
	v_cvt_pk_bf16_f32 v20, v20, v21
	v_cvt_pk_bf16_f32 v21, v22, v23
	v_or_b32_e32 v22, 0x100, v46
	v_mov_b32_e32 v23, v47
	v_lshl_add_u64 v[22:23], s[12:13], 0, v[22:23]
	v_pk_add_f32 v[16:17], v[162:163], v[16:17]
	v_add_f32_e32 v58, v58, v59
	v_add_f32_e32 v44, v44, v45
	global_store_dwordx2 v[22:23], v[20:21], off
	v_mul_f32_e32 v20, v17, v17
	v_mul_f32_e32 v21, v19, v19
	v_add_f32_e32 v44, v58, v44
	v_add_f32_e32 v32, v32, v33
	v_fmac_f32_e32 v20, v16, v16
	v_fmac_f32_e32 v21, v18, v18
	v_add_f32_e32 v32, v44, v32
	v_add_f32_e32 v20, v20, v21
	v_add_f32_e32 v21, v32, v20
	ds_bpermute_b32 v22, v227, v21
	global_store_dwordx4 v[214:215], v[16:19], off offset:576
	v_or_b32_e32 v46, 0x120, v46
	v_readlane_b32 s61, v252, 17
	v_pk_mul_f32 v[16:17], v[0:1], v[16:17]
	v_pk_mul_f32 v[18:19], v[2:3], v[18:19]
	v_cvt_pk_bf16_f32 v20, v16, v17
	s_waitcnt lgkmcnt(0)
	v_add_f32_e32 v16, v21, v22
	ds_bpermute_b32 v17, v226, v16
	v_cvt_pk_bf16_f32 v21, v18, v19
	v_lshl_add_u64 v[18:19], s[12:13], 0, v[46:47]
	v_readlane_b32 s62, v252, 18
	v_readlane_b32 s63, v252, 19
	v_readlane_b32 s64, v252, 20
	v_readlane_b32 s65, v252, 21
	v_readlane_b32 s66, v252, 22
	v_readlane_b32 s67, v252, 23
	v_readlane_b32 s68, v252, 24
	v_readlane_b32 s69, v252, 25
	v_readlane_b32 s70, v252, 26
	v_readlane_b32 s71, v252, 27
	v_readlane_b32 s72, v252, 28
	v_readlane_b32 s73, v252, 29
	global_store_dwordx2 v[18:19], v[20:21], off
	s_and_saveexec_b64 s[24:25], s[2:3]
	s_cbranch_execz .LBB0_1066
	v_lshl_add_u64 v[18:19], v[212:213], 2, s[14:15]
	s_waitcnt lgkmcnt(0)
	v_add_f32_e32 v16, v16, v17
	v_add_f32_e32 v16, 0x48400000, v16
	v_add_f32_e32 v16, 0xc8400000, v16
	global_atomic_add_f32 v[18:19], v16, off
.LBB0_1066:
	s_or_b64 exec, exec, s[24:25]
	s_waitcnt lgkmcnt(0)
	v_lshl_add_u64 v[16:17], v[144:145], 2, v[210:211]
	v_lshl_add_u64 v[162:163], v[16:17], 0, s[20:21]
	v_add_co_u32_e32 v16, vcc, 0x120000, v16
	v_lshlrev_b64 v[20:21], 11, v[194:195]
	s_nop 0
	v_addc_co_u32_e32 v17, vcc, 0, v17, vcc
	global_load_dwordx4 v[44:47], v[162:163], off offset:64
	global_load_dwordx4 v[32:35], v[162:163], off offset:512
	global_load_dwordx4 v[56:59], v[16:17], off
	s_nop 0
	global_load_dwordx4 v[16:19], v[162:163], off offset:576
	v_lshl_add_u64 v[164:165], v[20:21], 0, v[144:145]
	s_waitcnt vmcnt(27)
	v_pk_add_f32 v[22:23], v[160:161], v[62:63]
	v_pk_add_f32 v[20:21], v[158:159], v[60:61]
	v_mul_f32_e32 v61, v23, v23
	v_mul_f32_e32 v60, v21, v21
	v_fmac_f32_e32 v60, v20, v20
	v_fmac_f32_e32 v61, v22, v22
	global_store_dwordx4 v[196:197], v[20:23], off
	v_add_f32_e32 v62, v60, v61
	v_lshlrev_b64 v[60:61], 1, v[164:165]
	v_pk_mul_f32 v[22:23], v[14:15], v[22:23]
	v_pk_mul_f32 v[20:21], v[12:13], v[20:21]
	s_nop 0
	v_cvt_pk_bf16_f32 v20, v20, v21
	v_cvt_pk_bf16_f32 v21, v22, v23
	v_lshl_add_u64 v[22:23], s[12:13], 0, v[60:61]
	global_store_dwordx2 v[22:23], v[20:21], off
	s_waitcnt vmcnt(28)
	v_pk_add_f32 v[22:23], v[156:157], v[54:55]
	v_pk_add_f32 v[20:21], v[154:155], v[52:53]
	v_mul_f32_e32 v53, v23, v23
	v_mul_f32_e32 v52, v21, v21
	global_store_dwordx4 v[196:197], v[20:23], off offset:64
	v_fmac_f32_e32 v52, v20, v20
	v_fmac_f32_e32 v53, v22, v22
	v_pk_mul_f32 v[22:23], v[10:11], v[22:23]
	v_pk_mul_f32 v[20:21], v[8:9], v[20:21]
	v_add_f32_e32 v52, v52, v53
	v_cvt_pk_bf16_f32 v20, v20, v21
	v_cvt_pk_bf16_f32 v21, v22, v23
	v_or_b32_e32 v22, 32, v60
	v_mov_b32_e32 v23, v61
	v_lshl_add_u64 v[22:23], s[12:13], 0, v[22:23]
	global_store_dwordx2 v[22:23], v[20:21], off
	s_waitcnt vmcnt(29)
	v_pk_add_f32 v[22:23], v[152:153], v[42:43]
	v_pk_add_f32 v[20:21], v[150:151], v[40:41]
	v_mul_f32_e32 v41, v23, v23
	v_mul_f32_e32 v40, v21, v21
	global_store_dwordx4 v[196:197], v[20:23], off offset:512
	v_fmac_f32_e32 v40, v20, v20
	v_fmac_f32_e32 v41, v22, v22
	v_pk_mul_f32 v[22:23], v[6:7], v[22:23]
	v_pk_mul_f32 v[20:21], v[4:5], v[20:21]
	v_add_f32_e32 v52, v62, v52
	v_cvt_pk_bf16_f32 v20, v20, v21
	v_cvt_pk_bf16_f32 v21, v22, v23
	v_or_b32_e32 v22, 0x100, v60
	v_mov_b32_e32 v23, v61
	v_lshl_add_u64 v[22:23], s[12:13], 0, v[22:23]
	global_store_dwordx2 v[22:23], v[20:21], off
	s_waitcnt vmcnt(30)
	v_pk_add_f32 v[22:23], v[148:149], v[30:31]
	v_pk_add_f32 v[20:21], v[146:147], v[28:29]
	v_mul_f32_e32 v29, v23, v23
	v_mul_f32_e32 v28, v21, v21
	v_add_f32_e32 v40, v40, v41
	v_fmac_f32_e32 v28, v20, v20
	v_fmac_f32_e32 v29, v22, v22
	v_add_f32_e32 v40, v52, v40
	v_add_f32_e32 v28, v28, v29
	v_add_f32_e32 v29, v40, v28
	ds_bpermute_b32 v30, v227, v29
	global_store_dwordx4 v[196:197], v[20:23], off offset:576
	v_or_b32_e32 v60, 0x120, v60
	s_nop 0
	v_pk_mul_f32 v[20:21], v[0:1], v[20:21]
	v_pk_mul_f32 v[22:23], v[2:3], v[22:23]
	v_cvt_pk_bf16_f32 v28, v20, v21
	s_waitcnt lgkmcnt(0)
	v_add_f32_e32 v20, v29, v30
	ds_bpermute_b32 v21, v226, v20
	v_cvt_pk_bf16_f32 v29, v22, v23
	v_lshl_add_u64 v[22:23], s[12:13], 0, v[60:61]
	global_store_dwordx2 v[22:23], v[28:29], off
	s_and_saveexec_b64 s[24:25], s[2:3]
	s_cbranch_execz .LBB0_1068
	v_lshl_add_u64 v[22:23], v[194:195], 2, s[14:15]
	s_waitcnt lgkmcnt(0)
	v_add_f32_e32 v20, v20, v21
	v_add_f32_e32 v20, 0x48400000, v20
	v_add_f32_e32 v20, 0xc8400000, v20
	global_atomic_add_f32 v[22:23], v20, off
.LBB0_1068:
	s_or_b64 exec, exec, s[24:25]
	v_or_b32_e32 v146, 32, v178
	v_ashrrev_i32_e32 v147, 31, v146
	v_readlane_b32 s60, v252, 16
	s_waitcnt lgkmcnt(0)
	v_lshlrev_b64 v[20:21], 13, v[146:147]
	v_readlane_b32 s74, v252, 30
	v_readlane_b32 s75, v252, 31
	v_lshlrev_b64 v[60:61], 11, v[178:179]
	v_lshl_add_u64 v[150:151], v[60:61], 0, v[144:145]
	v_lshl_add_u64 v[20:21], s[74:75], 0, v[20:21]
	v_lshl_add_u64 v[148:149], v[144:145], 2, v[20:21]
	global_load_dwordx4 v[52:55], v[148:149], off
	global_load_dwordx4 v[40:43], v[148:149], off offset:64
	global_load_dwordx4 v[28:31], v[148:149], off offset:512
	global_load_dwordx4 v[20:23], v[148:149], off offset:576
	s_waitcnt vmcnt(27)
	v_pk_add_f32 v[62:63], v[142:143], v[66:67]
	v_pk_add_f32 v[60:61], v[140:141], v[64:65]
	v_mul_f32_e32 v65, v63, v63
	v_mul_f32_e32 v64, v61, v61
	global_store_dwordx4 v[180:181], v[60:63], off
	v_fmac_f32_e32 v64, v60, v60
	v_fmac_f32_e32 v65, v62, v62
	v_pk_mul_f32 v[62:63], v[14:15], v[62:63]
	v_pk_mul_f32 v[60:61], v[12:13], v[60:61]
	v_add_f32_e32 v66, v64, v65
	v_cvt_pk_bf16_f32 v60, v60, v61
	v_cvt_pk_bf16_f32 v61, v62, v63
	v_lshlrev_b64 v[62:63], 1, v[150:151]
	v_lshl_add_u64 v[64:65], s[12:13], 0, v[62:63]
	s_waitcnt vmcnt(27)
	v_pk_add_f32 v[50:51], v[126:127], v[50:51]
	v_pk_add_f32 v[48:49], v[124:125], v[48:49]
	global_store_dwordx2 v[64:65], v[60:61], off
	v_mul_f32_e32 v60, v49, v49
	v_mul_f32_e32 v61, v51, v51
	global_store_dwordx4 v[180:181], v[48:51], off offset:64
	v_fmac_f32_e32 v60, v48, v48
	v_fmac_f32_e32 v61, v50, v50
	v_pk_mul_f32 v[50:51], v[10:11], v[50:51]
	v_pk_mul_f32 v[48:49], v[8:9], v[48:49]
	s_waitcnt vmcnt(28)
	v_pk_add_f32 v[38:39], v[122:123], v[38:39]
	v_cvt_pk_bf16_f32 v48, v48, v49
	v_cvt_pk_bf16_f32 v49, v50, v51
	v_or_b32_e32 v50, 32, v62
	v_mov_b32_e32 v51, v63
	v_lshl_add_u64 v[50:51], s[12:13], 0, v[50:51]
	v_pk_add_f32 v[36:37], v[120:121], v[36:37]
	global_store_dwordx2 v[50:51], v[48:49], off
	v_mul_f32_e32 v48, v37, v37
	v_mul_f32_e32 v49, v39, v39
	global_store_dwordx4 v[180:181], v[36:39], off offset:512
	v_fmac_f32_e32 v48, v36, v36
	v_fmac_f32_e32 v49, v38, v38
	v_pk_mul_f32 v[38:39], v[6:7], v[38:39]
	v_pk_mul_f32 v[36:37], v[4:5], v[36:37]
	s_waitcnt vmcnt(29)
	v_pk_add_f32 v[26:27], v[118:119], v[26:27]
	v_cvt_pk_bf16_f32 v36, v36, v37
	v_cvt_pk_bf16_f32 v37, v38, v39
	v_or_b32_e32 v38, 0x100, v62
	v_mov_b32_e32 v39, v63
	v_lshl_add_u64 v[38:39], s[12:13], 0, v[38:39]
	v_pk_add_f32 v[24:25], v[116:117], v[24:25]
	v_add_f32_e32 v60, v60, v61
	global_store_dwordx2 v[38:39], v[36:37], off
	v_mul_f32_e32 v36, v25, v25
	v_mul_f32_e32 v37, v27, v27
	v_add_f32_e32 v60, v66, v60
	v_add_f32_e32 v48, v48, v49
	v_fmac_f32_e32 v36, v24, v24
	v_fmac_f32_e32 v37, v26, v26
	v_add_f32_e32 v48, v60, v48
	v_add_f32_e32 v36, v36, v37
	v_add_f32_e32 v37, v48, v36
	ds_bpermute_b32 v38, v227, v37
	global_store_dwordx4 v[180:181], v[24:27], off offset:576
	v_or_b32_e32 v62, 0x120, v62
	v_readlane_b32 s61, v252, 17
	v_pk_mul_f32 v[24:25], v[0:1], v[24:25]
	v_pk_mul_f32 v[26:27], v[2:3], v[26:27]
	v_cvt_pk_bf16_f32 v36, v24, v25
	s_waitcnt lgkmcnt(0)
	v_add_f32_e32 v24, v37, v38
	ds_bpermute_b32 v25, v226, v24
	v_cvt_pk_bf16_f32 v37, v26, v27
	v_lshl_add_u64 v[26:27], s[12:13], 0, v[62:63]
	v_readlane_b32 s62, v252, 18
	v_readlane_b32 s63, v252, 19
	v_readlane_b32 s64, v252, 20
	v_readlane_b32 s65, v252, 21
	v_readlane_b32 s66, v252, 22
	v_readlane_b32 s67, v252, 23
	v_readlane_b32 s68, v252, 24
	v_readlane_b32 s69, v252, 25
	v_readlane_b32 s70, v252, 26
	v_readlane_b32 s71, v252, 27
	v_readlane_b32 s72, v252, 28
	v_readlane_b32 s73, v252, 29
	global_store_dwordx2 v[26:27], v[36:37], off
	s_and_saveexec_b64 s[24:25], s[2:3]
	s_cbranch_execz .LBB0_1070
	v_lshl_add_u64 v[26:27], v[178:179], 2, s[14:15]
	s_waitcnt lgkmcnt(0)
	v_add_f32_e32 v24, v24, v25
	v_add_f32_e32 v24, 0x48400000, v24
	v_add_f32_e32 v24, 0xc8400000, v24
	global_atomic_add_f32 v[26:27], v24, off
.LBB0_1070:
	s_or_b64 exec, exec, s[24:25]
	v_or_b32_e32 v64, 48, v178
	v_ashrrev_i32_e32 v65, 31, v64
	v_readlane_b32 s60, v252, 16
	s_waitcnt lgkmcnt(0)
	v_lshlrev_b64 v[24:25], 13, v[64:65]
	v_readlane_b32 s74, v252, 30
	v_readlane_b32 s75, v252, 31
	v_or_b32_e32 v116, 16, v178
	v_ashrrev_i32_e32 v117, 31, v116
	v_lshl_add_u64 v[24:25], s[74:75], 0, v[24:25]
	v_lshl_add_u64 v[66:67], v[144:145], 2, v[24:25]
	global_load_dwordx4 v[60:63], v[66:67], off
	global_load_dwordx4 v[48:51], v[66:67], off offset:64
	global_load_dwordx4 v[36:39], v[66:67], off offset:512
	global_load_dwordx4 v[24:27], v[66:67], off offset:576
	s_waitcnt vmcnt(25)
	v_pk_add_f32 v[58:59], v[114:115], v[58:59]
	v_pk_add_f32 v[56:57], v[112:113], v[56:57]
	v_lshlrev_b64 v[118:119], 11, v[116:117]
	v_mul_f32_e32 v112, v57, v57
	v_mul_f32_e32 v113, v59, v59
	v_lshl_add_u64 v[118:119], v[118:119], 0, v[144:145]
	global_store_dwordx4 v[162:163], v[56:59], off
	v_fmac_f32_e32 v112, v56, v56
	v_fmac_f32_e32 v113, v58, v58
	v_pk_mul_f32 v[58:59], v[14:15], v[58:59]
	v_pk_mul_f32 v[56:57], v[12:13], v[56:57]
	v_add_f32_e32 v114, v112, v113
	v_cvt_pk_bf16_f32 v56, v56, v57
	v_cvt_pk_bf16_f32 v57, v58, v59
	v_lshlrev_b64 v[58:59], 1, v[118:119]
	v_lshl_add_u64 v[112:113], s[12:13], 0, v[58:59]
	v_pk_add_f32 v[46:47], v[110:111], v[46:47]
	v_pk_add_f32 v[44:45], v[108:109], v[44:45]
	global_store_dwordx2 v[112:113], v[56:57], off
	v_mul_f32_e32 v56, v45, v45
	v_mul_f32_e32 v57, v47, v47
	global_store_dwordx4 v[162:163], v[44:47], off offset:64
	v_fmac_f32_e32 v56, v44, v44
	v_fmac_f32_e32 v57, v46, v46
	v_pk_mul_f32 v[46:47], v[10:11], v[46:47]
	v_pk_mul_f32 v[44:45], v[8:9], v[44:45]
	v_pk_add_f32 v[34:35], v[106:107], v[34:35]
	v_cvt_pk_bf16_f32 v44, v44, v45
	v_cvt_pk_bf16_f32 v45, v46, v47
	v_or_b32_e32 v46, 32, v58
	v_mov_b32_e32 v47, v59
	v_lshl_add_u64 v[46:47], s[12:13], 0, v[46:47]
	v_pk_add_f32 v[32:33], v[104:105], v[32:33]
	global_store_dwordx2 v[46:47], v[44:45], off
	v_mul_f32_e32 v44, v33, v33
	v_mul_f32_e32 v45, v35, v35
	global_store_dwordx4 v[162:163], v[32:35], off offset:512
	v_fmac_f32_e32 v44, v32, v32
	v_fmac_f32_e32 v45, v34, v34
	v_pk_mul_f32 v[34:35], v[6:7], v[34:35]
	v_pk_mul_f32 v[32:33], v[4:5], v[32:33]
	s_waitcnt vmcnt(29)
	v_pk_add_f32 v[18:19], v[102:103], v[18:19]
	v_cvt_pk_bf16_f32 v32, v32, v33
	v_cvt_pk_bf16_f32 v33, v34, v35
	v_or_b32_e32 v34, 0x100, v58
	v_mov_b32_e32 v35, v59
	v_lshl_add_u64 v[34:35], s[12:13], 0, v[34:35]
	v_pk_add_f32 v[16:17], v[100:101], v[16:17]
	v_add_f32_e32 v56, v56, v57
	global_store_dwordx2 v[34:35], v[32:33], off
	v_mul_f32_e32 v32, v17, v17
	v_mul_f32_e32 v33, v19, v19
	v_add_f32_e32 v56, v114, v56
	v_add_f32_e32 v44, v44, v45
	v_fmac_f32_e32 v32, v16, v16
	v_fmac_f32_e32 v33, v18, v18
	v_add_f32_e32 v44, v56, v44
	v_add_f32_e32 v32, v32, v33
	v_add_f32_e32 v33, v44, v32
	ds_bpermute_b32 v34, v227, v33
	global_store_dwordx4 v[162:163], v[16:19], off offset:576
	v_or_b32_e32 v58, 0x120, v58
	v_readlane_b32 s61, v252, 17
	v_pk_mul_f32 v[16:17], v[0:1], v[16:17]
	v_pk_mul_f32 v[18:19], v[2:3], v[18:19]
	v_cvt_pk_bf16_f32 v32, v16, v17
	s_waitcnt lgkmcnt(0)
	v_add_f32_e32 v16, v33, v34
	ds_bpermute_b32 v17, v226, v16
	v_cvt_pk_bf16_f32 v33, v18, v19
	v_lshl_add_u64 v[18:19], s[12:13], 0, v[58:59]
	v_readlane_b32 s62, v252, 18
	v_readlane_b32 s63, v252, 19
	v_readlane_b32 s64, v252, 20
	v_readlane_b32 s65, v252, 21
	v_readlane_b32 s66, v252, 22
	v_readlane_b32 s67, v252, 23
	v_readlane_b32 s68, v252, 24
	v_readlane_b32 s69, v252, 25
	v_readlane_b32 s70, v252, 26
	v_readlane_b32 s71, v252, 27
	v_readlane_b32 s72, v252, 28
	v_readlane_b32 s73, v252, 29
	global_store_dwordx2 v[18:19], v[32:33], off
	s_and_saveexec_b64 s[24:25], s[2:3]
	s_cbranch_execz .LBB0_1072
	v_lshl_add_u64 v[18:19], v[116:117], 2, s[14:15]
	s_waitcnt lgkmcnt(0)
	v_add_f32_e32 v16, v16, v17
	v_add_f32_e32 v16, 0x48400000, v16
	v_add_f32_e32 v16, 0xc8400000, v16
	global_atomic_add_f32 v[18:19], v16, off
.LBB0_1072:
	s_or_b64 exec, exec, s[24:25]
	s_waitcnt lgkmcnt(0)
	v_lshlrev_b64 v[16:17], 11, v[146:147]
	v_lshl_add_u64 v[32:33], v[16:17], 0, v[144:145]
	s_waitcnt vmcnt(23)
	v_pk_add_f32 v[18:19], v[98:99], v[54:55]
	v_pk_add_f32 v[16:17], v[96:97], v[52:53]
	v_mul_f32_e32 v35, v19, v19
	v_mul_f32_e32 v34, v17, v17
	global_store_dwordx4 v[148:149], v[16:19], off
	v_fmac_f32_e32 v34, v16, v16
	v_fmac_f32_e32 v35, v18, v18
	v_pk_mul_f32 v[18:19], v[14:15], v[18:19]
	v_pk_mul_f32 v[16:17], v[12:13], v[16:17]
	v_lshlrev_b64 v[32:33], 1, v[32:33]
	v_cvt_pk_bf16_f32 v16, v16, v17
	v_cvt_pk_bf16_f32 v17, v18, v19
	v_lshl_add_u64 v[18:19], s[12:13], 0, v[32:33]
	global_store_dwordx2 v[18:19], v[16:17], off
	s_waitcnt vmcnt(24)
	v_pk_add_f32 v[18:19], v[94:95], v[42:43]
	v_pk_add_f32 v[16:17], v[92:93], v[40:41]
	v_add_f32_e32 v34, v34, v35
	v_mul_f32_e32 v35, v17, v17
	v_mul_f32_e32 v40, v19, v19
	global_store_dwordx4 v[148:149], v[16:19], off offset:64
	v_fmac_f32_e32 v35, v16, v16
	v_fmac_f32_e32 v40, v18, v18
	v_pk_mul_f32 v[18:19], v[10:11], v[18:19]
	v_pk_mul_f32 v[16:17], v[8:9], v[16:17]
	v_add_f32_e32 v35, v35, v40
	v_cvt_pk_bf16_f32 v16, v16, v17
	v_cvt_pk_bf16_f32 v17, v18, v19
	v_or_b32_e32 v18, 32, v32
	v_mov_b32_e32 v19, v33
	v_lshl_add_u64 v[18:19], s[12:13], 0, v[18:19]
	global_store_dwordx2 v[18:19], v[16:17], off
	s_waitcnt vmcnt(25)
	v_pk_add_f32 v[18:19], v[90:91], v[30:31]
	v_pk_add_f32 v[16:17], v[88:89], v[28:29]
	v_mul_f32_e32 v29, v19, v19
	v_mul_f32_e32 v28, v17, v17
	global_store_dwordx4 v[148:149], v[16:19], off offset:512
	v_fmac_f32_e32 v28, v16, v16
	v_fmac_f32_e32 v29, v18, v18
	v_pk_mul_f32 v[18:19], v[6:7], v[18:19]
	v_pk_mul_f32 v[16:17], v[4:5], v[16:17]
	v_add_f32_e32 v34, v34, v35
	v_cvt_pk_bf16_f32 v16, v16, v17
	v_cvt_pk_bf16_f32 v17, v18, v19
	v_or_b32_e32 v18, 0x100, v32
	v_mov_b32_e32 v19, v33
	v_lshl_add_u64 v[18:19], s[12:13], 0, v[18:19]
	global_store_dwordx2 v[18:19], v[16:17], off
	s_waitcnt vmcnt(26)
	v_pk_add_f32 v[18:19], v[86:87], v[22:23]
	v_pk_add_f32 v[16:17], v[84:85], v[20:21]
	v_mul_f32_e32 v21, v19, v19
	v_mul_f32_e32 v20, v17, v17
	v_add_f32_e32 v28, v28, v29
	v_fmac_f32_e32 v20, v16, v16
	v_fmac_f32_e32 v21, v18, v18
	v_add_f32_e32 v28, v34, v28
	v_add_f32_e32 v20, v20, v21
	v_add_f32_e32 v21, v28, v20
	ds_bpermute_b32 v22, v227, v21
	global_store_dwordx4 v[148:149], v[16:19], off offset:576
	v_or_b32_e32 v32, 0x120, v32
	s_nop 0
	v_pk_mul_f32 v[16:17], v[0:1], v[16:17]
	v_pk_mul_f32 v[18:19], v[2:3], v[18:19]
	v_cvt_pk_bf16_f32 v20, v16, v17
	s_waitcnt lgkmcnt(0)
	v_add_f32_e32 v16, v21, v22
	ds_bpermute_b32 v17, v226, v16
	v_cvt_pk_bf16_f32 v21, v18, v19
	v_lshl_add_u64 v[18:19], s[12:13], 0, v[32:33]
	global_store_dwordx2 v[18:19], v[20:21], off
	s_and_saveexec_b64 s[24:25], s[2:3]
	s_cbranch_execz .LBB0_1074
	v_lshl_add_u64 v[18:19], v[146:147], 2, s[14:15]
	s_waitcnt lgkmcnt(0)
	v_add_f32_e32 v16, v16, v17
	v_add_f32_e32 v16, 0x48400000, v16
	v_add_f32_e32 v16, 0xc8400000, v16
	global_atomic_add_f32 v[18:19], v16, off
.LBB0_1074:
	s_or_b64 exec, exec, s[24:25]
	s_waitcnt lgkmcnt(0)
	v_lshlrev_b64 v[16:17], 11, v[64:65]
	v_lshl_add_u64 v[20:21], v[16:17], 0, v[144:145]
	s_waitcnt vmcnt(19)
	v_pk_add_f32 v[16:17], v[80:81], v[60:61]
	v_pk_add_f32 v[18:19], v[82:83], v[62:63]
	v_mul_f32_e32 v22, v17, v17
	global_store_dwordx4 v[66:67], v[16:19], off
	v_fmac_f32_e32 v22, v16, v16
	v_pk_mul_f32 v[14:15], v[14:15], v[18:19]
	v_pk_mul_f32 v[12:13], v[12:13], v[16:17]
	v_lshlrev_b64 v[16:17], 1, v[20:21]
	v_cvt_pk_bf16_f32 v12, v12, v13
	v_cvt_pk_bf16_f32 v13, v14, v15
	v_lshl_add_u64 v[14:15], s[12:13], 0, v[16:17]
	global_store_dwordx2 v[14:15], v[12:13], off
	s_waitcnt vmcnt(20)
	v_pk_add_f32 v[14:15], v[78:79], v[50:51]
	v_pk_add_f32 v[12:13], v[76:77], v[48:49]
	v_pk_mul_f32 v[10:11], v[10:11], v[14:15]
	v_pk_mul_f32 v[8:9], v[8:9], v[12:13]
	global_store_dwordx4 v[66:67], v[12:15], off offset:64
	v_cvt_pk_bf16_f32 v8, v8, v9
	v_cvt_pk_bf16_f32 v9, v10, v11
	v_or_b32_e32 v10, 32, v16
	v_mov_b32_e32 v11, v17
	v_lshl_add_u64 v[10:11], s[12:13], 0, v[10:11]
	global_store_dwordx2 v[10:11], v[8:9], off
	s_waitcnt vmcnt(21)
	v_pk_add_f32 v[10:11], v[74:75], v[38:39]
	v_pk_add_f32 v[8:9], v[72:73], v[36:37]
	v_pk_mul_f32 v[6:7], v[6:7], v[10:11]
	v_pk_mul_f32 v[4:5], v[4:5], v[8:9]
	v_mul_f32_e32 v23, v19, v19
	v_cvt_pk_bf16_f32 v4, v4, v5
	v_cvt_pk_bf16_f32 v5, v6, v7
	v_or_b32_e32 v6, 0x100, v16
	v_mov_b32_e32 v7, v17
	v_fmac_f32_e32 v23, v18, v18
	v_mul_f32_e32 v18, v13, v13
	v_mul_f32_e32 v19, v15, v15
	v_lshl_add_u64 v[6:7], s[12:13], 0, v[6:7]
	v_fmac_f32_e32 v18, v12, v12
	v_fmac_f32_e32 v19, v14, v14
	global_store_dwordx4 v[66:67], v[8:11], off offset:512
	v_mul_f32_e32 v12, v9, v9
	v_mul_f32_e32 v13, v11, v11
	global_store_dwordx2 v[6:7], v[4:5], off
	s_waitcnt vmcnt(22)
	v_pk_add_f32 v[6:7], v[70:71], v[26:27]
	v_pk_add_f32 v[4:5], v[68:69], v[24:25]
	v_add_f32_e32 v22, v22, v23
	v_add_f32_e32 v18, v18, v19
	v_fmac_f32_e32 v12, v8, v8
	v_fmac_f32_e32 v13, v10, v10
	v_mul_f32_e32 v8, v5, v5
	v_mul_f32_e32 v9, v7, v7
	v_add_f32_e32 v18, v22, v18
	v_add_f32_e32 v12, v12, v13
	v_fmac_f32_e32 v8, v4, v4
	v_fmac_f32_e32 v9, v6, v6
	v_add_f32_e32 v12, v18, v12
	v_add_f32_e32 v8, v8, v9
	v_add_f32_e32 v8, v12, v8
	ds_bpermute_b32 v9, v227, v8
	v_pk_mul_f32 v[0:1], v[0:1], v[4:5]
	global_store_dwordx4 v[66:67], v[4:7], off offset:576
	v_pk_mul_f32 v[2:3], v[2:3], v[6:7]
	v_or_b32_e32 v16, 0x120, v16
	v_cvt_pk_bf16_f32 v4, v0, v1
	s_waitcnt lgkmcnt(0)
	v_add_f32_e32 v0, v8, v9
	ds_bpermute_b32 v1, v226, v0
	v_cvt_pk_bf16_f32 v5, v2, v3
	v_lshl_add_u64 v[2:3], s[12:13], 0, v[16:17]
	global_store_dwordx2 v[2:3], v[4:5], off
	s_and_saveexec_b64 s[24:25], s[2:3]
	s_cbranch_execz .LBB0_1076
	v_lshl_add_u64 v[2:3], v[64:65], 2, s[14:15]
	s_waitcnt lgkmcnt(0)
	v_add_f32_e32 v0, v0, v1
	v_add_f32_e32 v0, 0x48400000, v0
	v_add_f32_e32 v0, 0xc8400000, v0
	global_atomic_add_f32 v[2:3], v0, off

.LBB0_1162:
	v_lshl_add_u32 v166, s33, 8, v202
	v_ashrrev_i32_e32 v167, 31, v166
	v_lshl_add_u64 v[128:129], v[166:167], 2, s[16:17]
	global_load_dword v189, v[128:129], off
	v_lshl_or_b32 v170, s40, 8, v204
	v_ashrrev_i32_e32 v171, 31, v170
	v_lshlrev_b64 v[130:131], 11, v[166:167]
	v_lshl_add_u64 v[130:131], v[130:131], 0, v[170:171]
	v_lshlrev_b64 v[132:133], 1, v[130:131]
	v_lshl_add_u64 v[134:135], s[14:15], 0, v[132:133]
	v_readlane_b32 s68, v252, 16
	global_load_dwordx2 v[192:193], v[134:135], off
	v_and_b32_e32 v135, 64, v208
	v_readlane_b32 s69, v252, 17
	v_readlane_b32 s70, v252, 18
	v_readlane_b32 s71, v252, 19
	v_readlane_b32 s80, v252, 28
	v_readlane_b32 s81, v252, 29
	v_xor_b32_e32 v134, 16, v208
	v_or_b32_e32 v164, 16, v166
	v_or_b32_e32 v162, 32, v166
	v_or_b32_e32 v160, 48, v166
	v_add_u32_e32 v199, 64, v135
	v_readlane_b32 s82, v252, 30
	v_readlane_b32 s83, v252, 31
	s_mov_b64 s[68:69], s[80:81]
	v_ashrrev_i32_e32 v165, 31, v164
	v_ashrrev_i32_e32 v163, 31, v162
	v_ashrrev_i32_e32 v161, 31, v160
	v_cmp_lt_i32_e32 vcc, v134, v199
	s_mov_b64 s[70:71], s[82:83]
	v_lshl_add_u64 v[136:137], v[162:163], 2, s[16:17]
	v_cndmask_b32_e32 v140, v208, v134, vcc
	v_lshl_add_u64 v[134:135], v[164:165], 2, s[16:17]
	v_lshl_add_u64 v[138:139], v[160:161], 2, s[16:17]
	global_load_dword v216, v[128:129], off offset:512
	global_load_dword v215, v[128:129], off offset:576
	global_load_dword v214, v[128:129], off offset:640
	global_load_dword v188, v[134:135], off
	global_load_dword v198, v[136:137], off
	global_load_dword v217, v[138:139], off
	global_load_dword v212, v[128:129], off offset:704
	v_lshl_add_u64 v[128:129], v[130:131], 2, s[70:71]
	global_load_dwordx4 v[172:175], v[128:129], off
	global_load_dwordx4 v[176:179], v[128:129], off offset:64
	v_lshlrev_b32_e32 v211, 2, v140
	v_lshlrev_b64 v[140:141], 11, v[164:165]
	v_lshl_add_u64 v[130:131], v[140:141], 0, v[170:171]
	v_or_b32_e32 v134, 32, v132
	v_mov_b32_e32 v135, v133
	v_or_b32_e32 v136, 0x100, v132
	v_mov_b32_e32 v137, v133
	global_load_dwordx4 v[180:183], v[128:129], off offset:512
	global_load_dwordx4 v[144:147], v[128:129], off offset:576
	v_or_b32_e32 v132, 0x120, v132
	v_lshl_add_u64 v[128:129], v[130:131], 2, s[70:71]
	v_lshlrev_b64 v[168:169], 1, v[130:131]
	v_lshl_add_u64 v[184:185], s[14:15], 0, v[134:135]
	v_lshl_add_u64 v[186:187], s[14:15], 0, v[136:137]
	v_lshl_add_u64 v[190:191], s[14:15], 0, v[132:133]
	global_load_dwordx4 v[140:143], v[128:129], off
	global_load_dwordx4 v[136:139], v[128:129], off offset:64
	global_load_dwordx4 v[132:135], v[128:129], off offset:512
	s_nop 0
	global_load_dwordx4 v[128:131], v[128:129], off offset:576
	s_nop 0
	global_load_dwordx2 v[218:219], v[184:185], off
	global_load_dwordx2 v[220:221], v[186:187], off
	global_load_dwordx2 v[222:223], v[190:191], off
	v_or_b32_e32 v196, 32, v168
	v_mov_b32_e32 v197, v169
	v_lshl_add_u64 v[184:185], s[14:15], 0, v[196:197]
	v_lshl_add_u64 v[194:195], s[14:15], 0, v[168:169]
	v_or_b32_e32 v200, 0x100, v168
	v_mov_b32_e32 v201, v169
	v_or_b32_e32 v168, 0x120, v168
	v_lshl_add_u64 v[186:187], s[14:15], 0, v[200:201]
	v_lshl_add_u64 v[168:169], s[14:15], 0, v[168:169]
	v_readlane_b32 s72, v252, 20
	v_readlane_b32 s73, v252, 21
	v_readlane_b32 s74, v252, 22
	v_readlane_b32 s75, v252, 23
	v_readlane_b32 s76, v252, 24
	v_readlane_b32 s77, v252, 25
	v_readlane_b32 s78, v252, 26
	v_readlane_b32 s79, v252, 27
	s_waitcnt vmcnt(0)
	v_fmamk_f32 v189, v189, 0x3a000000, v209
	v_mul_f32_e32 v190, 0x4f800000, v189
	v_cmp_gt_f32_e32 vcc, s62, v189
	s_nop 1
	v_cndmask_b32_e32 v189, v189, v190, vcc
	v_sqrt_f32_e32 v196, v189
	global_load_dwordx2 v[194:195], v[194:195], off
	s_nop 0
	global_load_dwordx2 v[190:191], v[184:185], off
	s_nop 0
	global_load_dwordx2 v[186:187], v[186:187], off
	s_nop 0
	global_load_dwordx2 v[184:185], v[168:169], off
	v_add_u32_e32 v168, -1, v196
	v_add_u32_e32 v169, 1, v196
	v_fma_f32 v197, -v168, v196, v189
	v_fma_f32 v200, -v169, v196, v189
	v_cmp_ge_f32_e64 s[0:1], 0, v197
	s_nop 1
	v_cndmask_b32_e64 v168, v196, v168, s[0:1]
	v_cmp_lt_f32_e64 s[0:1], 0, v200
	s_nop 1
	v_cndmask_b32_e64 v168, v168, v169, s[0:1]
	v_mul_f32_e32 v169, 0x37800000, v168
	v_cndmask_b32_e32 v168, v168, v169, vcc
	v_cmp_class_f32_e32 vcc, v189, v210
	s_nop 1
	v_cndmask_b32_e32 v169, v168, v189, vcc
	v_div_scale_f32 v189, s[0:1], v169, v169, 1.0
	v_rcp_f32_e32 v196, v189
	v_div_scale_f32 v197, vcc, 1.0, v169, 1.0
	v_lshlrev_b32_e32 v168, 16, v192
	v_fma_f32 v200, -v189, v196, 1.0
	v_fmac_f32_e32 v196, v200, v196
	v_mul_f32_e32 v200, v197, v196
	v_fma_f32 v201, -v189, v200, v197
	v_fmac_f32_e32 v200, v201, v196
	v_fma_f32 v189, -v189, v200, v197
	v_div_fmas_f32 v189, v189, v196, v200
	v_div_fixup_f32 v189, v189, v169, 1.0
	v_mul_f32_e32 v124, v124, v189
	v_mul_f32_e32 v125, v125, v189
	v_mul_f32_e32 v126, v126, v189
	v_mul_f32_e32 v127, v127, v189
	v_mul_f32_e32 v124, 0xbfb8aa3b, v124
	v_mul_f32_e32 v125, 0xbfb8aa3b, v125
	v_mul_f32_e32 v126, 0xbfb8aa3b, v126
	v_mul_f32_e32 v127, 0xbfb8aa3b, v127
	v_exp_f32_e32 v124, v124
	v_exp_f32_e32 v125, v125
	v_exp_f32_e32 v126, v126
	v_exp_f32_e32 v127, v127
	v_add_f32_e32 v124, 1.0, v124
	v_add_f32_e32 v125, 1.0, v125
	v_rcp_f32_e32 v124, v124
	v_rcp_f32_e32 v125, v125
	v_add_f32_e32 v126, 1.0, v126
	v_add_f32_e32 v127, 1.0, v127
	v_rcp_f32_e32 v126, v126
	v_rcp_f32_e32 v127, v127
	v_and_b32_e32 v169, 0xffff0000, v192
	v_mul_f32_e32 v120, v120, v189
	v_pk_fma_f32 v[168:169], v[124:125], v[168:169], v[172:173]
	v_lshlrev_b32_e32 v124, 16, v193
	v_and_b32_e32 v125, 0xffff0000, v193
	v_mul_f32_e32 v120, 0xbfb8aa3b, v120
	v_pk_fma_f32 v[172:173], v[126:127], v[124:125], v[174:175]
	v_exp_f32_e32 v126, v120
	v_mul_f32_e32 v120, v121, v189
	v_mul_f32_e32 v120, 0xbfb8aa3b, v120
	v_mul_f32_e32 v122, v122, v189
	v_mul_f32_e32 v123, v123, v189
	v_exp_f32_e32 v127, v120
	v_mul_f32_e32 v122, 0xbfb8aa3b, v122
	v_mul_f32_e32 v123, 0xbfb8aa3b, v123
	v_exp_f32_e32 v122, v122
	v_exp_f32_e32 v123, v123
	v_add_f32_e32 v126, 1.0, v126
	v_add_f32_e32 v127, 1.0, v127
	v_rcp_f32_e32 v126, v126
	v_rcp_f32_e32 v127, v127
	v_add_f32_e32 v122, 1.0, v122
	v_add_f32_e32 v123, 1.0, v123
	v_rcp_f32_e32 v122, v122
	v_rcp_f32_e32 v123, v123
	v_lshlrev_b32_e32 v174, 16, v218
	v_and_b32_e32 v175, 0xffff0000, v218
	v_mul_f32_e32 v116, v116, v189
	v_pk_fma_f32 v[174:175], v[126:127], v[174:175], v[176:177]
	v_lshlrev_b32_e32 v126, 16, v219
	v_and_b32_e32 v127, 0xffff0000, v219
	v_mul_f32_e32 v116, 0xbfb8aa3b, v116
	v_pk_fma_f32 v[176:177], v[122:123], v[126:127], v[178:179]
	v_exp_f32_e32 v126, v116
	v_mul_f32_e32 v116, v117, v189
	v_mul_f32_e32 v116, 0xbfb8aa3b, v116
	v_mul_f32_e32 v118, v118, v189
	v_mul_f32_e32 v119, v119, v189
	v_exp_f32_e32 v127, v116
	v_mul_f32_e32 v118, 0xbfb8aa3b, v118
	v_mul_f32_e32 v119, 0xbfb8aa3b, v119
	v_exp_f32_e32 v118, v118
	v_exp_f32_e32 v119, v119
	v_add_f32_e32 v126, 1.0, v126
	v_add_f32_e32 v127, 1.0, v127
	v_rcp_f32_e32 v126, v126
	v_rcp_f32_e32 v127, v127
	v_add_f32_e32 v118, 1.0, v118
	v_add_f32_e32 v119, 1.0, v119
	v_rcp_f32_e32 v118, v118
	v_rcp_f32_e32 v119, v119
	v_lshlrev_b32_e32 v178, 16, v220
	v_and_b32_e32 v179, 0xffff0000, v220
	v_mul_f32_e32 v112, v112, v189
	v_pk_fma_f32 v[178:179], v[126:127], v[178:179], v[180:181]
	v_lshlrev_b32_e32 v126, 16, v221
	v_and_b32_e32 v127, 0xffff0000, v221
	v_mul_f32_e32 v112, 0xbfb8aa3b, v112
	v_pk_fma_f32 v[180:181], v[118:119], v[126:127], v[182:183]
	v_exp_f32_e32 v126, v112
	v_mul_f32_e32 v112, v113, v189
	v_mul_f32_e32 v112, 0xbfb8aa3b, v112
	v_mul_f32_e32 v114, v114, v189
	v_mul_f32_e32 v115, v115, v189
	v_exp_f32_e32 v127, v112
	v_mul_f32_e32 v114, 0xbfb8aa3b, v114
	v_mul_f32_e32 v115, 0xbfb8aa3b, v115
	v_exp_f32_e32 v114, v114
	v_exp_f32_e32 v115, v115
	v_add_f32_e32 v126, 1.0, v126
	v_add_f32_e32 v127, 1.0, v127
	v_rcp_f32_e32 v126, v126
	v_rcp_f32_e32 v127, v127
	v_add_f32_e32 v114, 1.0, v114
	v_add_f32_e32 v115, 1.0, v115
	v_rcp_f32_e32 v114, v114
	v_rcp_f32_e32 v115, v115
	v_pk_mul_f32 v[122:123], v[174:175], v[174:175]
	v_pk_mul_f32 v[116:117], v[176:177], v[176:177]
	v_lshlrev_b32_e32 v182, 16, v222
	v_and_b32_e32 v183, 0xffff0000, v222
	v_pk_mul_f32 v[124:125], v[168:169], v[168:169]
	v_pk_mul_f32 v[120:121], v[172:173], v[172:173]
	v_pk_fma_f32 v[144:145], v[126:127], v[182:183], v[144:145]
	v_lshlrev_b32_e32 v126, 16, v223
	v_and_b32_e32 v127, 0xffff0000, v223
	v_add_f32_e32 v116, v116, v117
	v_add_f32_e32 v117, v122, v123
	v_pk_mul_f32 v[118:119], v[178:179], v[178:179]
	v_pk_mul_f32 v[112:113], v[180:181], v[180:181]
	v_pk_fma_f32 v[146:147], v[114:115], v[126:127], v[146:147]
	v_add_f32_e32 v116, v117, v116
	v_add_f32_e32 v117, v120, v121
	v_add_f32_e32 v120, v124, v125
	v_pk_mul_f32 v[114:115], v[144:145], v[144:145]
	v_pk_mul_f32 v[126:127], v[146:147], v[146:147]
	v_add_f32_e32 v117, v120, v117
	v_add_f32_e32 v112, v112, v113
	v_add_f32_e32 v113, v118, v119
	v_add_f32_e32 v116, v117, v116
	v_add_f32_e32 v112, v113, v112
	v_add_f32_e32 v113, v126, v127
	v_add_f32_e32 v114, v114, v115
	v_add_f32_e32 v112, v116, v112
	v_add_f32_e32 v113, v114, v113
	v_add_f32_e32 v112, v112, v113
	ds_bpermute_b32 v113, v211, v112
	v_xor_b32_e32 v114, 32, v208
	v_cmp_lt_i32_e32 vcc, v114, v199
	v_lshl_add_u64 v[182:183], v[166:167], 2, s[18:19]
	s_waitcnt lgkmcnt(0)
	v_add_f32_e32 v112, v112, v113
	v_cndmask_b32_e32 v114, v208, v114, vcc
	v_lshlrev_b32_e32 v213, 2, v114
	ds_bpermute_b32 v113, v213, v112
	s_and_saveexec_b64 s[0:1], s[2:3]
	s_cbranch_execz .LBB0_1164
	s_waitcnt lgkmcnt(0)
	v_add_f32_e32 v112, v112, v113
	v_add_f32_e32 v112, 0x48400000, v112
	v_add_f32_e32 v112, 0xc8400000, v112
	global_atomic_add_f32 v[182:183], v112, off
.LBB0_1164:
	s_or_b64 exec, exec, s[0:1]
	s_waitcnt lgkmcnt(0)
	v_lshlrev_b64 v[112:113], 11, v[162:163]
	v_lshl_add_u64 v[112:113], v[112:113], 0, v[170:171]
	v_readlane_b32 s68, v252, 16
	v_readlane_b32 s82, v252, 30
	v_readlane_b32 s83, v252, 31
	v_lshlrev_b64 v[192:193], 1, v[112:113]
	v_lshl_add_u64 v[196:197], s[14:15], 0, v[192:193]
	v_lshl_add_u64 v[114:115], v[112:113], 2, s[82:83]
	v_or_b32_e32 v112, 32, v192
	v_mov_b32_e32 v113, v193
	v_lshl_add_u64 v[218:219], s[14:15], 0, v[112:113]
	v_fmamk_f32 v112, v188, 0x3a000000, v209
	v_mul_f32_e32 v113, 0x4f800000, v112
	v_cmp_gt_f32_e32 vcc, s62, v112
	global_load_dwordx4 v[124:127], v[114:115], off
	global_load_dwordx4 v[120:123], v[114:115], off offset:64
	v_cndmask_b32_e32 v116, v112, v113, vcc
	v_sqrt_f32_e32 v117, v116
	v_or_b32_e32 v112, 0x100, v192
	v_mov_b32_e32 v113, v193
	v_lshl_add_u64 v[188:189], s[14:15], 0, v[112:113]
	v_add_u32_e32 v112, -1, v117
	v_fma_f32 v113, -v112, v117, v116
	v_cmp_ge_f32_e64 s[0:1], 0, v113
	v_add_u32_e32 v113, 1, v117
	v_or_b32_e32 v192, 0x120, v192
	v_cndmask_b32_e64 v112, v117, v112, s[0:1]
	v_fma_f32 v117, -v113, v117, v116
	v_cmp_lt_f32_e64 s[0:1], 0, v117
	v_lshl_add_u64 v[220:221], s[14:15], 0, v[192:193]
	v_readlane_b32 s69, v252, 17
	v_cndmask_b32_e64 v112, v112, v113, s[0:1]
	v_mul_f32_e32 v113, 0x37800000, v112
	v_cndmask_b32_e32 v112, v112, v113, vcc
	v_cmp_class_f32_e32 vcc, v116, v210
	v_readlane_b32 s70, v252, 18
	v_readlane_b32 s71, v252, 19
	v_cndmask_b32_e32 v199, v112, v116, vcc
	v_div_scale_f32 v200, s[0:1], v199, v199, 1.0
	v_rcp_f32_e32 v201, v200
	global_load_dwordx4 v[116:119], v[114:115], off offset:512
	s_nop 0
	global_load_dwordx4 v[112:115], v[114:115], off offset:576
	v_readlane_b32 s72, v252, 20
	v_readlane_b32 s73, v252, 21
	v_fma_f32 v192, -v200, v201, 1.0
	v_fmac_f32_e32 v201, v192, v201
	v_div_scale_f32 v192, vcc, 1.0, v199, 1.0
	v_mul_f32_e32 v193, v192, v201
	v_fma_f32 v222, -v200, v193, v192
	v_fmac_f32_e32 v193, v222, v201
	v_fma_f32 v192, -v200, v193, v192
	v_div_fmas_f32 v192, v192, v201, v193
	v_div_fixup_f32 v199, v192, v199, 1.0
	global_load_dwordx2 v[200:201], v[196:197], off
	s_nop 0
	global_load_dwordx2 v[196:197], v[218:219], off
	global_load_dwordx2 v[192:193], v[188:189], off
	s_nop 0
	global_load_dwordx2 v[188:189], v[220:221], off
	v_mul_f32_e32 v108, v108, v199
	v_mul_f32_e32 v109, v109, v199
	v_mul_f32_e32 v108, 0xbfb8aa3b, v108
	v_mul_f32_e32 v109, 0xbfb8aa3b, v109
	v_mul_f32_e32 v110, v110, v199
	v_mul_f32_e32 v111, v111, v199
	v_exp_f32_e32 v108, v108
	v_exp_f32_e32 v109, v109
	v_mul_f32_e32 v110, 0xbfb8aa3b, v110
	v_mul_f32_e32 v111, 0xbfb8aa3b, v111
	v_exp_f32_e32 v110, v110
	v_exp_f32_e32 v111, v111
	v_add_f32_e32 v108, 1.0, v108
	v_add_f32_e32 v109, 1.0, v109
	v_rcp_f32_e32 v108, v108
	v_rcp_f32_e32 v109, v109
	v_add_f32_e32 v110, 1.0, v110
	v_add_f32_e32 v111, 1.0, v111
	v_rcp_f32_e32 v110, v110
	v_rcp_f32_e32 v111, v111
	s_waitcnt vmcnt(11)
	v_lshlrev_b32_e32 v218, 16, v194
	v_and_b32_e32 v219, 0xffff0000, v194
	v_mul_f32_e32 v104, v104, v199
	v_pk_fma_f32 v[140:141], v[108:109], v[218:219], v[140:141]
	v_lshlrev_b32_e32 v108, 16, v195
	v_and_b32_e32 v109, 0xffff0000, v195
	v_mul_f32_e32 v104, 0xbfb8aa3b, v104
	v_pk_fma_f32 v[142:143], v[110:111], v[108:109], v[142:143]
	v_exp_f32_e32 v110, v104
	v_mul_f32_e32 v104, v105, v199
	v_mul_f32_e32 v104, 0xbfb8aa3b, v104
	v_mul_f32_e32 v106, v106, v199
	v_mul_f32_e32 v107, v107, v199
	v_exp_f32_e32 v111, v104
	v_mul_f32_e32 v106, 0xbfb8aa3b, v106
	v_mul_f32_e32 v107, 0xbfb8aa3b, v107
	v_exp_f32_e32 v106, v106
	v_exp_f32_e32 v107, v107
	v_add_f32_e32 v110, 1.0, v110
	v_add_f32_e32 v111, 1.0, v111
	v_rcp_f32_e32 v110, v110
	v_rcp_f32_e32 v111, v111
	v_add_f32_e32 v106, 1.0, v106
	v_add_f32_e32 v107, 1.0, v107
	v_rcp_f32_e32 v106, v106
	v_rcp_f32_e32 v107, v107
	s_waitcnt vmcnt(10)
	v_lshlrev_b32_e32 v194, 16, v190
	v_and_b32_e32 v195, 0xffff0000, v190
	v_mul_f32_e32 v100, v100, v199
	v_pk_fma_f32 v[136:137], v[110:111], v[194:195], v[136:137]
	v_lshlrev_b32_e32 v110, 16, v191
	v_and_b32_e32 v111, 0xffff0000, v191
	v_mul_f32_e32 v100, 0xbfb8aa3b, v100
	v_pk_fma_f32 v[138:139], v[106:107], v[110:111], v[138:139]
	v_exp_f32_e32 v110, v100
	v_mul_f32_e32 v100, v101, v199
	v_mul_f32_e32 v100, 0xbfb8aa3b, v100
	v_mul_f32_e32 v102, v102, v199
	v_mul_f32_e32 v103, v103, v199
	v_exp_f32_e32 v111, v100
	v_mul_f32_e32 v102, 0xbfb8aa3b, v102
	v_mul_f32_e32 v103, 0xbfb8aa3b, v103
	v_exp_f32_e32 v102, v102
	v_exp_f32_e32 v103, v103
	v_add_f32_e32 v110, 1.0, v110
	v_add_f32_e32 v111, 1.0, v111
	v_rcp_f32_e32 v110, v110
	v_rcp_f32_e32 v111, v111
	v_add_f32_e32 v102, 1.0, v102
	v_add_f32_e32 v103, 1.0, v103
	v_rcp_f32_e32 v102, v102
	v_rcp_f32_e32 v103, v103
	s_waitcnt vmcnt(9)
	v_lshlrev_b32_e32 v190, 16, v186
	v_and_b32_e32 v191, 0xffff0000, v186
	v_mul_f32_e32 v96, v96, v199
	v_pk_fma_f32 v[132:133], v[110:111], v[190:191], v[132:133]
	v_lshlrev_b32_e32 v110, 16, v187
	v_and_b32_e32 v111, 0xffff0000, v187
	v_mul_f32_e32 v96, 0xbfb8aa3b, v96
	v_pk_fma_f32 v[134:135], v[102:103], v[110:111], v[134:135]
	v_exp_f32_e32 v110, v96
	v_mul_f32_e32 v96, v97, v199
	v_mul_f32_e32 v96, 0xbfb8aa3b, v96
	v_mul_f32_e32 v98, v98, v199
	v_mul_f32_e32 v99, v99, v199
	v_exp_f32_e32 v111, v96
	v_mul_f32_e32 v98, 0xbfb8aa3b, v98
	v_mul_f32_e32 v99, 0xbfb8aa3b, v99
	v_exp_f32_e32 v98, v98
	v_exp_f32_e32 v99, v99
	v_add_f32_e32 v110, 1.0, v110
	v_add_f32_e32 v111, 1.0, v111
	v_rcp_f32_e32 v110, v110
	v_rcp_f32_e32 v111, v111
	v_add_f32_e32 v98, 1.0, v98
	v_add_f32_e32 v99, 1.0, v99
	v_rcp_f32_e32 v98, v98
	v_rcp_f32_e32 v99, v99
	v_pk_mul_f32 v[106:107], v[136:137], v[136:137]
	v_pk_mul_f32 v[100:101], v[138:139], v[138:139]
	s_waitcnt vmcnt(8)
	v_lshlrev_b32_e32 v186, 16, v184
	v_and_b32_e32 v187, 0xffff0000, v184
	v_pk_mul_f32 v[108:109], v[140:141], v[140:141]
	v_pk_mul_f32 v[104:105], v[142:143], v[142:143]
	v_pk_fma_f32 v[128:129], v[110:111], v[186:187], v[128:129]
	v_lshlrev_b32_e32 v110, 16, v185
	v_and_b32_e32 v111, 0xffff0000, v185
	v_add_f32_e32 v100, v100, v101
	v_add_f32_e32 v101, v106, v107
	v_pk_mul_f32 v[102:103], v[132:133], v[132:133]
	v_pk_mul_f32 v[96:97], v[134:135], v[134:135]
	v_pk_fma_f32 v[130:131], v[98:99], v[110:111], v[130:131]
	v_add_f32_e32 v100, v101, v100
	v_add_f32_e32 v101, v104, v105
	v_add_f32_e32 v104, v108, v109
	v_pk_mul_f32 v[98:99], v[128:129], v[128:129]
	v_pk_mul_f32 v[110:111], v[130:131], v[130:131]
	v_add_f32_e32 v101, v104, v101
	v_add_f32_e32 v96, v96, v97
	v_add_f32_e32 v97, v102, v103
	v_add_f32_e32 v100, v101, v100
	v_add_f32_e32 v96, v97, v96
	v_add_f32_e32 v97, v110, v111
	v_add_f32_e32 v98, v98, v99
	v_add_f32_e32 v96, v100, v96
	v_add_f32_e32 v97, v98, v97
	v_add_f32_e32 v96, v96, v97
	ds_bpermute_b32 v97, v211, v96
	v_readlane_b32 s74, v252, 22
	v_readlane_b32 s75, v252, 23
	v_readlane_b32 s76, v252, 24
	v_readlane_b32 s77, v252, 25
	s_waitcnt lgkmcnt(0)
	v_add_f32_e32 v96, v96, v97
	ds_bpermute_b32 v97, v213, v96
	v_readlane_b32 s78, v252, 26
	v_readlane_b32 s79, v252, 27
	v_readlane_b32 s80, v252, 28
	v_readlane_b32 s81, v252, 29
	s_and_saveexec_b64 s[0:1], s[2:3]
	s_cbranch_execz .LBB0_1166
	s_waitcnt lgkmcnt(0)
	v_add_f32_e32 v96, v96, v97
	v_add_f32_e32 v96, 0x48400000, v96
	v_add_f32_e32 v96, 0xc8400000, v96
	global_atomic_add_f32 v[182:183], v96, off offset:64
.LBB0_1166:
	s_or_b64 exec, exec, s[0:1]
	s_waitcnt lgkmcnt(0)
	v_lshlrev_b64 v[96:97], 11, v[160:161]
	v_lshl_add_u64 v[96:97], v[96:97], 0, v[170:171]
	v_readlane_b32 s68, v252, 16
	v_readlane_b32 s82, v252, 30
	v_readlane_b32 s83, v252, 31
	v_lshlrev_b64 v[184:185], 1, v[96:97]
	v_lshl_add_u64 v[186:187], s[14:15], 0, v[184:185]
	v_lshl_add_u64 v[98:99], v[96:97], 2, s[82:83]
	v_or_b32_e32 v96, 32, v184
	v_mov_b32_e32 v97, v185
	v_lshl_add_u64 v[190:191], s[14:15], 0, v[96:97]
	v_fmamk_f32 v96, v198, 0x3a000000, v209
	v_mul_f32_e32 v97, 0x4f800000, v96
	v_cmp_gt_f32_e32 vcc, s62, v96
	global_load_dwordx4 v[108:111], v[98:99], off
	global_load_dwordx4 v[104:107], v[98:99], off offset:64
	v_cndmask_b32_e32 v100, v96, v97, vcc
	v_sqrt_f32_e32 v101, v100
	v_or_b32_e32 v96, 0x100, v184
	v_mov_b32_e32 v97, v185
	v_lshl_add_u64 v[218:219], s[14:15], 0, v[96:97]
	v_add_u32_e32 v96, -1, v101
	v_fma_f32 v97, -v96, v101, v100
	v_cmp_ge_f32_e64 s[0:1], 0, v97
	v_add_u32_e32 v97, 1, v101
	v_or_b32_e32 v184, 0x120, v184
	v_cndmask_b32_e64 v96, v101, v96, s[0:1]
	v_fma_f32 v101, -v97, v101, v100
	v_cmp_lt_f32_e64 s[0:1], 0, v101
	v_lshl_add_u64 v[184:185], s[14:15], 0, v[184:185]
	v_readlane_b32 s69, v252, 17
	v_cndmask_b32_e64 v96, v96, v97, s[0:1]
	v_mul_f32_e32 v97, 0x37800000, v96
	v_cndmask_b32_e32 v96, v96, v97, vcc
	v_cmp_class_f32_e32 vcc, v100, v210
	v_readlane_b32 s70, v252, 18
	v_readlane_b32 s71, v252, 19
	v_cndmask_b32_e32 v194, v96, v100, vcc
	v_div_scale_f32 v195, s[0:1], v194, v194, 1.0
	v_rcp_f32_e32 v198, v195
	global_load_dwordx4 v[100:103], v[98:99], off offset:512
	s_nop 0
	global_load_dwordx4 v[96:99], v[98:99], off offset:576
	v_readlane_b32 s72, v252, 20
	v_readlane_b32 s73, v252, 21
	v_fma_f32 v199, -v195, v198, 1.0
	v_fmac_f32_e32 v198, v199, v198
	v_div_scale_f32 v199, vcc, 1.0, v194, 1.0
	v_mul_f32_e32 v220, v199, v198
	v_fma_f32 v221, -v195, v220, v199
	v_fmac_f32_e32 v220, v221, v198
	v_fma_f32 v195, -v195, v220, v199
	v_div_fmas_f32 v195, v195, v198, v220
	v_div_fixup_f32 v220, v195, v194, 1.0
	global_load_dwordx2 v[198:199], v[186:187], off
	global_load_dwordx2 v[194:195], v[190:191], off
	s_nop 0
	global_load_dwordx2 v[190:191], v[218:219], off
	global_load_dwordx2 v[186:187], v[184:185], off
	v_mul_f32_e32 v92, v92, v220
	v_mul_f32_e32 v93, v93, v220
	v_mul_f32_e32 v92, 0xbfb8aa3b, v92
	v_mul_f32_e32 v93, 0xbfb8aa3b, v93
	v_mul_f32_e32 v94, v94, v220
	v_mul_f32_e32 v95, v95, v220
	v_exp_f32_e32 v92, v92
	v_exp_f32_e32 v93, v93
	v_mul_f32_e32 v94, 0xbfb8aa3b, v94
	v_mul_f32_e32 v95, 0xbfb8aa3b, v95
	v_exp_f32_e32 v94, v94
	v_exp_f32_e32 v95, v95
	v_add_f32_e32 v92, 1.0, v92
	v_add_f32_e32 v93, 1.0, v93
	v_rcp_f32_e32 v92, v92
	v_rcp_f32_e32 v93, v93
	v_add_f32_e32 v94, 1.0, v94
	v_add_f32_e32 v95, 1.0, v95
	v_rcp_f32_e32 v94, v94
	v_rcp_f32_e32 v95, v95
	s_waitcnt vmcnt(11)
	v_lshlrev_b32_e32 v184, 16, v200
	v_and_b32_e32 v185, 0xffff0000, v200
	v_mul_f32_e32 v88, v88, v220
	v_pk_fma_f32 v[124:125], v[92:93], v[184:185], v[124:125]
	v_lshlrev_b32_e32 v92, 16, v201
	v_and_b32_e32 v93, 0xffff0000, v201
	v_mul_f32_e32 v88, 0xbfb8aa3b, v88
	v_pk_fma_f32 v[126:127], v[94:95], v[92:93], v[126:127]
	v_exp_f32_e32 v94, v88
	v_mul_f32_e32 v88, v89, v220
	v_mul_f32_e32 v88, 0xbfb8aa3b, v88
	v_mul_f32_e32 v90, v90, v220
	v_mul_f32_e32 v91, v91, v220
	v_exp_f32_e32 v95, v88
	v_mul_f32_e32 v90, 0xbfb8aa3b, v90
	v_mul_f32_e32 v91, 0xbfb8aa3b, v91
	v_exp_f32_e32 v90, v90
	v_exp_f32_e32 v91, v91
	v_add_f32_e32 v94, 1.0, v94
	v_add_f32_e32 v95, 1.0, v95
	v_rcp_f32_e32 v94, v94
	v_rcp_f32_e32 v95, v95
	v_add_f32_e32 v90, 1.0, v90
	v_add_f32_e32 v91, 1.0, v91
	v_rcp_f32_e32 v90, v90
	v_rcp_f32_e32 v91, v91
	s_waitcnt vmcnt(10)
	v_lshlrev_b32_e32 v184, 16, v196
	v_and_b32_e32 v185, 0xffff0000, v196
	v_mul_f32_e32 v84, v84, v220
	v_pk_fma_f32 v[120:121], v[94:95], v[184:185], v[120:121]
	v_lshlrev_b32_e32 v94, 16, v197
	v_and_b32_e32 v95, 0xffff0000, v197
	v_mul_f32_e32 v84, 0xbfb8aa3b, v84
	v_pk_fma_f32 v[122:123], v[90:91], v[94:95], v[122:123]
	v_exp_f32_e32 v94, v84
	v_mul_f32_e32 v84, v85, v220
	v_mul_f32_e32 v84, 0xbfb8aa3b, v84
	v_mul_f32_e32 v86, v86, v220
	v_mul_f32_e32 v87, v87, v220
	v_exp_f32_e32 v95, v84
	v_mul_f32_e32 v86, 0xbfb8aa3b, v86
	v_mul_f32_e32 v87, 0xbfb8aa3b, v87
	v_exp_f32_e32 v86, v86
	v_exp_f32_e32 v87, v87
	v_add_f32_e32 v94, 1.0, v94
	v_add_f32_e32 v95, 1.0, v95
	v_rcp_f32_e32 v94, v94
	v_rcp_f32_e32 v95, v95
	v_add_f32_e32 v86, 1.0, v86
	v_add_f32_e32 v87, 1.0, v87
	v_rcp_f32_e32 v86, v86
	v_rcp_f32_e32 v87, v87
	s_waitcnt vmcnt(9)
	v_lshlrev_b32_e32 v184, 16, v192
	v_and_b32_e32 v185, 0xffff0000, v192
	v_mul_f32_e32 v80, v80, v220
	v_pk_fma_f32 v[116:117], v[94:95], v[184:185], v[116:117]
	v_lshlrev_b32_e32 v94, 16, v193
	v_and_b32_e32 v95, 0xffff0000, v193
	v_mul_f32_e32 v80, 0xbfb8aa3b, v80
	v_pk_fma_f32 v[118:119], v[86:87], v[94:95], v[118:119]
	v_exp_f32_e32 v94, v80
	v_mul_f32_e32 v80, v81, v220
	v_mul_f32_e32 v80, 0xbfb8aa3b, v80
	v_mul_f32_e32 v82, v82, v220
	v_mul_f32_e32 v83, v83, v220
	v_exp_f32_e32 v95, v80
	v_mul_f32_e32 v82, 0xbfb8aa3b, v82
	v_mul_f32_e32 v83, 0xbfb8aa3b, v83
	v_exp_f32_e32 v82, v82
	v_exp_f32_e32 v83, v83
	v_add_f32_e32 v94, 1.0, v94
	v_add_f32_e32 v95, 1.0, v95
	v_rcp_f32_e32 v94, v94
	v_rcp_f32_e32 v95, v95
	v_add_f32_e32 v82, 1.0, v82
	v_add_f32_e32 v83, 1.0, v83
	v_rcp_f32_e32 v82, v82
	v_rcp_f32_e32 v83, v83
	v_pk_mul_f32 v[90:91], v[120:121], v[120:121]
	v_pk_mul_f32 v[84:85], v[122:123], v[122:123]
	s_waitcnt vmcnt(8)
	v_lshlrev_b32_e32 v184, 16, v188
	v_and_b32_e32 v185, 0xffff0000, v188
	v_pk_mul_f32 v[92:93], v[124:125], v[124:125]
	v_pk_mul_f32 v[88:89], v[126:127], v[126:127]
	v_pk_fma_f32 v[184:185], v[94:95], v[184:185], v[112:113]
	v_lshlrev_b32_e32 v94, 16, v189
	v_and_b32_e32 v95, 0xffff0000, v189
	v_add_f32_e32 v84, v84, v85
	v_add_f32_e32 v85, v90, v91
	v_pk_mul_f32 v[86:87], v[116:117], v[116:117]
	v_pk_mul_f32 v[80:81], v[118:119], v[118:119]
	v_pk_fma_f32 v[114:115], v[82:83], v[94:95], v[114:115]
	v_add_f32_e32 v84, v85, v84
	v_add_f32_e32 v85, v88, v89
	v_add_f32_e32 v88, v92, v93
	v_pk_mul_f32 v[82:83], v[184:185], v[184:185]
	v_pk_mul_f32 v[94:95], v[114:115], v[114:115]
	v_add_f32_e32 v85, v88, v85
	v_add_f32_e32 v80, v80, v81
	v_add_f32_e32 v81, v86, v87
	v_add_f32_e32 v84, v85, v84
	v_add_f32_e32 v80, v81, v80
	v_add_f32_e32 v81, v94, v95
	v_add_f32_e32 v82, v82, v83
	v_add_f32_e32 v80, v84, v80
	v_add_f32_e32 v81, v82, v81
	v_add_f32_e32 v80, v80, v81
	ds_bpermute_b32 v81, v211, v80
	v_readlane_b32 s74, v252, 22
	v_readlane_b32 s75, v252, 23
	v_readlane_b32 s76, v252, 24
	v_readlane_b32 s77, v252, 25
	s_waitcnt lgkmcnt(0)
	v_add_f32_e32 v80, v80, v81
	ds_bpermute_b32 v81, v213, v80
	v_readlane_b32 s78, v252, 26
	v_readlane_b32 s79, v252, 27
	v_readlane_b32 s80, v252, 28
	v_readlane_b32 s81, v252, 29
	s_and_saveexec_b64 s[0:1], s[2:3]
	s_cbranch_execz .LBB0_1168
	s_waitcnt lgkmcnt(0)
	v_add_f32_e32 v80, v80, v81
	v_add_f32_e32 v80, 0x48400000, v80
	v_add_f32_e32 v80, 0xc8400000, v80
	global_atomic_add_f32 v[182:183], v80, off offset:128
.LBB0_1168:
	s_or_b64 exec, exec, s[0:1]
	v_add_u32_e32 v112, 0x80, v166
	v_ashrrev_i32_e32 v113, 31, v112
	s_waitcnt lgkmcnt(0)
	v_lshlrev_b64 v[80:81], 11, v[112:113]
	v_lshl_add_u64 v[80:81], v[80:81], 0, v[170:171]
	v_readlane_b32 s68, v252, 16
	v_readlane_b32 s82, v252, 30
	v_readlane_b32 s83, v252, 31
	v_lshlrev_b64 v[188:189], 1, v[80:81]
	v_lshl_add_u64 v[192:193], s[14:15], 0, v[188:189]
	v_lshl_add_u64 v[82:83], v[80:81], 2, s[82:83]
	v_or_b32_e32 v80, 32, v188
	v_mov_b32_e32 v81, v189
	v_lshl_add_u64 v[196:197], s[14:15], 0, v[80:81]
	v_fmamk_f32 v80, v217, 0x3a000000, v209
	v_mul_f32_e32 v81, 0x4f800000, v80
	v_cmp_gt_f32_e32 vcc, s62, v80
	global_load_dwordx4 v[92:95], v[82:83], off
	global_load_dwordx4 v[88:91], v[82:83], off offset:64
	v_cndmask_b32_e32 v84, v80, v81, vcc
	v_sqrt_f32_e32 v85, v84
	v_or_b32_e32 v80, 0x100, v188
	v_mov_b32_e32 v81, v189
	v_lshl_add_u64 v[218:219], s[14:15], 0, v[80:81]
	v_add_u32_e32 v80, -1, v85
	v_fma_f32 v81, -v80, v85, v84
	v_cmp_ge_f32_e64 s[0:1], 0, v81
	v_add_u32_e32 v81, 1, v85
	v_or_b32_e32 v188, 0x120, v188
	v_cndmask_b32_e64 v80, v85, v80, s[0:1]
	v_fma_f32 v85, -v81, v85, v84
	v_cmp_lt_f32_e64 s[0:1], 0, v85
	v_lshl_add_u64 v[188:189], s[14:15], 0, v[188:189]
	v_readlane_b32 s69, v252, 17
	v_cndmask_b32_e64 v80, v80, v81, s[0:1]
	v_mul_f32_e32 v81, 0x37800000, v80
	v_cndmask_b32_e32 v80, v80, v81, vcc
	v_cmp_class_f32_e32 vcc, v84, v210
	v_readlane_b32 s70, v252, 18
	v_readlane_b32 s71, v252, 19
	v_cndmask_b32_e32 v200, v80, v84, vcc
	v_div_scale_f32 v201, s[0:1], v200, v200, 1.0
	v_rcp_f32_e32 v217, v201
	global_load_dwordx4 v[84:87], v[82:83], off offset:512
	s_nop 0
	global_load_dwordx4 v[80:83], v[82:83], off offset:576
	v_readlane_b32 s72, v252, 20
	v_readlane_b32 s73, v252, 21
	v_fma_f32 v220, -v201, v217, 1.0
	v_fmac_f32_e32 v217, v220, v217
	v_div_scale_f32 v220, vcc, 1.0, v200, 1.0
	v_mul_f32_e32 v221, v220, v217
	v_fma_f32 v222, -v201, v221, v220
	v_fmac_f32_e32 v221, v222, v217
	v_fma_f32 v201, -v201, v221, v220
	v_div_fmas_f32 v201, v201, v217, v221
	v_div_fixup_f32 v217, v201, v200, 1.0
	global_load_dwordx2 v[200:201], v[192:193], off
	s_nop 0
	global_load_dwordx2 v[196:197], v[196:197], off
	s_nop 0
	global_load_dwordx2 v[192:193], v[218:219], off
	s_nop 0
	global_load_dwordx2 v[188:189], v[188:189], off
	v_mul_f32_e32 v76, v76, v217
	v_mul_f32_e32 v77, v77, v217
	v_mul_f32_e32 v76, 0xbfb8aa3b, v76
	v_mul_f32_e32 v77, 0xbfb8aa3b, v77
	v_mul_f32_e32 v78, v78, v217
	v_mul_f32_e32 v79, v79, v217
	v_exp_f32_e32 v76, v76
	v_exp_f32_e32 v77, v77
	v_mul_f32_e32 v78, 0xbfb8aa3b, v78
	v_mul_f32_e32 v79, 0xbfb8aa3b, v79
	v_exp_f32_e32 v78, v78
	v_exp_f32_e32 v79, v79
	v_add_f32_e32 v76, 1.0, v76
	v_add_f32_e32 v77, 1.0, v77
	v_rcp_f32_e32 v76, v76
	v_rcp_f32_e32 v77, v77
	v_add_f32_e32 v78, 1.0, v78
	v_add_f32_e32 v79, 1.0, v79
	v_rcp_f32_e32 v78, v78
	v_rcp_f32_e32 v79, v79
	s_waitcnt vmcnt(11)
	v_lshlrev_b32_e32 v218, 16, v198
	v_and_b32_e32 v219, 0xffff0000, v198
	v_mul_f32_e32 v72, v72, v217
	v_pk_fma_f32 v[108:109], v[76:77], v[218:219], v[108:109]
	v_lshlrev_b32_e32 v76, 16, v199
	v_and_b32_e32 v77, 0xffff0000, v199
	v_mul_f32_e32 v72, 0xbfb8aa3b, v72
	v_pk_fma_f32 v[110:111], v[78:79], v[76:77], v[110:111]
	v_exp_f32_e32 v78, v72
	v_mul_f32_e32 v72, v73, v217
	v_mul_f32_e32 v72, 0xbfb8aa3b, v72
	v_mul_f32_e32 v74, v74, v217
	v_mul_f32_e32 v75, v75, v217
	v_exp_f32_e32 v79, v72
	v_mul_f32_e32 v74, 0xbfb8aa3b, v74
	v_mul_f32_e32 v75, 0xbfb8aa3b, v75
	v_exp_f32_e32 v74, v74
	v_exp_f32_e32 v75, v75
	v_add_f32_e32 v78, 1.0, v78
	v_add_f32_e32 v79, 1.0, v79
	v_rcp_f32_e32 v78, v78
	v_rcp_f32_e32 v79, v79
	v_add_f32_e32 v74, 1.0, v74
	v_add_f32_e32 v75, 1.0, v75
	v_rcp_f32_e32 v74, v74
	v_rcp_f32_e32 v75, v75
	s_waitcnt vmcnt(10)
	v_lshlrev_b32_e32 v198, 16, v194
	v_and_b32_e32 v199, 0xffff0000, v194
	v_mul_f32_e32 v68, v68, v217
	v_pk_fma_f32 v[104:105], v[78:79], v[198:199], v[104:105]
	v_lshlrev_b32_e32 v78, 16, v195
	v_and_b32_e32 v79, 0xffff0000, v195
	v_mul_f32_e32 v68, 0xbfb8aa3b, v68
	v_pk_fma_f32 v[106:107], v[74:75], v[78:79], v[106:107]
	v_exp_f32_e32 v78, v68
	v_mul_f32_e32 v68, v69, v217
	v_mul_f32_e32 v68, 0xbfb8aa3b, v68
	v_mul_f32_e32 v70, v70, v217
	v_mul_f32_e32 v71, v71, v217
	v_exp_f32_e32 v79, v68
	v_mul_f32_e32 v70, 0xbfb8aa3b, v70
	v_mul_f32_e32 v71, 0xbfb8aa3b, v71
	v_exp_f32_e32 v70, v70
	v_exp_f32_e32 v71, v71
	v_add_f32_e32 v78, 1.0, v78
	v_add_f32_e32 v79, 1.0, v79
	v_rcp_f32_e32 v78, v78
	v_rcp_f32_e32 v79, v79
	v_add_f32_e32 v70, 1.0, v70
	v_add_f32_e32 v71, 1.0, v71
	v_rcp_f32_e32 v70, v70
	v_rcp_f32_e32 v71, v71
	s_waitcnt vmcnt(9)
	v_lshlrev_b32_e32 v194, 16, v190
	v_and_b32_e32 v195, 0xffff0000, v190
	v_mul_f32_e32 v64, v64, v217
	v_pk_fma_f32 v[100:101], v[78:79], v[194:195], v[100:101]
	v_lshlrev_b32_e32 v78, 16, v191
	v_and_b32_e32 v79, 0xffff0000, v191
	v_mul_f32_e32 v64, 0xbfb8aa3b, v64
	v_pk_fma_f32 v[102:103], v[70:71], v[78:79], v[102:103]
	v_exp_f32_e32 v78, v64
	v_mul_f32_e32 v64, v65, v217
	v_mul_f32_e32 v64, 0xbfb8aa3b, v64
	v_mul_f32_e32 v66, v66, v217
	v_mul_f32_e32 v67, v67, v217
	v_exp_f32_e32 v79, v64
	v_mul_f32_e32 v66, 0xbfb8aa3b, v66
	v_mul_f32_e32 v67, 0xbfb8aa3b, v67
	v_exp_f32_e32 v66, v66
	v_exp_f32_e32 v67, v67
	v_add_f32_e32 v78, 1.0, v78
	v_add_f32_e32 v79, 1.0, v79
	v_rcp_f32_e32 v78, v78
	v_rcp_f32_e32 v79, v79
	v_add_f32_e32 v66, 1.0, v66
	v_add_f32_e32 v67, 1.0, v67
	v_rcp_f32_e32 v66, v66
	v_rcp_f32_e32 v67, v67
	v_pk_mul_f32 v[74:75], v[104:105], v[104:105]
	v_pk_mul_f32 v[68:69], v[106:107], v[106:107]
	s_waitcnt vmcnt(8)
	v_lshlrev_b32_e32 v190, 16, v186
	v_and_b32_e32 v191, 0xffff0000, v186
	v_pk_mul_f32 v[76:77], v[108:109], v[108:109]
	v_pk_mul_f32 v[72:73], v[110:111], v[110:111]
	v_pk_fma_f32 v[96:97], v[78:79], v[190:191], v[96:97]
	v_lshlrev_b32_e32 v78, 16, v187
	v_and_b32_e32 v79, 0xffff0000, v187
	v_add_f32_e32 v68, v68, v69
	v_add_f32_e32 v69, v74, v75
	v_pk_mul_f32 v[70:71], v[100:101], v[100:101]
	v_pk_mul_f32 v[64:65], v[102:103], v[102:103]
	v_pk_fma_f32 v[98:99], v[66:67], v[78:79], v[98:99]
	v_add_f32_e32 v68, v69, v68
	v_add_f32_e32 v69, v72, v73
	v_add_f32_e32 v72, v76, v77
	v_pk_mul_f32 v[66:67], v[96:97], v[96:97]
	v_pk_mul_f32 v[78:79], v[98:99], v[98:99]
	v_add_f32_e32 v69, v72, v69
	v_add_f32_e32 v64, v64, v65
	v_add_f32_e32 v65, v70, v71
	v_add_f32_e32 v68, v69, v68
	v_add_f32_e32 v64, v65, v64
	v_add_f32_e32 v65, v78, v79
	v_add_f32_e32 v66, v66, v67
	v_add_f32_e32 v64, v68, v64
	v_add_f32_e32 v65, v66, v65
	v_add_f32_e32 v64, v64, v65
	ds_bpermute_b32 v65, v211, v64
	v_readlane_b32 s74, v252, 22
	v_readlane_b32 s75, v252, 23
	v_readlane_b32 s76, v252, 24
	v_readlane_b32 s77, v252, 25
	s_waitcnt lgkmcnt(0)
	v_add_f32_e32 v64, v64, v65
	ds_bpermute_b32 v65, v213, v64
	v_readlane_b32 s78, v252, 26
	v_readlane_b32 s79, v252, 27
	v_readlane_b32 s80, v252, 28
	v_readlane_b32 s81, v252, 29
	s_and_saveexec_b64 s[0:1], s[2:3]
	s_cbranch_execz .LBB0_1170
	s_waitcnt lgkmcnt(0)
	v_add_f32_e32 v64, v64, v65
	v_add_f32_e32 v64, 0x48400000, v64
	v_add_f32_e32 v64, 0xc8400000, v64
	global_atomic_add_f32 v[182:183], v64, off offset:192
.LBB0_1170:
	s_or_b64 exec, exec, s[0:1]
	v_or_b32_e32 v64, 16, v112
	s_waitcnt lgkmcnt(0)
	v_ashrrev_i32_e32 v65, 31, v64
	v_lshlrev_b64 v[64:65], 11, v[64:65]
	v_lshl_add_u64 v[64:65], v[64:65], 0, v[170:171]
	v_readlane_b32 s68, v252, 16
	v_readlane_b32 s82, v252, 30
	v_readlane_b32 s83, v252, 31
	v_lshlrev_b64 v[186:187], 1, v[64:65]
	v_lshl_add_u64 v[190:191], s[14:15], 0, v[186:187]
	v_lshl_add_u64 v[66:67], v[64:65], 2, s[82:83]
	v_or_b32_e32 v64, 32, v186
	v_mov_b32_e32 v65, v187
	v_lshl_add_u64 v[194:195], s[14:15], 0, v[64:65]
	v_fmamk_f32 v64, v216, 0x3a000000, v209
	v_mul_f32_e32 v65, 0x4f800000, v64
	v_cmp_gt_f32_e32 vcc, s62, v64
	global_load_dwordx4 v[76:79], v[66:67], off
	global_load_dwordx4 v[72:75], v[66:67], off offset:64
	v_cndmask_b32_e32 v68, v64, v65, vcc
	v_sqrt_f32_e32 v69, v68
	v_or_b32_e32 v64, 0x100, v186
	v_mov_b32_e32 v65, v187
	v_lshl_add_u64 v[216:217], s[14:15], 0, v[64:65]
	v_add_u32_e32 v64, -1, v69
	v_fma_f32 v65, -v64, v69, v68
	v_cmp_ge_f32_e64 s[0:1], 0, v65
	v_add_u32_e32 v65, 1, v69
	v_or_b32_e32 v186, 0x120, v186
	v_cndmask_b32_e64 v64, v69, v64, s[0:1]
	v_fma_f32 v69, -v65, v69, v68
	v_cmp_lt_f32_e64 s[0:1], 0, v69
	v_lshl_add_u64 v[186:187], s[14:15], 0, v[186:187]
	v_readlane_b32 s69, v252, 17
	v_cndmask_b32_e64 v64, v64, v65, s[0:1]
	v_mul_f32_e32 v65, 0x37800000, v64
	v_cndmask_b32_e32 v64, v64, v65, vcc
	v_cmp_class_f32_e32 vcc, v68, v210
	v_readlane_b32 s70, v252, 18
	v_readlane_b32 s71, v252, 19
	v_cndmask_b32_e32 v198, v64, v68, vcc
	v_div_scale_f32 v199, s[0:1], v198, v198, 1.0
	v_rcp_f32_e32 v218, v199
	global_load_dwordx4 v[68:71], v[66:67], off offset:512
	s_nop 0
	global_load_dwordx4 v[64:67], v[66:67], off offset:576
	v_readlane_b32 s72, v252, 20
	v_readlane_b32 s73, v252, 21
	v_fma_f32 v219, -v199, v218, 1.0
	v_fmac_f32_e32 v218, v219, v218
	v_div_scale_f32 v219, vcc, 1.0, v198, 1.0
	v_mul_f32_e32 v220, v219, v218
	v_fma_f32 v221, -v199, v220, v219
	v_fmac_f32_e32 v220, v221, v218
	v_fma_f32 v199, -v199, v220, v219
	v_div_fmas_f32 v199, v199, v218, v220
	v_div_fixup_f32 v218, v199, v198, 1.0
	global_load_dwordx2 v[198:199], v[190:191], off
	s_nop 0
	global_load_dwordx2 v[194:195], v[194:195], off
	s_nop 0
	global_load_dwordx2 v[190:191], v[216:217], off
	s_nop 0
	global_load_dwordx2 v[186:187], v[186:187], off
	v_mul_f32_e32 v60, v60, v218
	v_mul_f32_e32 v61, v61, v218
	v_mul_f32_e32 v60, 0xbfb8aa3b, v60
	v_mul_f32_e32 v61, 0xbfb8aa3b, v61
	v_mul_f32_e32 v62, v62, v218
	v_mul_f32_e32 v63, v63, v218
	v_exp_f32_e32 v60, v60
	v_exp_f32_e32 v61, v61
	v_mul_f32_e32 v62, 0xbfb8aa3b, v62
	v_mul_f32_e32 v63, 0xbfb8aa3b, v63
	v_exp_f32_e32 v62, v62
	v_exp_f32_e32 v63, v63
	v_add_f32_e32 v60, 1.0, v60
	v_add_f32_e32 v61, 1.0, v61
	v_rcp_f32_e32 v60, v60
	v_rcp_f32_e32 v61, v61
	v_add_f32_e32 v62, 1.0, v62
	v_add_f32_e32 v63, 1.0, v63
	v_rcp_f32_e32 v62, v62
	v_rcp_f32_e32 v63, v63
	s_waitcnt vmcnt(11)
	v_lshlrev_b32_e32 v216, 16, v200
	v_and_b32_e32 v217, 0xffff0000, v200
	v_mul_f32_e32 v56, v56, v218
	v_pk_fma_f32 v[92:93], v[60:61], v[216:217], v[92:93]
	v_lshlrev_b32_e32 v60, 16, v201
	v_and_b32_e32 v61, 0xffff0000, v201
	v_mul_f32_e32 v56, 0xbfb8aa3b, v56
	v_pk_fma_f32 v[94:95], v[62:63], v[60:61], v[94:95]
	v_exp_f32_e32 v62, v56
	v_mul_f32_e32 v56, v57, v218
	v_mul_f32_e32 v56, 0xbfb8aa3b, v56
	v_mul_f32_e32 v58, v58, v218
	v_mul_f32_e32 v59, v59, v218
	v_exp_f32_e32 v63, v56
	v_mul_f32_e32 v58, 0xbfb8aa3b, v58
	v_mul_f32_e32 v59, 0xbfb8aa3b, v59
	v_exp_f32_e32 v58, v58
	v_exp_f32_e32 v59, v59
	v_add_f32_e32 v62, 1.0, v62
	v_add_f32_e32 v63, 1.0, v63
	v_rcp_f32_e32 v62, v62
	v_rcp_f32_e32 v63, v63
	v_add_f32_e32 v58, 1.0, v58
	v_add_f32_e32 v59, 1.0, v59
	v_rcp_f32_e32 v58, v58
	v_rcp_f32_e32 v59, v59
	s_waitcnt vmcnt(10)
	v_lshlrev_b32_e32 v200, 16, v196
	v_and_b32_e32 v201, 0xffff0000, v196
	v_mul_f32_e32 v52, v52, v218
	v_pk_fma_f32 v[88:89], v[62:63], v[200:201], v[88:89]
	v_lshlrev_b32_e32 v62, 16, v197
	v_and_b32_e32 v63, 0xffff0000, v197
	v_mul_f32_e32 v52, 0xbfb8aa3b, v52
	v_pk_fma_f32 v[90:91], v[58:59], v[62:63], v[90:91]
	v_exp_f32_e32 v62, v52
	v_mul_f32_e32 v52, v53, v218
	v_mul_f32_e32 v52, 0xbfb8aa3b, v52
	v_mul_f32_e32 v54, v54, v218
	v_mul_f32_e32 v55, v55, v218
	v_exp_f32_e32 v63, v52
	v_mul_f32_e32 v54, 0xbfb8aa3b, v54
	v_mul_f32_e32 v55, 0xbfb8aa3b, v55
	v_exp_f32_e32 v54, v54
	v_exp_f32_e32 v55, v55
	v_add_f32_e32 v62, 1.0, v62
	v_add_f32_e32 v63, 1.0, v63
	v_rcp_f32_e32 v62, v62
	v_rcp_f32_e32 v63, v63
	v_add_f32_e32 v54, 1.0, v54
	v_add_f32_e32 v55, 1.0, v55
	v_rcp_f32_e32 v54, v54
	v_rcp_f32_e32 v55, v55
	s_waitcnt vmcnt(9)
	v_lshlrev_b32_e32 v196, 16, v192
	v_and_b32_e32 v197, 0xffff0000, v192
	v_mul_f32_e32 v48, v48, v218
	v_pk_fma_f32 v[84:85], v[62:63], v[196:197], v[84:85]
	v_lshlrev_b32_e32 v62, 16, v193
	v_and_b32_e32 v63, 0xffff0000, v193
	v_mul_f32_e32 v48, 0xbfb8aa3b, v48
	v_pk_fma_f32 v[86:87], v[54:55], v[62:63], v[86:87]
	v_exp_f32_e32 v62, v48
	v_mul_f32_e32 v48, v49, v218
	v_mul_f32_e32 v48, 0xbfb8aa3b, v48
	v_mul_f32_e32 v50, v50, v218
	v_mul_f32_e32 v51, v51, v218
	v_exp_f32_e32 v63, v48
	v_mul_f32_e32 v50, 0xbfb8aa3b, v50
	v_mul_f32_e32 v51, 0xbfb8aa3b, v51
	v_exp_f32_e32 v50, v50
	v_exp_f32_e32 v51, v51
	v_add_f32_e32 v62, 1.0, v62
	v_add_f32_e32 v63, 1.0, v63
	v_rcp_f32_e32 v62, v62
	v_rcp_f32_e32 v63, v63
	v_add_f32_e32 v50, 1.0, v50
	v_add_f32_e32 v51, 1.0, v51
	v_rcp_f32_e32 v50, v50
	v_rcp_f32_e32 v51, v51
	v_pk_mul_f32 v[58:59], v[88:89], v[88:89]
	v_pk_mul_f32 v[52:53], v[90:91], v[90:91]
	s_waitcnt vmcnt(8)
	v_lshlrev_b32_e32 v192, 16, v188
	v_and_b32_e32 v193, 0xffff0000, v188
	v_pk_mul_f32 v[60:61], v[92:93], v[92:93]
	v_pk_mul_f32 v[56:57], v[94:95], v[94:95]
	v_pk_fma_f32 v[80:81], v[62:63], v[192:193], v[80:81]
	v_lshlrev_b32_e32 v62, 16, v189
	v_and_b32_e32 v63, 0xffff0000, v189
	v_add_f32_e32 v52, v52, v53
	v_add_f32_e32 v53, v58, v59
	v_pk_mul_f32 v[54:55], v[84:85], v[84:85]
	v_pk_mul_f32 v[48:49], v[86:87], v[86:87]
	v_pk_fma_f32 v[82:83], v[50:51], v[62:63], v[82:83]
	v_add_f32_e32 v52, v53, v52
	v_add_f32_e32 v53, v56, v57
	v_add_f32_e32 v56, v60, v61
	v_pk_mul_f32 v[50:51], v[80:81], v[80:81]
	v_pk_mul_f32 v[62:63], v[82:83], v[82:83]
	v_add_f32_e32 v53, v56, v53
	v_add_f32_e32 v48, v48, v49
	v_add_f32_e32 v49, v54, v55
	v_add_f32_e32 v52, v53, v52
	v_add_f32_e32 v48, v49, v48
	v_add_f32_e32 v49, v62, v63
	v_add_f32_e32 v50, v50, v51
	v_add_f32_e32 v48, v52, v48
	v_add_f32_e32 v49, v50, v49
	v_add_f32_e32 v48, v48, v49
	ds_bpermute_b32 v49, v211, v48
	v_readlane_b32 s74, v252, 22
	v_readlane_b32 s75, v252, 23
	v_readlane_b32 s76, v252, 24
	v_readlane_b32 s77, v252, 25
	s_waitcnt lgkmcnt(0)
	v_add_f32_e32 v48, v48, v49
	ds_bpermute_b32 v49, v213, v48
	v_readlane_b32 s78, v252, 26
	v_readlane_b32 s79, v252, 27
	v_readlane_b32 s80, v252, 28
	v_readlane_b32 s81, v252, 29
	s_and_saveexec_b64 s[0:1], s[2:3]
	s_cbranch_execz .LBB0_1172
	s_waitcnt lgkmcnt(0)
	v_add_f32_e32 v48, v48, v49
	v_add_f32_e32 v48, 0x48400000, v48
	v_add_f32_e32 v48, 0xc8400000, v48
	global_atomic_add_f32 v[182:183], v48, off offset:512
.LBB0_1172:
	s_or_b64 exec, exec, s[0:1]
	v_or_b32_e32 v48, 32, v112
	s_waitcnt lgkmcnt(0)
	v_ashrrev_i32_e32 v49, 31, v48
	v_lshlrev_b64 v[48:49], 11, v[48:49]
	v_lshl_add_u64 v[48:49], v[48:49], 0, v[170:171]
	v_readlane_b32 s68, v252, 16
	v_readlane_b32 s82, v252, 30
	v_readlane_b32 s83, v252, 31
	v_lshlrev_b64 v[188:189], 1, v[48:49]
	v_lshl_add_u64 v[192:193], s[14:15], 0, v[188:189]
	v_lshl_add_u64 v[50:51], v[48:49], 2, s[82:83]
	v_or_b32_e32 v48, 32, v188
	v_mov_b32_e32 v49, v189
	v_lshl_add_u64 v[196:197], s[14:15], 0, v[48:49]
	v_fmamk_f32 v48, v215, 0x3a000000, v209
	v_mul_f32_e32 v49, 0x4f800000, v48
	v_cmp_gt_f32_e32 vcc, s62, v48
	global_load_dwordx4 v[60:63], v[50:51], off
	global_load_dwordx4 v[56:59], v[50:51], off offset:64
	v_cndmask_b32_e32 v52, v48, v49, vcc
	v_sqrt_f32_e32 v53, v52
	v_or_b32_e32 v48, 0x100, v188
	v_mov_b32_e32 v49, v189
	v_lshl_add_u64 v[216:217], s[14:15], 0, v[48:49]
	v_add_u32_e32 v48, -1, v53
	v_fma_f32 v49, -v48, v53, v52
	v_cmp_ge_f32_e64 s[0:1], 0, v49
	v_add_u32_e32 v49, 1, v53
	v_or_b32_e32 v188, 0x120, v188
	v_cndmask_b32_e64 v48, v53, v48, s[0:1]
	v_fma_f32 v53, -v49, v53, v52
	v_cmp_lt_f32_e64 s[0:1], 0, v53
	v_lshl_add_u64 v[188:189], s[14:15], 0, v[188:189]
	v_readlane_b32 s69, v252, 17
	v_cndmask_b32_e64 v48, v48, v49, s[0:1]
	v_mul_f32_e32 v49, 0x37800000, v48
	v_cndmask_b32_e32 v48, v48, v49, vcc
	v_cmp_class_f32_e32 vcc, v52, v210
	v_readlane_b32 s70, v252, 18
	v_readlane_b32 s71, v252, 19
	v_cndmask_b32_e32 v200, v48, v52, vcc
	v_div_scale_f32 v201, s[0:1], v200, v200, 1.0
	v_rcp_f32_e32 v215, v201
	global_load_dwordx4 v[52:55], v[50:51], off offset:512
	s_nop 0
	global_load_dwordx4 v[48:51], v[50:51], off offset:576
	v_readlane_b32 s72, v252, 20
	v_readlane_b32 s73, v252, 21
	v_fma_f32 v218, -v201, v215, 1.0
	v_fmac_f32_e32 v215, v218, v215
	v_div_scale_f32 v218, vcc, 1.0, v200, 1.0
	v_mul_f32_e32 v219, v218, v215
	v_fma_f32 v220, -v201, v219, v218
	v_fmac_f32_e32 v219, v220, v215
	v_fma_f32 v201, -v201, v219, v218
	v_div_fmas_f32 v201, v201, v215, v219
	v_div_fixup_f32 v215, v201, v200, 1.0
	global_load_dwordx2 v[200:201], v[192:193], off
	s_nop 0
	global_load_dwordx2 v[196:197], v[196:197], off
	s_nop 0
	global_load_dwordx2 v[192:193], v[216:217], off
	s_nop 0
	global_load_dwordx2 v[188:189], v[188:189], off
	v_mul_f32_e32 v44, v44, v215
	v_mul_f32_e32 v45, v45, v215
	v_mul_f32_e32 v44, 0xbfb8aa3b, v44
	v_mul_f32_e32 v45, 0xbfb8aa3b, v45
	v_mul_f32_e32 v46, v46, v215
	v_mul_f32_e32 v47, v47, v215
	v_exp_f32_e32 v44, v44
	v_exp_f32_e32 v45, v45
	v_mul_f32_e32 v46, 0xbfb8aa3b, v46
	v_mul_f32_e32 v47, 0xbfb8aa3b, v47
	v_exp_f32_e32 v46, v46
	v_exp_f32_e32 v47, v47
	v_add_f32_e32 v44, 1.0, v44
	v_add_f32_e32 v45, 1.0, v45
	v_rcp_f32_e32 v44, v44
	v_rcp_f32_e32 v45, v45
	v_add_f32_e32 v46, 1.0, v46
	v_add_f32_e32 v47, 1.0, v47
	v_rcp_f32_e32 v46, v46
	v_rcp_f32_e32 v47, v47
	s_waitcnt vmcnt(11)
	v_lshlrev_b32_e32 v216, 16, v198
	v_and_b32_e32 v217, 0xffff0000, v198
	v_mul_f32_e32 v40, v40, v215
	v_pk_fma_f32 v[76:77], v[44:45], v[216:217], v[76:77]
	v_lshlrev_b32_e32 v44, 16, v199
	v_and_b32_e32 v45, 0xffff0000, v199
	v_mul_f32_e32 v40, 0xbfb8aa3b, v40
	v_pk_fma_f32 v[78:79], v[46:47], v[44:45], v[78:79]
	v_exp_f32_e32 v46, v40
	v_mul_f32_e32 v40, v41, v215
	v_mul_f32_e32 v40, 0xbfb8aa3b, v40
	v_mul_f32_e32 v42, v42, v215
	v_mul_f32_e32 v43, v43, v215
	v_exp_f32_e32 v47, v40
	v_mul_f32_e32 v42, 0xbfb8aa3b, v42
	v_mul_f32_e32 v43, 0xbfb8aa3b, v43
	v_exp_f32_e32 v42, v42
	v_exp_f32_e32 v43, v43
	v_add_f32_e32 v46, 1.0, v46
	v_add_f32_e32 v47, 1.0, v47
	v_rcp_f32_e32 v46, v46
	v_rcp_f32_e32 v47, v47
	v_add_f32_e32 v42, 1.0, v42
	v_add_f32_e32 v43, 1.0, v43
	v_rcp_f32_e32 v42, v42
	v_rcp_f32_e32 v43, v43
	s_waitcnt vmcnt(10)
	v_lshlrev_b32_e32 v198, 16, v194
	v_and_b32_e32 v199, 0xffff0000, v194
	v_mul_f32_e32 v36, v36, v215
	v_pk_fma_f32 v[72:73], v[46:47], v[198:199], v[72:73]
	v_lshlrev_b32_e32 v46, 16, v195
	v_and_b32_e32 v47, 0xffff0000, v195
	v_mul_f32_e32 v36, 0xbfb8aa3b, v36
	v_pk_fma_f32 v[74:75], v[42:43], v[46:47], v[74:75]
	v_exp_f32_e32 v46, v36
	v_mul_f32_e32 v36, v37, v215
	v_mul_f32_e32 v36, 0xbfb8aa3b, v36
	v_mul_f32_e32 v38, v38, v215
	v_mul_f32_e32 v39, v39, v215
	v_exp_f32_e32 v47, v36
	v_mul_f32_e32 v38, 0xbfb8aa3b, v38
	v_mul_f32_e32 v39, 0xbfb8aa3b, v39
	v_exp_f32_e32 v38, v38
	v_exp_f32_e32 v39, v39
	v_add_f32_e32 v46, 1.0, v46
	v_add_f32_e32 v47, 1.0, v47
	v_rcp_f32_e32 v46, v46
	v_rcp_f32_e32 v47, v47
	v_add_f32_e32 v38, 1.0, v38
	v_add_f32_e32 v39, 1.0, v39
	v_rcp_f32_e32 v38, v38
	v_rcp_f32_e32 v39, v39
	s_waitcnt vmcnt(9)
	v_lshlrev_b32_e32 v194, 16, v190
	v_and_b32_e32 v195, 0xffff0000, v190
	v_mul_f32_e32 v32, v32, v215
	v_pk_fma_f32 v[68:69], v[46:47], v[194:195], v[68:69]
	v_lshlrev_b32_e32 v46, 16, v191
	v_and_b32_e32 v47, 0xffff0000, v191
	v_mul_f32_e32 v32, 0xbfb8aa3b, v32
	v_pk_fma_f32 v[70:71], v[38:39], v[46:47], v[70:71]
	v_exp_f32_e32 v46, v32
	v_mul_f32_e32 v32, v33, v215
	v_mul_f32_e32 v32, 0xbfb8aa3b, v32
	v_mul_f32_e32 v34, v34, v215
	v_mul_f32_e32 v35, v35, v215
	v_exp_f32_e32 v47, v32
	v_mul_f32_e32 v34, 0xbfb8aa3b, v34
	v_mul_f32_e32 v35, 0xbfb8aa3b, v35
	v_exp_f32_e32 v34, v34
	v_exp_f32_e32 v35, v35
	v_add_f32_e32 v46, 1.0, v46
	v_add_f32_e32 v47, 1.0, v47
	v_rcp_f32_e32 v46, v46
	v_rcp_f32_e32 v47, v47
	v_add_f32_e32 v34, 1.0, v34
	v_add_f32_e32 v35, 1.0, v35
	v_rcp_f32_e32 v34, v34
	v_rcp_f32_e32 v35, v35
	v_pk_mul_f32 v[42:43], v[72:73], v[72:73]
	v_pk_mul_f32 v[36:37], v[74:75], v[74:75]
	s_waitcnt vmcnt(8)
	v_lshlrev_b32_e32 v190, 16, v186
	v_and_b32_e32 v191, 0xffff0000, v186
	v_pk_mul_f32 v[44:45], v[76:77], v[76:77]
	v_pk_mul_f32 v[40:41], v[78:79], v[78:79]
	v_pk_fma_f32 v[64:65], v[46:47], v[190:191], v[64:65]
	v_lshlrev_b32_e32 v46, 16, v187
	v_and_b32_e32 v47, 0xffff0000, v187
	v_add_f32_e32 v36, v36, v37
	v_add_f32_e32 v37, v42, v43
	v_pk_mul_f32 v[38:39], v[68:69], v[68:69]
	v_pk_mul_f32 v[32:33], v[70:71], v[70:71]
	v_pk_fma_f32 v[66:67], v[34:35], v[46:47], v[66:67]
	v_add_f32_e32 v36, v37, v36
	v_add_f32_e32 v37, v40, v41
	v_add_f32_e32 v40, v44, v45
	v_pk_mul_f32 v[34:35], v[64:65], v[64:65]
	v_pk_mul_f32 v[46:47], v[66:67], v[66:67]
	v_add_f32_e32 v37, v40, v37
	v_add_f32_e32 v32, v32, v33
	v_add_f32_e32 v33, v38, v39
	v_add_f32_e32 v36, v37, v36
	v_add_f32_e32 v32, v33, v32
	v_add_f32_e32 v33, v46, v47
	v_add_f32_e32 v34, v34, v35
	v_add_f32_e32 v32, v36, v32
	v_add_f32_e32 v33, v34, v33
	v_add_f32_e32 v32, v32, v33
	ds_bpermute_b32 v33, v211, v32
	v_readlane_b32 s74, v252, 22
	v_readlane_b32 s75, v252, 23
	v_readlane_b32 s76, v252, 24
	v_readlane_b32 s77, v252, 25
	s_waitcnt lgkmcnt(0)
	v_add_f32_e32 v32, v32, v33
	ds_bpermute_b32 v33, v213, v32
	v_readlane_b32 s78, v252, 26
	v_readlane_b32 s79, v252, 27
	v_readlane_b32 s80, v252, 28
	v_readlane_b32 s81, v252, 29
	s_and_saveexec_b64 s[0:1], s[2:3]
	s_cbranch_execz .LBB0_1174
	s_waitcnt lgkmcnt(0)
	v_add_f32_e32 v32, v32, v33
	v_add_f32_e32 v32, 0x48400000, v32
	v_add_f32_e32 v32, 0xc8400000, v32
	global_atomic_add_f32 v[182:183], v32, off offset:576
.LBB0_1174:
	s_or_b64 exec, exec, s[0:1]
	v_or_b32_e32 v32, 48, v112
	s_waitcnt lgkmcnt(0)
	v_ashrrev_i32_e32 v33, 31, v32
	v_lshlrev_b64 v[32:33], 11, v[32:33]
	v_lshl_add_u64 v[32:33], v[32:33], 0, v[170:171]
	v_readlane_b32 s68, v252, 16
	v_readlane_b32 s82, v252, 30
	v_readlane_b32 s83, v252, 31
	v_lshlrev_b64 v[186:187], 1, v[32:33]
	v_lshl_add_u64 v[190:191], s[14:15], 0, v[186:187]
	v_lshl_add_u64 v[34:35], v[32:33], 2, s[82:83]
	v_or_b32_e32 v32, 32, v186
	v_mov_b32_e32 v33, v187
	v_lshl_add_u64 v[194:195], s[14:15], 0, v[32:33]
	v_fmamk_f32 v32, v214, 0x3a000000, v209
	v_mul_f32_e32 v33, 0x4f800000, v32
	v_cmp_gt_f32_e32 vcc, s62, v32
	global_load_dwordx4 v[44:47], v[34:35], off
	global_load_dwordx4 v[40:43], v[34:35], off offset:64
	v_cndmask_b32_e32 v36, v32, v33, vcc
	v_sqrt_f32_e32 v37, v36
	v_or_b32_e32 v32, 0x100, v186
	v_mov_b32_e32 v33, v187
	v_lshl_add_u64 v[214:215], s[14:15], 0, v[32:33]
	v_add_u32_e32 v32, -1, v37
	v_fma_f32 v33, -v32, v37, v36
	v_cmp_ge_f32_e64 s[0:1], 0, v33
	v_add_u32_e32 v33, 1, v37
	v_or_b32_e32 v186, 0x120, v186
	v_cndmask_b32_e64 v32, v37, v32, s[0:1]
	v_fma_f32 v37, -v33, v37, v36
	v_cmp_lt_f32_e64 s[0:1], 0, v37
	v_lshl_add_u64 v[186:187], s[14:15], 0, v[186:187]
	v_readlane_b32 s69, v252, 17
	v_cndmask_b32_e64 v32, v32, v33, s[0:1]
	v_mul_f32_e32 v33, 0x37800000, v32
	v_cndmask_b32_e32 v32, v32, v33, vcc
	v_cmp_class_f32_e32 vcc, v36, v210
	v_readlane_b32 s70, v252, 18
	v_readlane_b32 s71, v252, 19
	v_cndmask_b32_e32 v198, v32, v36, vcc
	v_div_scale_f32 v199, s[0:1], v198, v198, 1.0
	v_rcp_f32_e32 v216, v199
	global_load_dwordx4 v[36:39], v[34:35], off offset:512
	s_nop 0
	global_load_dwordx4 v[32:35], v[34:35], off offset:576
	v_readlane_b32 s72, v252, 20
	v_readlane_b32 s73, v252, 21
	v_fma_f32 v217, -v199, v216, 1.0
	v_fmac_f32_e32 v216, v217, v216
	v_div_scale_f32 v217, vcc, 1.0, v198, 1.0
	v_mul_f32_e32 v218, v217, v216
	v_fma_f32 v219, -v199, v218, v217
	v_fmac_f32_e32 v218, v219, v216
	v_fma_f32 v199, -v199, v218, v217
	v_div_fmas_f32 v199, v199, v216, v218
	v_div_fixup_f32 v216, v199, v198, 1.0
	global_load_dwordx2 v[198:199], v[190:191], off
	s_nop 0
	global_load_dwordx2 v[194:195], v[194:195], off
	s_nop 0
	global_load_dwordx2 v[190:191], v[214:215], off
	s_nop 0
	global_load_dwordx2 v[186:187], v[186:187], off
	v_mul_f32_e32 v28, v28, v216
	v_mul_f32_e32 v29, v29, v216
	v_mul_f32_e32 v28, 0xbfb8aa3b, v28
	v_mul_f32_e32 v29, 0xbfb8aa3b, v29
	v_mul_f32_e32 v24, v24, v216
	v_mul_f32_e32 v25, v25, v216
	v_exp_f32_e32 v28, v28
	v_exp_f32_e32 v29, v29
	v_mul_f32_e32 v24, 0xbfb8aa3b, v24
	v_mul_f32_e32 v25, 0xbfb8aa3b, v25
	v_mul_f32_e32 v26, v26, v216
	v_mul_f32_e32 v27, v27, v216
	v_mul_f32_e32 v30, v30, v216
	v_mul_f32_e32 v31, v31, v216
	v_exp_f32_e32 v24, v24
	v_exp_f32_e32 v25, v25
	v_mul_f32_e32 v26, 0xbfb8aa3b, v26
	v_mul_f32_e32 v27, 0xbfb8aa3b, v27
	v_mul_f32_e32 v20, v20, v216
	v_mul_f32_e32 v21, v21, v216
	v_mul_f32_e32 v30, 0xbfb8aa3b, v30
	v_mul_f32_e32 v31, 0xbfb8aa3b, v31
	v_exp_f32_e32 v26, v26
	v_exp_f32_e32 v27, v27
	v_mul_f32_e32 v20, 0xbfb8aa3b, v20
	v_mul_f32_e32 v21, 0xbfb8aa3b, v21
	v_mul_f32_e32 v22, v22, v216
	v_mul_f32_e32 v23, v23, v216
	v_mul_f32_e32 v16, v16, v216
	v_mul_f32_e32 v17, v17, v216
	v_exp_f32_e32 v30, v30
	v_exp_f32_e32 v31, v31
	v_exp_f32_e32 v20, v20
	v_exp_f32_e32 v21, v21
	v_mul_f32_e32 v22, 0xbfb8aa3b, v22
	v_mul_f32_e32 v23, 0xbfb8aa3b, v23
	v_mul_f32_e32 v16, 0xbfb8aa3b, v16
	v_mul_f32_e32 v17, 0xbfb8aa3b, v17
	v_mul_f32_e32 v18, v18, v216
	v_mul_f32_e32 v19, v19, v216
	v_add_f32_e32 v28, 1.0, v28
	v_add_f32_e32 v29, 1.0, v29
	v_exp_f32_e32 v22, v22
	v_exp_f32_e32 v23, v23
	v_exp_f32_e32 v16, v16
	v_exp_f32_e32 v17, v17
	v_mul_f32_e32 v18, 0xbfb8aa3b, v18
	v_mul_f32_e32 v19, 0xbfb8aa3b, v19
	v_rcp_f32_e32 v28, v28
	v_rcp_f32_e32 v29, v29
	v_add_f32_e32 v24, 1.0, v24
	v_add_f32_e32 v25, 1.0, v25
	v_exp_f32_e32 v18, v18
	v_exp_f32_e32 v19, v19
	v_rcp_f32_e32 v24, v24
	v_rcp_f32_e32 v25, v25
	v_add_f32_e32 v26, 1.0, v26
	v_add_f32_e32 v27, 1.0, v27
	v_add_f32_e32 v30, 1.0, v30
	v_add_f32_e32 v31, 1.0, v31
	v_rcp_f32_e32 v26, v26
	v_rcp_f32_e32 v27, v27
	v_add_f32_e32 v20, 1.0, v20
	v_add_f32_e32 v21, 1.0, v21
	s_waitcnt vmcnt(11)
	v_lshlrev_b32_e32 v214, 16, v200
	v_and_b32_e32 v215, 0xffff0000, v200
	v_rcp_f32_e32 v30, v30
	v_rcp_f32_e32 v31, v31
	v_rcp_f32_e32 v20, v20
	v_rcp_f32_e32 v21, v21
	v_add_f32_e32 v22, 1.0, v22
	v_add_f32_e32 v23, 1.0, v23
	v_add_f32_e32 v16, 1.0, v16
	v_add_f32_e32 v17, 1.0, v17
	v_pk_fma_f32 v[28:29], v[28:29], v[214:215], v[60:61]
	v_lshlrev_b32_e32 v60, 16, v201
	v_and_b32_e32 v61, 0xffff0000, v201
	s_waitcnt vmcnt(10)
	v_lshlrev_b32_e32 v200, 16, v196
	v_and_b32_e32 v201, 0xffff0000, v196
	v_rcp_f32_e32 v22, v22
	v_rcp_f32_e32 v23, v23
	v_rcp_f32_e32 v16, v16
	v_rcp_f32_e32 v17, v17
	v_add_f32_e32 v18, 1.0, v18
	v_add_f32_e32 v19, 1.0, v19
	v_pk_fma_f32 v[24:25], v[24:25], v[200:201], v[56:57]
	v_lshlrev_b32_e32 v56, 16, v197
	v_and_b32_e32 v57, 0xffff0000, v197
	v_rcp_f32_e32 v18, v18
	v_rcp_f32_e32 v19, v19
	v_pk_fma_f32 v[26:27], v[26:27], v[56:57], v[58:59]
	s_waitcnt vmcnt(9)
	v_lshlrev_b32_e32 v196, 16, v192
	v_and_b32_e32 v197, 0xffff0000, v192
	v_pk_fma_f32 v[30:31], v[30:31], v[60:61], v[62:63]
	v_pk_mul_f32 v[56:57], v[24:25], v[24:25]
	v_pk_mul_f32 v[58:59], v[26:27], v[26:27]
	v_pk_fma_f32 v[20:21], v[20:21], v[196:197], v[52:53]
	v_lshlrev_b32_e32 v52, 16, v193
	v_and_b32_e32 v53, 0xffff0000, v193
	s_waitcnt vmcnt(8)
	v_lshlrev_b32_e32 v192, 16, v188
	v_and_b32_e32 v193, 0xffff0000, v188
	v_pk_mul_f32 v[60:61], v[28:29], v[28:29]
	v_pk_mul_f32 v[62:63], v[30:31], v[30:31]
	v_pk_fma_f32 v[22:23], v[22:23], v[52:53], v[54:55]
	v_pk_fma_f32 v[16:17], v[16:17], v[192:193], v[48:49]
	v_lshlrev_b32_e32 v48, 16, v189
	v_and_b32_e32 v49, 0xffff0000, v189
	v_add_f32_e32 v58, v58, v59
	v_add_f32_e32 v56, v56, v57
	v_pk_mul_f32 v[52:53], v[20:21], v[20:21]
	v_pk_mul_f32 v[54:55], v[22:23], v[22:23]
	v_pk_fma_f32 v[18:19], v[18:19], v[48:49], v[50:51]
	v_add_f32_e32 v56, v56, v58
	v_add_f32_e32 v57, v62, v63
	v_add_f32_e32 v58, v60, v61
	v_pk_mul_f32 v[48:49], v[16:17], v[16:17]
	v_pk_mul_f32 v[50:51], v[18:19], v[18:19]
	v_add_f32_e32 v57, v58, v57
	v_add_f32_e32 v54, v54, v55
	v_add_f32_e32 v52, v52, v53
	v_add_f32_e32 v56, v57, v56
	v_add_f32_e32 v52, v52, v54
	v_add_f32_e32 v50, v50, v51
	v_add_f32_e32 v48, v48, v49
	v_add_f32_e32 v52, v56, v52
	v_add_f32_e32 v48, v48, v50
	v_add_f32_e32 v48, v52, v48
	ds_bpermute_b32 v49, v211, v48
	v_readlane_b32 s74, v252, 22
	v_readlane_b32 s75, v252, 23
	v_readlane_b32 s76, v252, 24
	v_readlane_b32 s77, v252, 25
	s_waitcnt lgkmcnt(0)
	v_add_f32_e32 v48, v48, v49
	ds_bpermute_b32 v49, v213, v48
	v_readlane_b32 s78, v252, 26
	v_readlane_b32 s79, v252, 27
	v_readlane_b32 s80, v252, 28
	v_readlane_b32 s81, v252, 29
	s_and_saveexec_b64 s[0:1], s[2:3]
	s_cbranch_execz .LBB0_1176
	s_waitcnt lgkmcnt(0)
	v_add_f32_e32 v48, v48, v49
	v_add_f32_e32 v48, 0x48400000, v48
	v_add_f32_e32 v48, 0xc8400000, v48
	global_atomic_add_f32 v[182:183], v48, off offset:640
.LBB0_1176:
	s_or_b64 exec, exec, s[0:1]
	v_fmamk_f32 v48, v212, 0x3a000000, v209
	s_waitcnt lgkmcnt(0)
	v_mul_f32_e32 v49, 0x4f800000, v48
	v_cmp_gt_f32_e32 vcc, s62, v48
	s_nop 1
	v_cndmask_b32_e32 v48, v48, v49, vcc
	v_sqrt_f32_e32 v49, v48
	s_nop 0
	v_add_u32_e32 v50, -1, v49
	v_fma_f32 v52, -v50, v49, v48
	v_add_u32_e32 v51, 1, v49
	v_cmp_ge_f32_e64 s[0:1], 0, v52
	s_nop 1
	v_cndmask_b32_e64 v50, v49, v50, s[0:1]
	v_fma_f32 v49, -v51, v49, v48
	v_cmp_lt_f32_e64 s[0:1], 0, v49
	s_nop 1
	v_cndmask_b32_e64 v49, v50, v51, s[0:1]
	v_mul_f32_e32 v50, 0x37800000, v49
	v_cndmask_b32_e32 v49, v49, v50, vcc
	v_cmp_class_f32_e32 vcc, v48, v210
	s_nop 1
	v_cndmask_b32_e32 v48, v49, v48, vcc
	v_div_scale_f32 v49, s[0:1], v48, v48, 1.0
	v_rcp_f32_e32 v50, v49
	s_nop 0
	v_fma_f32 v51, -v49, v50, 1.0
	v_fmac_f32_e32 v50, v51, v50
	v_div_scale_f32 v51, vcc, 1.0, v48, 1.0
	v_mul_f32_e32 v52, v51, v50
	v_fma_f32 v53, -v49, v52, v51
	v_fmac_f32_e32 v52, v53, v50
	v_fma_f32 v49, -v49, v52, v51
	v_div_fmas_f32 v49, v49, v50, v52
	v_div_fixup_f32 v50, v49, v48, 1.0
	v_mul_f32_e32 v12, v12, v50
	v_mul_f32_e32 v13, v13, v50
	v_mul_f32_e32 v12, 0xbfb8aa3b, v12
	v_mul_f32_e32 v13, 0xbfb8aa3b, v13
	v_mul_f32_e32 v14, v14, v50
	v_mul_f32_e32 v15, v15, v50
	v_exp_f32_e32 v12, v12
	v_exp_f32_e32 v13, v13
	v_mul_f32_e32 v14, 0xbfb8aa3b, v14
	v_mul_f32_e32 v15, 0xbfb8aa3b, v15
	v_exp_f32_e32 v14, v14
	v_exp_f32_e32 v15, v15
	v_add_f32_e32 v12, 1.0, v12
	v_add_f32_e32 v13, 1.0, v13
	v_rcp_f32_e32 v12, v12
	v_rcp_f32_e32 v13, v13
	v_add_f32_e32 v14, 1.0, v14
	v_add_f32_e32 v15, 1.0, v15
	v_rcp_f32_e32 v14, v14
	v_rcp_f32_e32 v15, v15
	s_waitcnt vmcnt(3)
	v_lshlrev_b32_e32 v48, 16, v198
	v_and_b32_e32 v49, 0xffff0000, v198
	v_mul_f32_e32 v8, v8, v50
	v_pk_fma_f32 v[44:45], v[12:13], v[48:49], v[44:45]
	v_lshlrev_b32_e32 v12, 16, v199
	v_and_b32_e32 v13, 0xffff0000, v199
	v_mul_f32_e32 v8, 0xbfb8aa3b, v8
	v_pk_fma_f32 v[46:47], v[14:15], v[12:13], v[46:47]
	v_exp_f32_e32 v14, v8
	v_mul_f32_e32 v8, v9, v50
	v_mul_f32_e32 v8, 0xbfb8aa3b, v8
	v_mul_f32_e32 v10, v10, v50
	v_mul_f32_e32 v11, v11, v50
	v_exp_f32_e32 v15, v8
	v_mul_f32_e32 v10, 0xbfb8aa3b, v10
	v_mul_f32_e32 v11, 0xbfb8aa3b, v11
	v_exp_f32_e32 v10, v10
	v_exp_f32_e32 v11, v11
	v_add_f32_e32 v14, 1.0, v14
	v_add_f32_e32 v15, 1.0, v15
	v_rcp_f32_e32 v14, v14
	v_rcp_f32_e32 v15, v15
	v_add_f32_e32 v10, 1.0, v10
	v_add_f32_e32 v11, 1.0, v11
	v_rcp_f32_e32 v10, v10
	v_rcp_f32_e32 v11, v11
	s_waitcnt vmcnt(2)
	v_lshlrev_b32_e32 v48, 16, v194
	v_and_b32_e32 v49, 0xffff0000, v194
	v_mul_f32_e32 v4, v4, v50
	v_pk_fma_f32 v[40:41], v[14:15], v[48:49], v[40:41]
	v_lshlrev_b32_e32 v14, 16, v195
	v_and_b32_e32 v15, 0xffff0000, v195
	v_mul_f32_e32 v4, 0xbfb8aa3b, v4
	v_pk_fma_f32 v[42:43], v[10:11], v[14:15], v[42:43]
	v_exp_f32_e32 v14, v4
	v_mul_f32_e32 v4, v5, v50
	v_mul_f32_e32 v4, 0xbfb8aa3b, v4
	v_mul_f32_e32 v6, v6, v50
	v_mul_f32_e32 v7, v7, v50
	v_exp_f32_e32 v15, v4
	v_mul_f32_e32 v6, 0xbfb8aa3b, v6
	v_mul_f32_e32 v7, 0xbfb8aa3b, v7
	v_exp_f32_e32 v6, v6
	v_exp_f32_e32 v7, v7
	v_add_f32_e32 v14, 1.0, v14
	v_add_f32_e32 v15, 1.0, v15
	v_rcp_f32_e32 v14, v14
	v_rcp_f32_e32 v15, v15
	v_add_f32_e32 v6, 1.0, v6
	v_add_f32_e32 v7, 1.0, v7
	v_rcp_f32_e32 v6, v6
	v_rcp_f32_e32 v7, v7
	s_waitcnt vmcnt(1)
	v_lshlrev_b32_e32 v48, 16, v190
	v_and_b32_e32 v49, 0xffff0000, v190
	v_mul_f32_e32 v0, v0, v50
	v_pk_fma_f32 v[36:37], v[14:15], v[48:49], v[36:37]
	v_lshlrev_b32_e32 v14, 16, v191
	v_and_b32_e32 v15, 0xffff0000, v191
	v_mul_f32_e32 v0, 0xbfb8aa3b, v0
	v_pk_fma_f32 v[38:39], v[6:7], v[14:15], v[38:39]
	v_exp_f32_e32 v14, v0
	v_mul_f32_e32 v0, v1, v50
	v_mul_f32_e32 v0, 0xbfb8aa3b, v0
	v_mul_f32_e32 v2, v2, v50
	v_mul_f32_e32 v3, v3, v50
	v_exp_f32_e32 v15, v0
	v_mul_f32_e32 v2, 0xbfb8aa3b, v2
	v_mul_f32_e32 v3, 0xbfb8aa3b, v3
	v_exp_f32_e32 v2, v2
	v_exp_f32_e32 v3, v3
	v_add_f32_e32 v14, 1.0, v14
	v_add_f32_e32 v15, 1.0, v15
	v_rcp_f32_e32 v14, v14
	v_rcp_f32_e32 v15, v15
	v_add_f32_e32 v2, 1.0, v2
	v_add_f32_e32 v3, 1.0, v3
	v_rcp_f32_e32 v2, v2
	v_rcp_f32_e32 v3, v3
	v_pk_mul_f32 v[10:11], v[40:41], v[40:41]
	v_pk_mul_f32 v[4:5], v[42:43], v[42:43]
	s_waitcnt vmcnt(0)
	v_lshlrev_b32_e32 v48, 16, v186
	v_and_b32_e32 v49, 0xffff0000, v186
	v_pk_mul_f32 v[12:13], v[44:45], v[44:45]
	v_pk_mul_f32 v[8:9], v[46:47], v[46:47]
	v_pk_fma_f32 v[32:33], v[14:15], v[48:49], v[32:33]
	v_lshlrev_b32_e32 v14, 16, v187
	v_and_b32_e32 v15, 0xffff0000, v187
	v_add_f32_e32 v4, v4, v5
	v_add_f32_e32 v5, v10, v11
	v_pk_mul_f32 v[6:7], v[36:37], v[36:37]
	v_pk_mul_f32 v[0:1], v[38:39], v[38:39]
	v_pk_fma_f32 v[34:35], v[2:3], v[14:15], v[34:35]
	v_add_f32_e32 v4, v5, v4
	v_add_f32_e32 v5, v8, v9
	v_add_f32_e32 v8, v12, v13
	v_pk_mul_f32 v[2:3], v[32:33], v[32:33]
	v_pk_mul_f32 v[14:15], v[34:35], v[34:35]
	v_add_f32_e32 v5, v8, v5
	v_add_f32_e32 v0, v0, v1
	v_add_f32_e32 v1, v6, v7
	v_add_f32_e32 v4, v5, v4
	v_add_f32_e32 v0, v1, v0
	v_add_f32_e32 v1, v14, v15
	v_add_f32_e32 v2, v2, v3
	v_add_f32_e32 v0, v4, v0
	v_add_f32_e32 v1, v2, v1
	v_add_f32_e32 v0, v0, v1
	ds_bpermute_b32 v1, v211, v0
	s_waitcnt lgkmcnt(0)
	v_add_f32_e32 v0, v0, v1
	ds_bpermute_b32 v1, v213, v0
	s_and_saveexec_b64 s[0:1], s[2:3]
	s_cbranch_execz .LBB0_1178
	s_waitcnt lgkmcnt(0)
	v_add_f32_e32 v0, v0, v1
	v_add_f32_e32 v0, 0x48400000, v0
	v_add_f32_e32 v0, 0xc8400000, v0
	global_atomic_add_f32 v[182:183], v0, off offset:704
